# v26 + K-loop load segments reordered ds_reads first, scalar setup and LDS-DMA loads after
# baseline (speedup 1.0000x reference)
; #define PG8_STAGE(bufoff, gbase, voff) do { _Pragma("unroll") for (int _i = 0; _i < 2; ++_i) \
;         __builtin_amdgcn_global_load_lds((const unsigned*)((const char*)(gbase) + (voff)[_i]), (PG8_LAS unsigned*)(lds + (bufoff) + ldsw + _i * 8192), 16, 0, 0); } while (0)
; #define PG8_LDA(dst, b, h) do { _Pragma("unroll") for (int m = 0; m < 4; ++m) _Pragma("unroll") for (int k = 0; k < 2; ++k) dst[m][k] = *(const PG8_LAS bf16x8*)(lds + PG8_SA(b, h) + aoff + m * 2048 + k * 1024); } while (0)
; #define PG8_LDB(dst, b, h) do { _Pragma("unroll") for (int n = 0; n < 2; ++n) _Pragma("unroll") for (int k = 0; k < 2; ++k) dst[n][k] = *(const PG8_LAS bf16x8*)(lds + PG8_SB(b, h) + boff + n * 2048 + k * 1024); } while (0)
; #define PG8_MMA(ai, bj, At, Bt) do { __builtin_amdgcn_s_setprio(1); _Pragma("unroll") for (int m = 0; m < 4; ++m) _Pragma("unroll") for (int n = 0; n < 2; ++n) _Pragma("unroll") for (int k = 0; k < 2; ++k) \
;         acc[ai][bj][m][n] = __builtin_amdgcn_mfma_f32_16x16x32_bf16(Bt[n][k], At[m][k], acc[ai][bj][m][n], 0, 0, 0); __builtin_amdgcn_s_setprio(0); } while (0)
; #define PG8_WAIT_V(n) asm volatile("s_waitcnt vmcnt(" #n ")" ::: "memory")
; #define PG8_WAIT_L(n) asm volatile("s_waitcnt lgkmcnt(" #n ")" ::: "memory")
; template <class Epi, class Sched, bool ALIGN_EPI = false, bool SP2 = false>
; __device__ __forceinline__ void gemm_phase(PG8_LAS unsigned char* lds, const Gemm g, const Sched& S, const Epi& E, const int wave0) {
;     ...
;             const bool last = (t == nt - 2);
;             const char* a1 = cA + (size_t)(t + 1) * kstep;
;             const char* a2 = last ? nA : cA + (size_t)(t + 2) * kstep; const char* b2 = last ? nB : cB + (size_t)(t + 2) * kstep;
;             const char* a3 = a2 + kstep; const char* b3 = b2 + kstep;
;             if (last && has_next) S.a_ready(nxt);
;             if constexpr (SP2) {
;             PG8_LDB(B0, 0, 0); PG8_LDB(B1, 0, 1); PG8_SCHED; PG8_LDA(At, 0, 0); PG8_STAGE(PG8_SA(1, 1), a1 + hstepA, voffA);
;             PG8_WAIT_V(8); PG8_WAIT_L(0); PG8_BAR; PG8_MMA(0, 0, At, B0); PG8_MMA(0, 1, At, B1); PG8_BAR; PG8_SCHED;
;             PG8_LDA(At, 0, 1); PG8_STAGE(PG8_SB(0, 0), b2, voffB); PG8_STAGE(PG8_SB(0, 1), b2 + hstepB, voffB); PG8_STAGE(PG8_SA(0, 0), a2, voffA);
;             PG8_WAIT_V(8); PG8_WAIT_L(0); PG8_BAR; PG8_MMA(1, 0, At, B0); PG8_MMA(1, 1, At, B1); PG8_BAR; PG8_SCHED;
.LBB0_316:
	ds_read_b128 v[144:147], v252
	ds_read_b128 v[148:151], v252 offset:1024
	ds_read_b128 v[152:155], v252 offset:2048
	ds_read_b128 v[156:159], v252 offset:3072
	ds_read_b128 v[178:181], v253
	ds_read_b128 v[182:185], v253 offset:1024
	ds_read_b128 v[186:189], v253 offset:2048
	ds_read_b128 v[190:193], v253 offset:3072
	ds_read_b128 v[194:197], v143
	ds_read_b128 v[208:211], v143 offset:1024
	ds_read_b128 v[212:215], v143 offset:2048
	ds_read_b128 v[216:219], v143 offset:3072
	ds_read_b128 v[220:223], v143 offset:4096
	ds_read_b128 v[224:227], v143 offset:5120
	ds_read_b128 v[228:231], v143 offset:6144
	ds_read_b128 v[232:235], v143 offset:7168
	s_add_u32 s16, s0, 0xfff80080
	s_addc_u32 s17, s1, -1
	s_add_i32 s38, 0, 0x10000
	s_cmp_eq_u32 s37, 28
	s_cselect_b32 s19, s11, s17
	s_cselect_b32 s18, s33, s16
	s_cselect_b32 s17, s9, s36
	s_cselect_b32 s16, s34, s35
	s_add_i32 s40, 0, 0x14000
	s_add_i32 m0, s23, 0xc000
	s_nop 0
	global_load_lds_dwordx4 v136, s[0:1]
	s_add_i32 m0, s23, 0xe000
	s_nop 0
	global_load_lds_dwordx4 v138, s[0:1]
	s_waitcnt vmcnt(8)
	s_waitcnt lgkmcnt(0)
	s_barrier
	s_setprio 1
	s_waitcnt lgkmcnt(0)
	v_mfma_f32_16x16x32_bf16 v[126:129], v[144:147], v[194:197], v[126:129]
	v_mfma_f32_16x16x32_bf16 v[122:125], v[152:155], v[194:197], v[122:125]
	v_mfma_f32_16x16x32_bf16 v[118:121], v[144:147], v[212:215], v[118:121]
	v_mfma_f32_16x16x32_bf16 v[114:117], v[152:155], v[212:215], v[114:117]
	v_mfma_f32_16x16x32_bf16 v[102:105], v[144:147], v[220:223], v[102:105]
	v_mfma_f32_16x16x32_bf16 v[98:101], v[152:155], v[220:223], v[98:101]
	v_mfma_f32_16x16x32_bf16 v[86:89], v[144:147], v[228:231], v[86:89]
	v_mfma_f32_16x16x32_bf16 v[82:85], v[152:155], v[228:231], v[82:85]
	s_setprio 0
	s_setprio 1
	v_mfma_f32_16x16x32_bf16 v[126:129], v[148:151], v[208:211], v[126:129]
	v_mfma_f32_16x16x32_bf16 v[122:125], v[156:159], v[208:211], v[122:125]
	v_mfma_f32_16x16x32_bf16 v[118:121], v[148:151], v[216:219], v[118:121]
	v_mfma_f32_16x16x32_bf16 v[114:117], v[156:159], v[216:219], v[114:117]
	v_mfma_f32_16x16x32_bf16 v[102:105], v[148:151], v[224:227], v[102:105]
	v_mfma_f32_16x16x32_bf16 v[98:101], v[156:159], v[224:227], v[98:101]
	v_mfma_f32_16x16x32_bf16 v[86:89], v[148:151], v[232:235], v[86:89]
	v_mfma_f32_16x16x32_bf16 v[82:85], v[156:159], v[232:235], v[82:85]
	s_setprio 0
	s_setprio 1
	v_mfma_f32_16x16x32_bf16 v[110:113], v[178:181], v[194:197], v[110:113]
	v_mfma_f32_16x16x32_bf16 v[106:109], v[186:189], v[194:197], v[106:109]
	v_mfma_f32_16x16x32_bf16 v[94:97], v[178:181], v[212:215], v[94:97]
	v_mfma_f32_16x16x32_bf16 v[90:93], v[186:189], v[212:215], v[90:93]
	v_mfma_f32_16x16x32_bf16 v[78:81], v[178:181], v[220:223], v[78:81]
	v_mfma_f32_16x16x32_bf16 v[74:77], v[186:189], v[220:223], v[74:77]
	v_mfma_f32_16x16x32_bf16 v[70:73], v[178:181], v[228:231], v[70:73]
	v_mfma_f32_16x16x32_bf16 v[66:69], v[186:189], v[228:231], v[66:69]
	s_setprio 0
	s_setprio 1
	v_mfma_f32_16x16x32_bf16 v[110:113], v[182:185], v[208:211], v[110:113]
	v_mfma_f32_16x16x32_bf16 v[106:109], v[190:193], v[208:211], v[106:109]
	v_mfma_f32_16x16x32_bf16 v[94:97], v[182:185], v[216:219], v[94:97]
	v_mfma_f32_16x16x32_bf16 v[90:93], v[190:193], v[216:219], v[90:93]
	v_mfma_f32_16x16x32_bf16 v[78:81], v[182:185], v[224:227], v[78:81]
	v_mfma_f32_16x16x32_bf16 v[74:77], v[190:193], v[224:227], v[74:77]
	v_mfma_f32_16x16x32_bf16 v[70:73], v[182:185], v[232:235], v[70:73]
	v_mfma_f32_16x16x32_bf16 v[66:69], v[190:193], v[232:235], v[66:69]
	s_setprio 0
	s_barrier
	ds_read_b128 v[194:197], v143 offset:16384
	ds_read_b128 v[208:211], v143 offset:17408
	ds_read_b128 v[212:215], v143 offset:18432
	ds_read_b128 v[216:219], v143 offset:19456
	ds_read_b128 v[220:223], v143 offset:20480
	ds_read_b128 v[224:227], v143 offset:21504
	ds_read_b128 v[228:231], v143 offset:22528
	ds_read_b128 v[232:235], v143 offset:23552
	s_add_i32 s38, s38, s22
	s_mov_b32 m0, s38
	s_nop 0
	global_load_lds_dwordx4 v64, s[16:17]
	s_add_i32 m0, s38, 0x2000
	s_add_u32 s38, s16, 0x80000
	s_addc_u32 s39, s17, 0
	s_add_i32 s40, s40, s22
	global_load_lds_dwordx4 v130, s[16:17]
	s_mov_b32 m0, s40
	s_mov_b64 s[100:101], s[18:19]
	global_load_lds_dwordx4 v64, s[38:39]
	s_add_i32 m0, s40, 0x2000
	s_nop 0
	global_load_lds_dwordx4 v130, s[38:39]
	s_mov_b32 m0, s23
	s_nop 0
	global_load_lds_dwordx4 v134, s[18:19]
	s_mov_b32 m0, s24
	s_nop 0
	global_load_lds_dwordx4 v132, s[18:19]
	s_waitcnt vmcnt(8)
	s_waitcnt lgkmcnt(0)
	s_barrier
	s_setprio 1
	s_waitcnt lgkmcnt(0)
	v_mfma_f32_16x16x32_bf16 v[60:63], v[144:147], v[194:197], v[60:63]
	v_mfma_f32_16x16x32_bf16 v[56:59], v[152:155], v[194:197], v[56:59]
	v_mfma_f32_16x16x32_bf16 v[52:55], v[144:147], v[212:215], v[52:55]
	v_mfma_f32_16x16x32_bf16 v[48:51], v[152:155], v[212:215], v[48:51]
	v_mfma_f32_16x16x32_bf16 v[36:39], v[144:147], v[220:223], v[36:39]
	v_mfma_f32_16x16x32_bf16 v[32:35], v[152:155], v[220:223], v[32:35]
	v_mfma_f32_16x16x32_bf16 v[20:23], v[144:147], v[228:231], v[20:23]
	v_mfma_f32_16x16x32_bf16 v[16:19], v[152:155], v[228:231], v[16:19]
	s_setprio 0
	s_setprio 1
	v_mfma_f32_16x16x32_bf16 v[60:63], v[148:151], v[208:211], v[60:63]
	v_mfma_f32_16x16x32_bf16 v[56:59], v[156:159], v[208:211], v[56:59]
	v_mfma_f32_16x16x32_bf16 v[52:55], v[148:151], v[216:219], v[52:55]
	v_mfma_f32_16x16x32_bf16 v[48:51], v[156:159], v[216:219], v[48:51]
	v_mfma_f32_16x16x32_bf16 v[36:39], v[148:151], v[224:227], v[36:39]
	v_mfma_f32_16x16x32_bf16 v[32:35], v[156:159], v[224:227], v[32:35]
	v_mfma_f32_16x16x32_bf16 v[20:23], v[148:151], v[232:235], v[20:23]
	v_mfma_f32_16x16x32_bf16 v[16:19], v[156:159], v[232:235], v[16:19]
	s_setprio 0
	s_setprio 1
	v_mfma_f32_16x16x32_bf16 v[44:47], v[178:181], v[194:197], v[44:47]
	v_mfma_f32_16x16x32_bf16 v[40:43], v[186:189], v[194:197], v[40:43]
	v_mfma_f32_16x16x32_bf16 v[28:31], v[178:181], v[212:215], v[28:31]
	v_mfma_f32_16x16x32_bf16 v[24:27], v[186:189], v[212:215], v[24:27]
	v_mfma_f32_16x16x32_bf16 v[12:15], v[178:181], v[220:223], v[12:15]
	v_mfma_f32_16x16x32_bf16 v[8:11], v[186:189], v[220:223], v[8:11]
	v_mfma_f32_16x16x32_bf16 v[4:7], v[178:181], v[228:231], v[4:7]
	v_mfma_f32_16x16x32_bf16 v[0:3], v[186:189], v[228:231], v[0:3]
	s_setprio 0
	s_setprio 1
	v_mfma_f32_16x16x32_bf16 v[44:47], v[182:185], v[208:211], v[44:47]
	v_mfma_f32_16x16x32_bf16 v[40:43], v[190:193], v[208:211], v[40:43]
	v_mfma_f32_16x16x32_bf16 v[28:31], v[182:185], v[216:219], v[28:31]
	v_mfma_f32_16x16x32_bf16 v[24:27], v[190:193], v[216:219], v[24:27]
	v_mfma_f32_16x16x32_bf16 v[12:15], v[182:185], v[224:227], v[12:15]
	v_mfma_f32_16x16x32_bf16 v[8:11], v[190:193], v[224:227], v[8:11]
	v_mfma_f32_16x16x32_bf16 v[4:7], v[182:185], v[232:235], v[4:7]
	v_mfma_f32_16x16x32_bf16 v[0:3], v[190:193], v[232:235], v[0:3]
	s_setprio 0
	s_barrier
; #define PG8_STAGE(bufoff, gbase, voff) do { _Pragma("unroll") for (int _i = 0; _i < 2; ++_i) \
;         __builtin_amdgcn_global_load_lds((const unsigned*)((const char*)(gbase) + (voff)[_i]), (PG8_LAS unsigned*)(lds + (bufoff) + ldsw + _i * 8192), 16, 0, 0); } while (0)
; #define PG8_LDA(dst, b, h) do { _Pragma("unroll") for (int m = 0; m < 4; ++m) _Pragma("unroll") for (int k = 0; k < 2; ++k) dst[m][k] = *(const PG8_LAS bf16x8*)(lds + PG8_SA(b, h) + aoff + m * 2048 + k * 1024); } while (0)
; #define PG8_LDB(dst, b, h) do { _Pragma("unroll") for (int n = 0; n < 2; ++n) _Pragma("unroll") for (int k = 0; k < 2; ++k) dst[n][k] = *(const PG8_LAS bf16x8*)(lds + PG8_SB(b, h) + boff + n * 2048 + k * 1024); } while (0)
; #define PG8_MMA(ai, bj, At, Bt) do { __builtin_amdgcn_s_setprio(1); _Pragma("unroll") for (int m = 0; m < 4; ++m) _Pragma("unroll") for (int n = 0; n < 2; ++n) _Pragma("unroll") for (int k = 0; k < 2; ++k) \
;         acc[ai][bj][m][n] = __builtin_amdgcn_mfma_f32_16x16x32_bf16(Bt[n][k], At[m][k], acc[ai][bj][m][n], 0, 0, 0); __builtin_amdgcn_s_setprio(0); } while (0)
; #define PG8_WAIT_V(n) asm volatile("s_waitcnt vmcnt(" #n ")" ::: "memory")
; #define PG8_WAIT_L(n) asm volatile("s_waitcnt lgkmcnt(" #n ")" ::: "memory")
; #define PG8_BAR __builtin_amdgcn_s_barrier()
; #define PG8_SCHED __builtin_amdgcn_sched_barrier(0)
; template <class Epi, class Sched, bool ALIGN_EPI = false, bool SP2 = false>
; __device__ __forceinline__ void gemm_phase(PG8_LAS unsigned char* lds, const Gemm g, const Sched& S, const Epi& E, const int wave0) {
;     ...
;             PG8_LDB(B0, 1, 0); PG8_LDB(B1, 1, 1); PG8_SCHED; PG8_LDA(At, 1, 0); PG8_STAGE(PG8_SA(0, 1), a2 + hstepA, voffA);
;             PG8_WAIT_V(8); PG8_WAIT_L(0); PG8_BAR; PG8_MMA(0, 0, At, B0); PG8_MMA(0, 1, At, B1); PG8_BAR; PG8_SCHED;
;             PG8_LDA(At, 1, 1); PG8_STAGE(PG8_SB(1, 0), b3, voffB); PG8_STAGE(PG8_SB(1, 1), b3 + hstepB, voffB); PG8_STAGE(PG8_SA(1, 0), a3, voffA);
;             PG8_WAIT_V(8); PG8_WAIT_L(0); PG8_BAR; PG8_MMA(1, 0, At, B0); PG8_MMA(1, 1, At, B1); PG8_BAR; PG8_SCHED;
	ds_read_b128 v[144:147], v254
	ds_read_b128 v[148:151], v254 offset:1024
	ds_read_b128 v[152:155], v254 offset:2048
	ds_read_b128 v[156:159], v254 offset:3072
	ds_read_b128 v[178:181], v255
	ds_read_b128 v[182:185], v255 offset:1024
	ds_read_b128 v[186:189], v255 offset:2048
	ds_read_b128 v[190:193], v255 offset:3072
	ds_read_b128 v[194:197], v143 offset:32768
	ds_read_b128 v[208:211], v143 offset:33792
	ds_read_b128 v[212:215], v143 offset:34816
	ds_read_b128 v[216:219], v143 offset:35840
	ds_read_b128 v[220:223], v143 offset:36864
	ds_read_b128 v[224:227], v143 offset:37888
	ds_read_b128 v[228:231], v143 offset:38912
	ds_read_b128 v[232:235], v143 offset:39936
	s_add_i32 s38, 0, 0x18000
	s_add_i32 s39, 0, 0x1c000
	s_add_u32 s18, s18, 0x80000
	s_addc_u32 s19, s19, 0
	s_mov_b32 m0, s25
	s_nop 0
	global_load_lds_dwordx4 v134, s[18:19]
	s_mov_b32 m0, s26
	s_nop 0
	global_load_lds_dwordx4 v132, s[18:19]
	s_waitcnt vmcnt(8)
	s_waitcnt lgkmcnt(0)
	s_barrier
	s_setprio 1
	s_waitcnt lgkmcnt(0)
	v_mfma_f32_16x16x32_bf16 v[126:129], v[144:147], v[194:197], v[126:129]
	v_mfma_f32_16x16x32_bf16 v[122:125], v[152:155], v[194:197], v[122:125]
	v_mfma_f32_16x16x32_bf16 v[118:121], v[144:147], v[212:215], v[118:121]
	v_mfma_f32_16x16x32_bf16 v[114:117], v[152:155], v[212:215], v[114:117]
	v_mfma_f32_16x16x32_bf16 v[102:105], v[144:147], v[220:223], v[102:105]
	v_mfma_f32_16x16x32_bf16 v[98:101], v[152:155], v[220:223], v[98:101]
	v_mfma_f32_16x16x32_bf16 v[86:89], v[144:147], v[228:231], v[86:89]
	v_mfma_f32_16x16x32_bf16 v[82:85], v[152:155], v[228:231], v[82:85]
	s_setprio 0
	s_setprio 1
	v_mfma_f32_16x16x32_bf16 v[126:129], v[148:151], v[208:211], v[126:129]
	v_mfma_f32_16x16x32_bf16 v[122:125], v[156:159], v[208:211], v[122:125]
	v_mfma_f32_16x16x32_bf16 v[118:121], v[148:151], v[216:219], v[118:121]
	v_mfma_f32_16x16x32_bf16 v[114:117], v[156:159], v[216:219], v[114:117]
	v_mfma_f32_16x16x32_bf16 v[102:105], v[148:151], v[224:227], v[102:105]
	v_mfma_f32_16x16x32_bf16 v[98:101], v[156:159], v[224:227], v[98:101]
	v_mfma_f32_16x16x32_bf16 v[86:89], v[148:151], v[232:235], v[86:89]
	v_mfma_f32_16x16x32_bf16 v[82:85], v[156:159], v[232:235], v[82:85]
	s_setprio 0
	s_setprio 1
	v_mfma_f32_16x16x32_bf16 v[110:113], v[178:181], v[194:197], v[110:113]
	v_mfma_f32_16x16x32_bf16 v[106:109], v[186:189], v[194:197], v[106:109]
	v_mfma_f32_16x16x32_bf16 v[94:97], v[178:181], v[212:215], v[94:97]
	v_mfma_f32_16x16x32_bf16 v[90:93], v[186:189], v[212:215], v[90:93]
	v_mfma_f32_16x16x32_bf16 v[78:81], v[178:181], v[220:223], v[78:81]
	v_mfma_f32_16x16x32_bf16 v[74:77], v[186:189], v[220:223], v[74:77]
	v_mfma_f32_16x16x32_bf16 v[70:73], v[178:181], v[228:231], v[70:73]
	v_mfma_f32_16x16x32_bf16 v[66:69], v[186:189], v[228:231], v[66:69]
	s_setprio 0
	s_setprio 1
	v_mfma_f32_16x16x32_bf16 v[110:113], v[182:185], v[208:211], v[110:113]
	v_mfma_f32_16x16x32_bf16 v[106:109], v[190:193], v[208:211], v[106:109]
	v_mfma_f32_16x16x32_bf16 v[94:97], v[182:185], v[216:219], v[94:97]
	v_mfma_f32_16x16x32_bf16 v[90:93], v[190:193], v[216:219], v[90:93]
	v_mfma_f32_16x16x32_bf16 v[78:81], v[182:185], v[224:227], v[78:81]
	v_mfma_f32_16x16x32_bf16 v[74:77], v[190:193], v[224:227], v[74:77]
	v_mfma_f32_16x16x32_bf16 v[70:73], v[182:185], v[232:235], v[70:73]
	v_mfma_f32_16x16x32_bf16 v[66:69], v[190:193], v[232:235], v[66:69]
	s_setprio 0
	s_barrier
	ds_read_b128 v[194:197], v143 offset:49152
	ds_read_b128 v[208:211], v143 offset:50176
	ds_read_b128 v[212:215], v143 offset:51200
	ds_read_b128 v[216:219], v143 offset:52224
	ds_read_b128 v[220:223], v143 offset:53248
	ds_read_b128 v[224:227], v143 offset:54272
	ds_read_b128 v[228:231], v143 offset:55296
	ds_read_b128 v[232:235], v143 offset:56320
	s_add_i32 s18, s38, s22
	s_add_u32 s42, s16, 0x80
	s_addc_u32 s43, s17, 0
	s_mov_b32 m0, s18
	s_nop 0
	global_load_lds_dwordx4 v64, s[42:43]
	s_add_i32 m0, s18, 0x2000
	s_add_u32 s16, s16, 0x80080
	s_addc_u32 s17, s17, 0
	s_add_i32 s18, s39, s22
	global_load_lds_dwordx4 v130, s[42:43]
	s_mov_b32 m0, s18
	s_nop 0
	global_load_lds_dwordx4 v64, s[16:17]
	s_add_i32 m0, s18, 0x2000
	s_nop 0
	global_load_lds_dwordx4 v130, s[16:17]
	s_add_u32 s100, s100, 0x80
	s_addc_u32 s101, s101, 0
	s_mov_b32 m0, s27
	s_nop 0
	global_load_lds_dwordx4 v134, s[100:101]
	s_mov_b32 m0, s28
	s_nop 0
	global_load_lds_dwordx4 v132, s[100:101]
	s_waitcnt vmcnt(8)
	s_waitcnt lgkmcnt(0)
	s_barrier
	s_setprio 1
	s_waitcnt lgkmcnt(0)
	v_mfma_f32_16x16x32_bf16 v[60:63], v[144:147], v[194:197], v[60:63]
	v_mfma_f32_16x16x32_bf16 v[56:59], v[152:155], v[194:197], v[56:59]
	v_mfma_f32_16x16x32_bf16 v[52:55], v[144:147], v[212:215], v[52:55]
	v_mfma_f32_16x16x32_bf16 v[48:51], v[152:155], v[212:215], v[48:51]
	v_mfma_f32_16x16x32_bf16 v[36:39], v[144:147], v[220:223], v[36:39]
	v_mfma_f32_16x16x32_bf16 v[32:35], v[152:155], v[220:223], v[32:35]
	v_mfma_f32_16x16x32_bf16 v[20:23], v[144:147], v[228:231], v[20:23]
	v_mfma_f32_16x16x32_bf16 v[16:19], v[152:155], v[228:231], v[16:19]
	s_setprio 0
	s_setprio 1
	v_mfma_f32_16x16x32_bf16 v[60:63], v[148:151], v[208:211], v[60:63]
	v_mfma_f32_16x16x32_bf16 v[56:59], v[156:159], v[208:211], v[56:59]
	v_mfma_f32_16x16x32_bf16 v[52:55], v[148:151], v[216:219], v[52:55]
	v_mfma_f32_16x16x32_bf16 v[48:51], v[156:159], v[216:219], v[48:51]
	v_mfma_f32_16x16x32_bf16 v[36:39], v[148:151], v[224:227], v[36:39]
	v_mfma_f32_16x16x32_bf16 v[32:35], v[156:159], v[224:227], v[32:35]
	v_mfma_f32_16x16x32_bf16 v[20:23], v[148:151], v[232:235], v[20:23]
	v_mfma_f32_16x16x32_bf16 v[16:19], v[156:159], v[232:235], v[16:19]
	s_setprio 0
	s_setprio 1
	v_mfma_f32_16x16x32_bf16 v[44:47], v[178:181], v[194:197], v[44:47]
	v_mfma_f32_16x16x32_bf16 v[40:43], v[186:189], v[194:197], v[40:43]
	v_mfma_f32_16x16x32_bf16 v[28:31], v[178:181], v[212:215], v[28:31]
	v_mfma_f32_16x16x32_bf16 v[24:27], v[186:189], v[212:215], v[24:27]
	v_mfma_f32_16x16x32_bf16 v[12:15], v[178:181], v[220:223], v[12:15]
	v_mfma_f32_16x16x32_bf16 v[8:11], v[186:189], v[220:223], v[8:11]
	v_mfma_f32_16x16x32_bf16 v[4:7], v[178:181], v[228:231], v[4:7]
	v_mfma_f32_16x16x32_bf16 v[0:3], v[186:189], v[228:231], v[0:3]
	s_setprio 0
	s_setprio 1
	v_mfma_f32_16x16x32_bf16 v[44:47], v[182:185], v[208:211], v[44:47]
	v_mfma_f32_16x16x32_bf16 v[40:43], v[190:193], v[208:211], v[40:43]
	v_mfma_f32_16x16x32_bf16 v[28:31], v[182:185], v[216:219], v[28:31]
	v_mfma_f32_16x16x32_bf16 v[24:27], v[190:193], v[216:219], v[24:27]
	v_mfma_f32_16x16x32_bf16 v[12:15], v[182:185], v[224:227], v[12:15]
	v_mfma_f32_16x16x32_bf16 v[8:11], v[190:193], v[224:227], v[8:11]
	v_mfma_f32_16x16x32_bf16 v[4:7], v[182:185], v[232:235], v[4:7]
	v_mfma_f32_16x16x32_bf16 v[0:3], v[190:193], v[232:235], v[0:3]
	s_setprio 0
	s_barrier
	s_add_i32 s37, s37, 2
	s_add_u32 s0, s0, 0x100
	s_addc_u32 s1, s1, 0
	s_add_u32 s35, s35, 0x100
	s_addc_u32 s36, s36, 0
	s_cmp_gt_u32 s37, 29
	s_cbranch_scc0 .LBB0_316
	s_mov_b64 s[42:43], 0x80
	s_and_b64 vcc, exec, s[6:7]
	s_mov_b64 s[34:35], 0x45000
	s_cbranch_vccz .LBB0_319
	s_barrier

; #define PG8_STAGE(bufoff, gbase, voff) do { _Pragma("unroll") for (int _i = 0; _i < 2; ++_i) \
;         __builtin_amdgcn_global_load_lds((const unsigned*)((const char*)(gbase) + (voff)[_i]), (PG8_LAS unsigned*)(lds + (bufoff) + ldsw + _i * 8192), 16, 0, 0); } while (0)
; #define PG8_LDA(dst, b, h) do { _Pragma("unroll") for (int m = 0; m < 4; ++m) _Pragma("unroll") for (int k = 0; k < 2; ++k) dst[m][k] = *(const PG8_LAS bf16x8*)(lds + PG8_SA(b, h) + aoff + m * 2048 + k * 1024); } while (0)
; #define PG8_LDB(dst, b, h) do { _Pragma("unroll") for (int n = 0; n < 2; ++n) _Pragma("unroll") for (int k = 0; k < 2; ++k) dst[n][k] = *(const PG8_LAS bf16x8*)(lds + PG8_SB(b, h) + boff + n * 2048 + k * 1024); } while (0)
; #define PG8_MMA(ai, bj, At, Bt) do { __builtin_amdgcn_s_setprio(1); _Pragma("unroll") for (int m = 0; m < 4; ++m) _Pragma("unroll") for (int n = 0; n < 2; ++n) _Pragma("unroll") for (int k = 0; k < 2; ++k) \
;         acc[ai][bj][m][n] = __builtin_amdgcn_mfma_f32_16x16x32_bf16(Bt[n][k], At[m][k], acc[ai][bj][m][n], 0, 0, 0); __builtin_amdgcn_s_setprio(0); } while (0)
; #define PG8_WAIT_V(n) asm volatile("s_waitcnt vmcnt(" #n ")" ::: "memory")
; #define PG8_WAIT_L(n) asm volatile("s_waitcnt lgkmcnt(" #n ")" ::: "memory")
; template <class Epi, class Sched, bool ALIGN_EPI = false, bool SP2 = false>
; __device__ __forceinline__ void gemm_phase(PG8_LAS unsigned char* lds, const Gemm g, const Sched& S, const Epi& E, const int wave0) {
;     ...
;             const bool last = (t == nt - 2);
;             const char* a1 = cA + (size_t)(t + 1) * kstep;
;             const char* a2 = last ? nA : cA + (size_t)(t + 2) * kstep; const char* b2 = last ? nB : cB + (size_t)(t + 2) * kstep;
;             const char* a3 = a2 + kstep; const char* b3 = b2 + kstep;
;             if (last && has_next) S.a_ready(nxt);
;             if constexpr (SP2) {
;             PG8_LDB(B0, 0, 0); PG8_LDB(B1, 0, 1); PG8_SCHED; PG8_LDA(At, 0, 0); PG8_STAGE(PG8_SA(1, 1), a1 + hstepA, voffA);
;             PG8_WAIT_V(8); PG8_WAIT_L(0); PG8_BAR; PG8_MMA(0, 0, At, B0); PG8_MMA(0, 1, At, B1); PG8_BAR; PG8_SCHED;
;             PG8_LDA(At, 0, 1); PG8_STAGE(PG8_SB(0, 0), b2, voffB); PG8_STAGE(PG8_SB(0, 1), b2 + hstepB, voffB); PG8_STAGE(PG8_SA(0, 0), a2, voffA);
;             PG8_WAIT_V(8); PG8_WAIT_L(0); PG8_BAR; PG8_MMA(1, 0, At, B0); PG8_MMA(1, 1, At, B1); PG8_BAR; PG8_SCHED;
.LBB0_1178:
	ds_read_b128 v[130:133], v252
	ds_read_b128 v[134:137], v252 offset:1024
	ds_read_b128 v[148:151], v252 offset:2048
	ds_read_b128 v[152:155], v252 offset:3072
	ds_read_b128 v[178:181], v253
	ds_read_b128 v[182:185], v253 offset:1024
	ds_read_b128 v[186:189], v253 offset:2048
	ds_read_b128 v[190:193], v253 offset:3072
	ds_read_b128 v[194:197], v159
	ds_read_b128 v[208:211], v159 offset:1024
	ds_read_b128 v[212:215], v159 offset:2048
	ds_read_b128 v[216:219], v159 offset:3072
	ds_read_b128 v[220:223], v159 offset:4096
	ds_read_b128 v[224:227], v159 offset:5120
	ds_read_b128 v[228:231], v159 offset:6144
	ds_read_b128 v[232:235], v159 offset:7168
	s_add_u32 s2, s0, 0xfffc0080
	s_addc_u32 s3, s1, -1
	s_add_i32 s31, 0, 0x10000
	s_cmp_eq_u32 s19, 12
	s_cselect_b32 s17, s45, s3
	s_cselect_b32 s16, s44, s2
	s_cselect_b32 s3, s9, s18
	s_cselect_b32 s2, s11, s13
	s_add_i32 s33, 0, 0x14000
	s_add_i32 m0, s23, 0xc000
	s_nop 0
	global_load_lds_dwordx4 v144, s[0:1]
	s_add_i32 m0, s23, 0xe000
	s_nop 0
	global_load_lds_dwordx4 v146, s[0:1]
	s_waitcnt vmcnt(8)
	s_waitcnt lgkmcnt(0)
	s_barrier
	s_setprio 1
	s_waitcnt lgkmcnt(0)
	v_mfma_f32_16x16x32_bf16 v[126:129], v[130:133], v[194:197], v[126:129]
	v_mfma_f32_16x16x32_bf16 v[122:125], v[148:151], v[194:197], v[122:125]
	v_mfma_f32_16x16x32_bf16 v[110:113], v[130:133], v[212:215], v[110:113]
	v_mfma_f32_16x16x32_bf16 v[106:109], v[148:151], v[212:215], v[106:109]
	v_mfma_f32_16x16x32_bf16 v[94:97], v[130:133], v[220:223], v[94:97]
	v_mfma_f32_16x16x32_bf16 v[90:93], v[148:151], v[220:223], v[90:93]
	v_mfma_f32_16x16x32_bf16 v[78:81], v[130:133], v[228:231], v[78:81]
	v_mfma_f32_16x16x32_bf16 v[74:77], v[148:151], v[228:231], v[74:77]
	s_setprio 0
	s_setprio 1
	v_mfma_f32_16x16x32_bf16 v[126:129], v[134:137], v[208:211], v[126:129]
	v_mfma_f32_16x16x32_bf16 v[122:125], v[152:155], v[208:211], v[122:125]
	v_mfma_f32_16x16x32_bf16 v[110:113], v[134:137], v[216:219], v[110:113]
	v_mfma_f32_16x16x32_bf16 v[106:109], v[152:155], v[216:219], v[106:109]
	v_mfma_f32_16x16x32_bf16 v[94:97], v[134:137], v[224:227], v[94:97]
	v_mfma_f32_16x16x32_bf16 v[90:93], v[152:155], v[224:227], v[90:93]
	v_mfma_f32_16x16x32_bf16 v[78:81], v[134:137], v[232:235], v[78:81]
	v_mfma_f32_16x16x32_bf16 v[74:77], v[152:155], v[232:235], v[74:77]
	s_setprio 0
	s_setprio 1
	v_mfma_f32_16x16x32_bf16 v[118:121], v[178:181], v[194:197], v[118:121]
	v_mfma_f32_16x16x32_bf16 v[114:117], v[186:189], v[194:197], v[114:117]
	v_mfma_f32_16x16x32_bf16 v[102:105], v[178:181], v[212:215], v[102:105]
	v_mfma_f32_16x16x32_bf16 v[98:101], v[186:189], v[212:215], v[98:101]
	v_mfma_f32_16x16x32_bf16 v[86:89], v[178:181], v[220:223], v[86:89]
	v_mfma_f32_16x16x32_bf16 v[82:85], v[186:189], v[220:223], v[82:85]
	v_mfma_f32_16x16x32_bf16 v[70:73], v[178:181], v[228:231], v[70:73]
	v_mfma_f32_16x16x32_bf16 v[66:69], v[186:189], v[228:231], v[66:69]
	s_setprio 0
	s_setprio 1
	v_mfma_f32_16x16x32_bf16 v[118:121], v[182:185], v[208:211], v[118:121]
	v_mfma_f32_16x16x32_bf16 v[114:117], v[190:193], v[208:211], v[114:117]
	v_mfma_f32_16x16x32_bf16 v[102:105], v[182:185], v[216:219], v[102:105]
	v_mfma_f32_16x16x32_bf16 v[98:101], v[190:193], v[216:219], v[98:101]
	v_mfma_f32_16x16x32_bf16 v[86:89], v[182:185], v[224:227], v[86:89]
	v_mfma_f32_16x16x32_bf16 v[82:85], v[190:193], v[224:227], v[82:85]
	v_mfma_f32_16x16x32_bf16 v[70:73], v[182:185], v[232:235], v[70:73]
	v_mfma_f32_16x16x32_bf16 v[66:69], v[190:193], v[232:235], v[66:69]
	s_setprio 0
	s_barrier
	ds_read_b128 v[194:197], v159 offset:16384
	ds_read_b128 v[208:211], v159 offset:17408
	ds_read_b128 v[212:215], v159 offset:18432
	ds_read_b128 v[216:219], v159 offset:19456
	ds_read_b128 v[220:223], v159 offset:20480
	ds_read_b128 v[224:227], v159 offset:21504
	ds_read_b128 v[228:231], v159 offset:22528
	ds_read_b128 v[232:235], v159 offset:23552
	s_add_i32 s31, s31, s22
	s_mov_b32 m0, s31
	s_nop 0
	global_load_lds_dwordx4 v64, s[2:3]
	s_add_i32 m0, s31, 0x2000
	s_add_u32 s34, s2, 0x40000
	s_addc_u32 s35, s3, 0
	s_add_i32 s31, s33, s22
	global_load_lds_dwordx4 v138, s[2:3]
	s_mov_b32 m0, s31
	s_mov_b64 s[100:101], s[16:17]
	global_load_lds_dwordx4 v64, s[34:35]
	s_add_i32 m0, s31, 0x2000
	s_nop 0
	global_load_lds_dwordx4 v138, s[34:35]
	s_mov_b32 m0, s23
	s_nop 0
	global_load_lds_dwordx4 v142, s[16:17]
	s_mov_b32 m0, s24
	s_nop 0
	global_load_lds_dwordx4 v140, s[16:17]
	s_waitcnt vmcnt(8)
	s_waitcnt lgkmcnt(0)
	s_barrier
	s_setprio 1
	s_waitcnt lgkmcnt(0)
	v_mfma_f32_16x16x32_bf16 v[60:63], v[130:133], v[194:197], v[60:63]
	v_mfma_f32_16x16x32_bf16 v[56:59], v[148:151], v[194:197], v[56:59]
	v_mfma_f32_16x16x32_bf16 v[44:47], v[130:133], v[212:215], v[44:47]
	v_mfma_f32_16x16x32_bf16 v[40:43], v[148:151], v[212:215], v[40:43]
	v_mfma_f32_16x16x32_bf16 v[28:31], v[130:133], v[220:223], v[28:31]
	v_mfma_f32_16x16x32_bf16 v[24:27], v[148:151], v[220:223], v[24:27]
	v_mfma_f32_16x16x32_bf16 v[12:15], v[130:133], v[228:231], v[12:15]
	v_mfma_f32_16x16x32_bf16 v[8:11], v[148:151], v[228:231], v[8:11]
	s_setprio 0
	s_setprio 1
	v_mfma_f32_16x16x32_bf16 v[60:63], v[134:137], v[208:211], v[60:63]
	v_mfma_f32_16x16x32_bf16 v[56:59], v[152:155], v[208:211], v[56:59]
	v_mfma_f32_16x16x32_bf16 v[44:47], v[134:137], v[216:219], v[44:47]
	v_mfma_f32_16x16x32_bf16 v[40:43], v[152:155], v[216:219], v[40:43]
	v_mfma_f32_16x16x32_bf16 v[28:31], v[134:137], v[224:227], v[28:31]
	v_mfma_f32_16x16x32_bf16 v[24:27], v[152:155], v[224:227], v[24:27]
	v_mfma_f32_16x16x32_bf16 v[12:15], v[134:137], v[232:235], v[12:15]
	v_mfma_f32_16x16x32_bf16 v[8:11], v[152:155], v[232:235], v[8:11]
	s_setprio 0
	s_setprio 1
	v_mfma_f32_16x16x32_bf16 v[52:55], v[178:181], v[194:197], v[52:55]
	v_mfma_f32_16x16x32_bf16 v[48:51], v[186:189], v[194:197], v[48:51]
	v_mfma_f32_16x16x32_bf16 v[36:39], v[178:181], v[212:215], v[36:39]
	v_mfma_f32_16x16x32_bf16 v[32:35], v[186:189], v[212:215], v[32:35]
	v_mfma_f32_16x16x32_bf16 v[20:23], v[178:181], v[220:223], v[20:23]
	v_mfma_f32_16x16x32_bf16 v[16:19], v[186:189], v[220:223], v[16:19]
	v_mfma_f32_16x16x32_bf16 v[4:7], v[178:181], v[228:231], v[4:7]
	v_mfma_f32_16x16x32_bf16 v[0:3], v[186:189], v[228:231], v[0:3]
	s_setprio 0
	s_setprio 1
	v_mfma_f32_16x16x32_bf16 v[52:55], v[182:185], v[208:211], v[52:55]
	v_mfma_f32_16x16x32_bf16 v[48:51], v[190:193], v[208:211], v[48:51]
	v_mfma_f32_16x16x32_bf16 v[36:39], v[182:185], v[216:219], v[36:39]
	v_mfma_f32_16x16x32_bf16 v[32:35], v[190:193], v[216:219], v[32:35]
	v_mfma_f32_16x16x32_bf16 v[20:23], v[182:185], v[224:227], v[20:23]
	v_mfma_f32_16x16x32_bf16 v[16:19], v[190:193], v[224:227], v[16:19]
	v_mfma_f32_16x16x32_bf16 v[4:7], v[182:185], v[232:235], v[4:7]
	v_mfma_f32_16x16x32_bf16 v[0:3], v[190:193], v[232:235], v[0:3]
	s_setprio 0
	s_barrier
; #define PG8_STAGE(bufoff, gbase, voff) do { _Pragma("unroll") for (int _i = 0; _i < 2; ++_i) \
;         __builtin_amdgcn_global_load_lds((const unsigned*)((const char*)(gbase) + (voff)[_i]), (PG8_LAS unsigned*)(lds + (bufoff) + ldsw + _i * 8192), 16, 0, 0); } while (0)
; #define PG8_LDA(dst, b, h) do { _Pragma("unroll") for (int m = 0; m < 4; ++m) _Pragma("unroll") for (int k = 0; k < 2; ++k) dst[m][k] = *(const PG8_LAS bf16x8*)(lds + PG8_SA(b, h) + aoff + m * 2048 + k * 1024); } while (0)
; #define PG8_LDB(dst, b, h) do { _Pragma("unroll") for (int n = 0; n < 2; ++n) _Pragma("unroll") for (int k = 0; k < 2; ++k) dst[n][k] = *(const PG8_LAS bf16x8*)(lds + PG8_SB(b, h) + boff + n * 2048 + k * 1024); } while (0)
; #define PG8_MMA(ai, bj, At, Bt) do { __builtin_amdgcn_s_setprio(1); _Pragma("unroll") for (int m = 0; m < 4; ++m) _Pragma("unroll") for (int n = 0; n < 2; ++n) _Pragma("unroll") for (int k = 0; k < 2; ++k) \
;         acc[ai][bj][m][n] = __builtin_amdgcn_mfma_f32_16x16x32_bf16(Bt[n][k], At[m][k], acc[ai][bj][m][n], 0, 0, 0); __builtin_amdgcn_s_setprio(0); } while (0)
; #define PG8_WAIT_V(n) asm volatile("s_waitcnt vmcnt(" #n ")" ::: "memory")
; #define PG8_WAIT_L(n) asm volatile("s_waitcnt lgkmcnt(" #n ")" ::: "memory")
; #define PG8_BAR __builtin_amdgcn_s_barrier()
; #define PG8_SCHED __builtin_amdgcn_sched_barrier(0)
; template <class Epi, class Sched, bool ALIGN_EPI = false, bool SP2 = false>
; __device__ __forceinline__ void gemm_phase(PG8_LAS unsigned char* lds, const Gemm g, const Sched& S, const Epi& E, const int wave0) {
;     ...
;             PG8_LDB(B0, 1, 0); PG8_LDB(B1, 1, 1); PG8_SCHED; PG8_LDA(At, 1, 0); PG8_STAGE(PG8_SA(0, 1), a2 + hstepA, voffA);
;             PG8_WAIT_V(8); PG8_WAIT_L(0); PG8_BAR; PG8_MMA(0, 0, At, B0); PG8_MMA(0, 1, At, B1); PG8_BAR; PG8_SCHED;
;             PG8_LDA(At, 1, 1); PG8_STAGE(PG8_SB(1, 0), b3, voffB); PG8_STAGE(PG8_SB(1, 1), b3 + hstepB, voffB); PG8_STAGE(PG8_SA(1, 0), a3, voffA);
;             PG8_WAIT_V(8); PG8_WAIT_L(0); PG8_BAR; PG8_MMA(1, 0, At, B0); PG8_MMA(1, 1, At, B1); PG8_BAR; PG8_SCHED;
	ds_read_b128 v[130:133], v254
	ds_read_b128 v[134:137], v254 offset:1024
	ds_read_b128 v[148:151], v254 offset:2048
	ds_read_b128 v[152:155], v254 offset:3072
	ds_read_b128 v[178:181], v255
	ds_read_b128 v[182:185], v255 offset:1024
	ds_read_b128 v[186:189], v255 offset:2048
	ds_read_b128 v[190:193], v255 offset:3072
	ds_read_b128 v[194:197], v159 offset:32768
	ds_read_b128 v[208:211], v159 offset:33792
	ds_read_b128 v[212:215], v159 offset:34816
	ds_read_b128 v[216:219], v159 offset:35840
	ds_read_b128 v[220:223], v159 offset:36864
	ds_read_b128 v[224:227], v159 offset:37888
	ds_read_b128 v[228:231], v159 offset:38912
	ds_read_b128 v[232:235], v159 offset:39936
	s_add_i32 s31, 0, 0x18000
	s_add_i32 s33, 0, 0x1c000
	s_add_u32 s16, s16, 0x40000
	s_addc_u32 s17, s17, 0
	s_mov_b32 m0, s25
	s_nop 0
	global_load_lds_dwordx4 v142, s[16:17]
	s_mov_b32 m0, s26
	s_nop 0
	global_load_lds_dwordx4 v140, s[16:17]
	s_waitcnt vmcnt(8)
	s_waitcnt lgkmcnt(0)
	s_barrier
	s_setprio 1
	s_waitcnt lgkmcnt(0)
	v_mfma_f32_16x16x32_bf16 v[126:129], v[130:133], v[194:197], v[126:129]
	v_mfma_f32_16x16x32_bf16 v[122:125], v[148:151], v[194:197], v[122:125]
	v_mfma_f32_16x16x32_bf16 v[110:113], v[130:133], v[212:215], v[110:113]
	v_mfma_f32_16x16x32_bf16 v[106:109], v[148:151], v[212:215], v[106:109]
	v_mfma_f32_16x16x32_bf16 v[94:97], v[130:133], v[220:223], v[94:97]
	v_mfma_f32_16x16x32_bf16 v[90:93], v[148:151], v[220:223], v[90:93]
	v_mfma_f32_16x16x32_bf16 v[78:81], v[130:133], v[228:231], v[78:81]
	v_mfma_f32_16x16x32_bf16 v[74:77], v[148:151], v[228:231], v[74:77]
	s_setprio 0
	s_setprio 1
	v_mfma_f32_16x16x32_bf16 v[126:129], v[134:137], v[208:211], v[126:129]
	v_mfma_f32_16x16x32_bf16 v[122:125], v[152:155], v[208:211], v[122:125]
	v_mfma_f32_16x16x32_bf16 v[110:113], v[134:137], v[216:219], v[110:113]
	v_mfma_f32_16x16x32_bf16 v[106:109], v[152:155], v[216:219], v[106:109]
	v_mfma_f32_16x16x32_bf16 v[94:97], v[134:137], v[224:227], v[94:97]
	v_mfma_f32_16x16x32_bf16 v[90:93], v[152:155], v[224:227], v[90:93]
	v_mfma_f32_16x16x32_bf16 v[78:81], v[134:137], v[232:235], v[78:81]
	v_mfma_f32_16x16x32_bf16 v[74:77], v[152:155], v[232:235], v[74:77]
	s_setprio 0
	s_setprio 1
	v_mfma_f32_16x16x32_bf16 v[118:121], v[178:181], v[194:197], v[118:121]
	v_mfma_f32_16x16x32_bf16 v[114:117], v[186:189], v[194:197], v[114:117]
	v_mfma_f32_16x16x32_bf16 v[102:105], v[178:181], v[212:215], v[102:105]
	v_mfma_f32_16x16x32_bf16 v[98:101], v[186:189], v[212:215], v[98:101]
	v_mfma_f32_16x16x32_bf16 v[86:89], v[178:181], v[220:223], v[86:89]
	v_mfma_f32_16x16x32_bf16 v[82:85], v[186:189], v[220:223], v[82:85]
	v_mfma_f32_16x16x32_bf16 v[70:73], v[178:181], v[228:231], v[70:73]
	v_mfma_f32_16x16x32_bf16 v[66:69], v[186:189], v[228:231], v[66:69]
	s_setprio 0
	s_setprio 1
	v_mfma_f32_16x16x32_bf16 v[118:121], v[182:185], v[208:211], v[118:121]
	v_mfma_f32_16x16x32_bf16 v[114:117], v[190:193], v[208:211], v[114:117]
	v_mfma_f32_16x16x32_bf16 v[102:105], v[182:185], v[216:219], v[102:105]
	v_mfma_f32_16x16x32_bf16 v[98:101], v[190:193], v[216:219], v[98:101]
	v_mfma_f32_16x16x32_bf16 v[86:89], v[182:185], v[224:227], v[86:89]
	v_mfma_f32_16x16x32_bf16 v[82:85], v[190:193], v[224:227], v[82:85]
	v_mfma_f32_16x16x32_bf16 v[70:73], v[182:185], v[232:235], v[70:73]
	v_mfma_f32_16x16x32_bf16 v[66:69], v[190:193], v[232:235], v[66:69]
	s_setprio 0
	s_barrier
	ds_read_b128 v[194:197], v159 offset:49152
	ds_read_b128 v[208:211], v159 offset:50176
	ds_read_b128 v[212:215], v159 offset:51200
	ds_read_b128 v[216:219], v159 offset:52224
	ds_read_b128 v[220:223], v159 offset:53248
	ds_read_b128 v[224:227], v159 offset:54272
	ds_read_b128 v[228:231], v159 offset:55296
	ds_read_b128 v[232:235], v159 offset:56320
	s_add_i32 s16, s31, s22
	s_add_u32 s36, s2, 0x80
	s_addc_u32 s37, s3, 0
	s_mov_b32 m0, s16
	s_nop 0
	global_load_lds_dwordx4 v64, s[36:37]
	s_add_i32 m0, s16, 0x2000
	s_add_u32 s2, s2, 0x40080
	s_addc_u32 s3, s3, 0
	s_add_i32 s16, s33, s22
	global_load_lds_dwordx4 v138, s[36:37]
	s_mov_b32 m0, s16
	s_nop 0
	global_load_lds_dwordx4 v64, s[2:3]
	s_add_i32 m0, s16, 0x2000
	s_nop 0
	global_load_lds_dwordx4 v138, s[2:3]
	s_add_u32 s100, s100, 0x80
	s_addc_u32 s101, s101, 0
	s_mov_b32 m0, s27
	s_nop 0
	global_load_lds_dwordx4 v142, s[100:101]
	s_mov_b32 m0, s28
	s_nop 0
	global_load_lds_dwordx4 v140, s[100:101]
	s_waitcnt vmcnt(8)
	s_waitcnt lgkmcnt(0)
	s_barrier
	s_setprio 1
	s_waitcnt lgkmcnt(0)
	v_mfma_f32_16x16x32_bf16 v[60:63], v[130:133], v[194:197], v[60:63]
	v_mfma_f32_16x16x32_bf16 v[56:59], v[148:151], v[194:197], v[56:59]
	v_mfma_f32_16x16x32_bf16 v[44:47], v[130:133], v[212:215], v[44:47]
	v_mfma_f32_16x16x32_bf16 v[40:43], v[148:151], v[212:215], v[40:43]
	v_mfma_f32_16x16x32_bf16 v[28:31], v[130:133], v[220:223], v[28:31]
	v_mfma_f32_16x16x32_bf16 v[24:27], v[148:151], v[220:223], v[24:27]
	v_mfma_f32_16x16x32_bf16 v[12:15], v[130:133], v[228:231], v[12:15]
	v_mfma_f32_16x16x32_bf16 v[8:11], v[148:151], v[228:231], v[8:11]
	s_setprio 0
	s_setprio 1
	v_mfma_f32_16x16x32_bf16 v[60:63], v[134:137], v[208:211], v[60:63]
	v_mfma_f32_16x16x32_bf16 v[56:59], v[152:155], v[208:211], v[56:59]
	v_mfma_f32_16x16x32_bf16 v[44:47], v[134:137], v[216:219], v[44:47]
	v_mfma_f32_16x16x32_bf16 v[40:43], v[152:155], v[216:219], v[40:43]
	v_mfma_f32_16x16x32_bf16 v[28:31], v[134:137], v[224:227], v[28:31]
	v_mfma_f32_16x16x32_bf16 v[24:27], v[152:155], v[224:227], v[24:27]
	v_mfma_f32_16x16x32_bf16 v[12:15], v[134:137], v[232:235], v[12:15]
	v_mfma_f32_16x16x32_bf16 v[8:11], v[152:155], v[232:235], v[8:11]
	s_setprio 0
	s_setprio 1
	v_mfma_f32_16x16x32_bf16 v[52:55], v[178:181], v[194:197], v[52:55]
	v_mfma_f32_16x16x32_bf16 v[48:51], v[186:189], v[194:197], v[48:51]
	v_mfma_f32_16x16x32_bf16 v[36:39], v[178:181], v[212:215], v[36:39]
	v_mfma_f32_16x16x32_bf16 v[32:35], v[186:189], v[212:215], v[32:35]
	v_mfma_f32_16x16x32_bf16 v[20:23], v[178:181], v[220:223], v[20:23]
	v_mfma_f32_16x16x32_bf16 v[16:19], v[186:189], v[220:223], v[16:19]
	v_mfma_f32_16x16x32_bf16 v[4:7], v[178:181], v[228:231], v[4:7]
	v_mfma_f32_16x16x32_bf16 v[0:3], v[186:189], v[228:231], v[0:3]
	s_setprio 0
	s_setprio 1
	v_mfma_f32_16x16x32_bf16 v[52:55], v[182:185], v[208:211], v[52:55]
	v_mfma_f32_16x16x32_bf16 v[48:51], v[190:193], v[208:211], v[48:51]
	v_mfma_f32_16x16x32_bf16 v[36:39], v[182:185], v[216:219], v[36:39]
	v_mfma_f32_16x16x32_bf16 v[32:35], v[190:193], v[216:219], v[32:35]
	v_mfma_f32_16x16x32_bf16 v[20:23], v[182:185], v[224:227], v[20:23]
	v_mfma_f32_16x16x32_bf16 v[16:19], v[190:193], v[224:227], v[16:19]
	v_mfma_f32_16x16x32_bf16 v[4:7], v[182:185], v[232:235], v[4:7]
	v_mfma_f32_16x16x32_bf16 v[0:3], v[190:193], v[232:235], v[0:3]
	s_setprio 0
	s_barrier
	s_add_i32 s19, s19, 2
	s_add_u32 s0, s0, 0x100
	s_addc_u32 s1, s1, 0
	s_add_u32 s13, s13, 0x100
	s_addc_u32 s18, s18, 0
	s_cmp_gt_u32 s19, 13
	s_cbranch_scc0 .LBB0_1178
	s_mov_b64 s[36:37], 0x80
	s_and_b64 vcc, exec, s[6:7]
	s_cbranch_vccz .LBB0_1181
	s_barrier

; #define PG8_STAGE(bufoff, gbase, voff) do { _Pragma("unroll") for (int _i = 0; _i < 2; ++_i) \
;         __builtin_amdgcn_global_load_lds((const unsigned*)((const char*)(gbase) + (voff)[_i]), (PG8_LAS unsigned*)(lds + (bufoff) + ldsw + _i * 8192), 16, 0, 0); } while (0)
; #define PG8_LDA(dst, b, h) do { _Pragma("unroll") for (int m = 0; m < 4; ++m) _Pragma("unroll") for (int k = 0; k < 2; ++k) dst[m][k] = *(const PG8_LAS bf16x8*)(lds + PG8_SA(b, h) + aoff + m * 2048 + k * 1024); } while (0)
; #define PG8_LDB(dst, b, h) do { _Pragma("unroll") for (int n = 0; n < 2; ++n) _Pragma("unroll") for (int k = 0; k < 2; ++k) dst[n][k] = *(const PG8_LAS bf16x8*)(lds + PG8_SB(b, h) + boff + n * 2048 + k * 1024); } while (0)
; #define PG8_MMA(ai, bj, At, Bt) do { __builtin_amdgcn_s_setprio(1); _Pragma("unroll") for (int m = 0; m < 4; ++m) _Pragma("unroll") for (int n = 0; n < 2; ++n) _Pragma("unroll") for (int k = 0; k < 2; ++k) \
;         acc[ai][bj][m][n] = __builtin_amdgcn_mfma_f32_16x16x32_bf16(Bt[n][k], At[m][k], acc[ai][bj][m][n], 0, 0, 0); __builtin_amdgcn_s_setprio(0); } while (0)
; #define PG8_WAIT_V(n) asm volatile("s_waitcnt vmcnt(" #n ")" ::: "memory")
; #define PG8_WAIT_L(n) asm volatile("s_waitcnt lgkmcnt(" #n ")" ::: "memory")
; template <class Epi, class Sched, bool ALIGN_EPI = false, bool SP2 = false>
; __device__ __forceinline__ void gemm_phase(PG8_LAS unsigned char* lds, const Gemm g, const Sched& S, const Epi& E, const int wave0) {
;     ...
;             const bool last = (t == nt - 2);
;             const char* a1 = cA + (size_t)(t + 1) * kstep;
;             const char* a2 = last ? nA : cA + (size_t)(t + 2) * kstep; const char* b2 = last ? nB : cB + (size_t)(t + 2) * kstep;
;             const char* a3 = a2 + kstep; const char* b3 = b2 + kstep;
;             if (last && has_next) S.a_ready(nxt);
;             if constexpr (SP2) {
;             PG8_LDB(B0, 0, 0); PG8_LDB(B1, 0, 1); PG8_SCHED; PG8_LDA(At, 0, 0); PG8_STAGE(PG8_SA(1, 1), a1 + hstepA, voffA);
;             PG8_WAIT_V(8); PG8_WAIT_L(0); PG8_BAR; PG8_MMA(0, 0, At, B0); PG8_MMA(0, 1, At, B1); PG8_BAR; PG8_SCHED;
;             PG8_LDA(At, 0, 1); PG8_STAGE(PG8_SB(0, 0), b2, voffB); PG8_STAGE(PG8_SB(0, 1), b2 + hstepB, voffB); PG8_STAGE(PG8_SA(0, 0), a2, voffA);
;             PG8_WAIT_V(8); PG8_WAIT_L(0); PG8_BAR; PG8_MMA(1, 0, At, B0); PG8_MMA(1, 1, At, B1); PG8_BAR; PG8_SCHED;
.LBB0_1231:
	ds_read_b128 v[140:143], v252
	ds_read_b128 v[144:147], v252 offset:1024
	ds_read_b128 v[154:157], v252 offset:2048
	ds_read_b128 v[158:161], v252 offset:3072
	ds_read_b128 v[178:181], v253
	ds_read_b128 v[182:185], v253 offset:1024
	ds_read_b128 v[186:189], v253 offset:2048
	ds_read_b128 v[190:193], v253 offset:3072
	ds_read_b128 v[194:197], v153
	ds_read_b128 v[208:211], v153 offset:1024
	ds_read_b128 v[212:215], v153 offset:2048
	ds_read_b128 v[216:219], v153 offset:3072
	ds_read_b128 v[220:223], v153 offset:4096
	ds_read_b128 v[224:227], v153 offset:5120
	ds_read_b128 v[228:231], v153 offset:6144
	ds_read_b128 v[232:235], v153 offset:7168
	s_add_u32 s2, s0, 0xfffc0080
	s_addc_u32 s3, s1, -1
	s_add_i32 s31, 0, 0x10000
	s_cmp_eq_u32 s19, 12
	s_cselect_b32 s17, s43, s3
	s_cselect_b32 s16, s42, s2
	s_cselect_b32 s3, s9, s18
	s_cselect_b32 s2, s11, s13
	s_add_i32 s33, 0, 0x14000
	s_add_i32 m0, s23, 0xc000
	s_nop 0
	global_load_lds_dwordx4 v136, s[0:1]
	s_add_i32 m0, s23, 0xe000
	s_nop 0
	global_load_lds_dwordx4 v138, s[0:1]
	s_waitcnt vmcnt(8)
	s_waitcnt lgkmcnt(0)
	s_barrier
	s_setprio 1
	s_waitcnt lgkmcnt(0)
	v_mfma_f32_16x16x32_bf16 v[126:129], v[140:143], v[194:197], v[126:129]
	v_mfma_f32_16x16x32_bf16 v[122:125], v[154:157], v[194:197], v[122:125]
	v_mfma_f32_16x16x32_bf16 v[110:113], v[140:143], v[212:215], v[110:113]
	v_mfma_f32_16x16x32_bf16 v[106:109], v[154:157], v[212:215], v[106:109]
	v_mfma_f32_16x16x32_bf16 v[94:97], v[140:143], v[220:223], v[94:97]
	v_mfma_f32_16x16x32_bf16 v[90:93], v[154:157], v[220:223], v[90:93]
	v_mfma_f32_16x16x32_bf16 v[78:81], v[140:143], v[228:231], v[78:81]
	v_mfma_f32_16x16x32_bf16 v[74:77], v[154:157], v[228:231], v[74:77]
	s_setprio 0
	s_setprio 1
	v_mfma_f32_16x16x32_bf16 v[126:129], v[144:147], v[208:211], v[126:129]
	v_mfma_f32_16x16x32_bf16 v[122:125], v[158:161], v[208:211], v[122:125]
	v_mfma_f32_16x16x32_bf16 v[110:113], v[144:147], v[216:219], v[110:113]
	v_mfma_f32_16x16x32_bf16 v[106:109], v[158:161], v[216:219], v[106:109]
	v_mfma_f32_16x16x32_bf16 v[94:97], v[144:147], v[224:227], v[94:97]
	v_mfma_f32_16x16x32_bf16 v[90:93], v[158:161], v[224:227], v[90:93]
	v_mfma_f32_16x16x32_bf16 v[78:81], v[144:147], v[232:235], v[78:81]
	v_mfma_f32_16x16x32_bf16 v[74:77], v[158:161], v[232:235], v[74:77]
	s_setprio 0
	s_setprio 1
	v_mfma_f32_16x16x32_bf16 v[118:121], v[178:181], v[194:197], v[118:121]
	v_mfma_f32_16x16x32_bf16 v[114:117], v[186:189], v[194:197], v[114:117]
	v_mfma_f32_16x16x32_bf16 v[102:105], v[178:181], v[212:215], v[102:105]
	v_mfma_f32_16x16x32_bf16 v[98:101], v[186:189], v[212:215], v[98:101]
	v_mfma_f32_16x16x32_bf16 v[86:89], v[178:181], v[220:223], v[86:89]
	v_mfma_f32_16x16x32_bf16 v[82:85], v[186:189], v[220:223], v[82:85]
	v_mfma_f32_16x16x32_bf16 v[70:73], v[178:181], v[228:231], v[70:73]
	v_mfma_f32_16x16x32_bf16 v[66:69], v[186:189], v[228:231], v[66:69]
	s_setprio 0
	s_setprio 1
	v_mfma_f32_16x16x32_bf16 v[118:121], v[182:185], v[208:211], v[118:121]
	v_mfma_f32_16x16x32_bf16 v[114:117], v[190:193], v[208:211], v[114:117]
	v_mfma_f32_16x16x32_bf16 v[102:105], v[182:185], v[216:219], v[102:105]
	v_mfma_f32_16x16x32_bf16 v[98:101], v[190:193], v[216:219], v[98:101]
	v_mfma_f32_16x16x32_bf16 v[86:89], v[182:185], v[224:227], v[86:89]
	v_mfma_f32_16x16x32_bf16 v[82:85], v[190:193], v[224:227], v[82:85]
	v_mfma_f32_16x16x32_bf16 v[70:73], v[182:185], v[232:235], v[70:73]
	v_mfma_f32_16x16x32_bf16 v[66:69], v[190:193], v[232:235], v[66:69]
	s_setprio 0
	s_barrier
	ds_read_b128 v[194:197], v153 offset:16384
	ds_read_b128 v[208:211], v153 offset:17408
	ds_read_b128 v[212:215], v153 offset:18432
	ds_read_b128 v[216:219], v153 offset:19456
	ds_read_b128 v[220:223], v153 offset:20480
	ds_read_b128 v[224:227], v153 offset:21504
	ds_read_b128 v[228:231], v153 offset:22528
	ds_read_b128 v[232:235], v153 offset:23552
	s_add_i32 s31, s31, s22
	s_mov_b32 m0, s31
	s_nop 0
	global_load_lds_dwordx4 v64, s[2:3]
	s_add_i32 m0, s31, 0x2000
	s_add_u32 s34, s2, 0x40000
	s_addc_u32 s35, s3, 0
	s_add_i32 s31, s33, s22
	global_load_lds_dwordx4 v130, s[2:3]
	s_mov_b32 m0, s31
	s_mov_b64 s[100:101], s[16:17]
	global_load_lds_dwordx4 v64, s[34:35]
	s_add_i32 m0, s31, 0x2000
	s_nop 0
	global_load_lds_dwordx4 v130, s[34:35]
	s_mov_b32 m0, s23
	s_nop 0
	global_load_lds_dwordx4 v134, s[16:17]
	s_mov_b32 m0, s24
	s_nop 0
	global_load_lds_dwordx4 v132, s[16:17]
	s_waitcnt vmcnt(8)
	s_waitcnt lgkmcnt(0)
	s_barrier
	s_setprio 1
	s_waitcnt lgkmcnt(0)
	v_mfma_f32_16x16x32_bf16 v[60:63], v[140:143], v[194:197], v[60:63]
	v_mfma_f32_16x16x32_bf16 v[56:59], v[154:157], v[194:197], v[56:59]
	v_mfma_f32_16x16x32_bf16 v[44:47], v[140:143], v[212:215], v[44:47]
	v_mfma_f32_16x16x32_bf16 v[40:43], v[154:157], v[212:215], v[40:43]
	v_mfma_f32_16x16x32_bf16 v[28:31], v[140:143], v[220:223], v[28:31]
	v_mfma_f32_16x16x32_bf16 v[24:27], v[154:157], v[220:223], v[24:27]
	v_mfma_f32_16x16x32_bf16 v[12:15], v[140:143], v[228:231], v[12:15]
	v_mfma_f32_16x16x32_bf16 v[8:11], v[154:157], v[228:231], v[8:11]
	s_setprio 0
	s_setprio 1
	v_mfma_f32_16x16x32_bf16 v[60:63], v[144:147], v[208:211], v[60:63]
	v_mfma_f32_16x16x32_bf16 v[56:59], v[158:161], v[208:211], v[56:59]
	v_mfma_f32_16x16x32_bf16 v[44:47], v[144:147], v[216:219], v[44:47]
	v_mfma_f32_16x16x32_bf16 v[40:43], v[158:161], v[216:219], v[40:43]
	v_mfma_f32_16x16x32_bf16 v[28:31], v[144:147], v[224:227], v[28:31]
	v_mfma_f32_16x16x32_bf16 v[24:27], v[158:161], v[224:227], v[24:27]
	v_mfma_f32_16x16x32_bf16 v[12:15], v[144:147], v[232:235], v[12:15]
	v_mfma_f32_16x16x32_bf16 v[8:11], v[158:161], v[232:235], v[8:11]
	s_setprio 0
	s_setprio 1
	v_mfma_f32_16x16x32_bf16 v[52:55], v[178:181], v[194:197], v[52:55]
	v_mfma_f32_16x16x32_bf16 v[48:51], v[186:189], v[194:197], v[48:51]
	v_mfma_f32_16x16x32_bf16 v[36:39], v[178:181], v[212:215], v[36:39]
	v_mfma_f32_16x16x32_bf16 v[32:35], v[186:189], v[212:215], v[32:35]
	v_mfma_f32_16x16x32_bf16 v[20:23], v[178:181], v[220:223], v[20:23]
	v_mfma_f32_16x16x32_bf16 v[16:19], v[186:189], v[220:223], v[16:19]
	v_mfma_f32_16x16x32_bf16 v[4:7], v[178:181], v[228:231], v[4:7]
	v_mfma_f32_16x16x32_bf16 v[0:3], v[186:189], v[228:231], v[0:3]
	s_setprio 0
	s_setprio 1
	v_mfma_f32_16x16x32_bf16 v[52:55], v[182:185], v[208:211], v[52:55]
	v_mfma_f32_16x16x32_bf16 v[48:51], v[190:193], v[208:211], v[48:51]
	v_mfma_f32_16x16x32_bf16 v[36:39], v[182:185], v[216:219], v[36:39]
	v_mfma_f32_16x16x32_bf16 v[32:35], v[190:193], v[216:219], v[32:35]
	v_mfma_f32_16x16x32_bf16 v[20:23], v[182:185], v[224:227], v[20:23]
	v_mfma_f32_16x16x32_bf16 v[16:19], v[190:193], v[224:227], v[16:19]
	v_mfma_f32_16x16x32_bf16 v[4:7], v[182:185], v[232:235], v[4:7]
	v_mfma_f32_16x16x32_bf16 v[0:3], v[190:193], v[232:235], v[0:3]
	s_setprio 0
	s_barrier
; #define PG8_STAGE(bufoff, gbase, voff) do { _Pragma("unroll") for (int _i = 0; _i < 2; ++_i) \
;         __builtin_amdgcn_global_load_lds((const unsigned*)((const char*)(gbase) + (voff)[_i]), (PG8_LAS unsigned*)(lds + (bufoff) + ldsw + _i * 8192), 16, 0, 0); } while (0)
; #define PG8_LDA(dst, b, h) do { _Pragma("unroll") for (int m = 0; m < 4; ++m) _Pragma("unroll") for (int k = 0; k < 2; ++k) dst[m][k] = *(const PG8_LAS bf16x8*)(lds + PG8_SA(b, h) + aoff + m * 2048 + k * 1024); } while (0)
; #define PG8_LDB(dst, b, h) do { _Pragma("unroll") for (int n = 0; n < 2; ++n) _Pragma("unroll") for (int k = 0; k < 2; ++k) dst[n][k] = *(const PG8_LAS bf16x8*)(lds + PG8_SB(b, h) + boff + n * 2048 + k * 1024); } while (0)
; #define PG8_MMA(ai, bj, At, Bt) do { __builtin_amdgcn_s_setprio(1); _Pragma("unroll") for (int m = 0; m < 4; ++m) _Pragma("unroll") for (int n = 0; n < 2; ++n) _Pragma("unroll") for (int k = 0; k < 2; ++k) \
;         acc[ai][bj][m][n] = __builtin_amdgcn_mfma_f32_16x16x32_bf16(Bt[n][k], At[m][k], acc[ai][bj][m][n], 0, 0, 0); __builtin_amdgcn_s_setprio(0); } while (0)
; #define PG8_WAIT_V(n) asm volatile("s_waitcnt vmcnt(" #n ")" ::: "memory")
; #define PG8_WAIT_L(n) asm volatile("s_waitcnt lgkmcnt(" #n ")" ::: "memory")
; #define PG8_BAR __builtin_amdgcn_s_barrier()
; #define PG8_SCHED __builtin_amdgcn_sched_barrier(0)
; template <class Epi, class Sched, bool ALIGN_EPI = false, bool SP2 = false>
; __device__ __forceinline__ void gemm_phase(PG8_LAS unsigned char* lds, const Gemm g, const Sched& S, const Epi& E, const int wave0) {
;     ...
;             PG8_LDB(B0, 1, 0); PG8_LDB(B1, 1, 1); PG8_SCHED; PG8_LDA(At, 1, 0); PG8_STAGE(PG8_SA(0, 1), a2 + hstepA, voffA);
;             PG8_WAIT_V(8); PG8_WAIT_L(0); PG8_BAR; PG8_MMA(0, 0, At, B0); PG8_MMA(0, 1, At, B1); PG8_BAR; PG8_SCHED;
;             PG8_LDA(At, 1, 1); PG8_STAGE(PG8_SB(1, 0), b3, voffB); PG8_STAGE(PG8_SB(1, 1), b3 + hstepB, voffB); PG8_STAGE(PG8_SA(1, 0), a3, voffA);
;             PG8_WAIT_V(8); PG8_WAIT_L(0); PG8_BAR; PG8_MMA(1, 0, At, B0); PG8_MMA(1, 1, At, B1); PG8_BAR; PG8_SCHED;
	ds_read_b128 v[140:143], v254
	ds_read_b128 v[144:147], v254 offset:1024
	ds_read_b128 v[154:157], v254 offset:2048
	ds_read_b128 v[158:161], v254 offset:3072
	ds_read_b128 v[178:181], v255
	ds_read_b128 v[182:185], v255 offset:1024
	ds_read_b128 v[186:189], v255 offset:2048
	ds_read_b128 v[190:193], v255 offset:3072
	ds_read_b128 v[194:197], v153 offset:32768
	ds_read_b128 v[208:211], v153 offset:33792
	ds_read_b128 v[212:215], v153 offset:34816
	ds_read_b128 v[216:219], v153 offset:35840
	ds_read_b128 v[220:223], v153 offset:36864
	ds_read_b128 v[224:227], v153 offset:37888
	ds_read_b128 v[228:231], v153 offset:38912
	ds_read_b128 v[232:235], v153 offset:39936
	s_add_i32 s31, 0, 0x18000
	s_add_i32 s33, 0, 0x1c000
	s_add_u32 s16, s16, 0x40000
	s_addc_u32 s17, s17, 0
	s_mov_b32 m0, s25
	s_nop 0
	global_load_lds_dwordx4 v134, s[16:17]
	s_mov_b32 m0, s26
	s_nop 0
	global_load_lds_dwordx4 v132, s[16:17]
	s_waitcnt vmcnt(8)
	s_waitcnt lgkmcnt(0)
	s_barrier
	s_setprio 1
	s_waitcnt lgkmcnt(0)
	v_mfma_f32_16x16x32_bf16 v[126:129], v[140:143], v[194:197], v[126:129]
	v_mfma_f32_16x16x32_bf16 v[122:125], v[154:157], v[194:197], v[122:125]
	v_mfma_f32_16x16x32_bf16 v[110:113], v[140:143], v[212:215], v[110:113]
	v_mfma_f32_16x16x32_bf16 v[106:109], v[154:157], v[212:215], v[106:109]
	v_mfma_f32_16x16x32_bf16 v[94:97], v[140:143], v[220:223], v[94:97]
	v_mfma_f32_16x16x32_bf16 v[90:93], v[154:157], v[220:223], v[90:93]
	v_mfma_f32_16x16x32_bf16 v[78:81], v[140:143], v[228:231], v[78:81]
	v_mfma_f32_16x16x32_bf16 v[74:77], v[154:157], v[228:231], v[74:77]
	s_setprio 0
	s_setprio 1
	v_mfma_f32_16x16x32_bf16 v[126:129], v[144:147], v[208:211], v[126:129]
	v_mfma_f32_16x16x32_bf16 v[122:125], v[158:161], v[208:211], v[122:125]
	v_mfma_f32_16x16x32_bf16 v[110:113], v[144:147], v[216:219], v[110:113]
	v_mfma_f32_16x16x32_bf16 v[106:109], v[158:161], v[216:219], v[106:109]
	v_mfma_f32_16x16x32_bf16 v[94:97], v[144:147], v[224:227], v[94:97]
	v_mfma_f32_16x16x32_bf16 v[90:93], v[158:161], v[224:227], v[90:93]
	v_mfma_f32_16x16x32_bf16 v[78:81], v[144:147], v[232:235], v[78:81]
	v_mfma_f32_16x16x32_bf16 v[74:77], v[158:161], v[232:235], v[74:77]
	s_setprio 0
	s_setprio 1
	v_mfma_f32_16x16x32_bf16 v[118:121], v[178:181], v[194:197], v[118:121]
	v_mfma_f32_16x16x32_bf16 v[114:117], v[186:189], v[194:197], v[114:117]
	v_mfma_f32_16x16x32_bf16 v[102:105], v[178:181], v[212:215], v[102:105]
	v_mfma_f32_16x16x32_bf16 v[98:101], v[186:189], v[212:215], v[98:101]
	v_mfma_f32_16x16x32_bf16 v[86:89], v[178:181], v[220:223], v[86:89]
	v_mfma_f32_16x16x32_bf16 v[82:85], v[186:189], v[220:223], v[82:85]
	v_mfma_f32_16x16x32_bf16 v[70:73], v[178:181], v[228:231], v[70:73]
	v_mfma_f32_16x16x32_bf16 v[66:69], v[186:189], v[228:231], v[66:69]
	s_setprio 0
	s_setprio 1
	v_mfma_f32_16x16x32_bf16 v[118:121], v[182:185], v[208:211], v[118:121]
	v_mfma_f32_16x16x32_bf16 v[114:117], v[190:193], v[208:211], v[114:117]
	v_mfma_f32_16x16x32_bf16 v[102:105], v[182:185], v[216:219], v[102:105]
	v_mfma_f32_16x16x32_bf16 v[98:101], v[190:193], v[216:219], v[98:101]
	v_mfma_f32_16x16x32_bf16 v[86:89], v[182:185], v[224:227], v[86:89]
	v_mfma_f32_16x16x32_bf16 v[82:85], v[190:193], v[224:227], v[82:85]
	v_mfma_f32_16x16x32_bf16 v[70:73], v[182:185], v[232:235], v[70:73]
	v_mfma_f32_16x16x32_bf16 v[66:69], v[190:193], v[232:235], v[66:69]
	s_setprio 0
	s_barrier
	ds_read_b128 v[194:197], v153 offset:49152
	ds_read_b128 v[208:211], v153 offset:50176
	ds_read_b128 v[212:215], v153 offset:51200
	ds_read_b128 v[216:219], v153 offset:52224
	ds_read_b128 v[220:223], v153 offset:53248
	ds_read_b128 v[224:227], v153 offset:54272
	ds_read_b128 v[228:231], v153 offset:55296
	ds_read_b128 v[232:235], v153 offset:56320
	s_add_i32 s16, s31, s22
	s_add_u32 s36, s2, 0x80
	s_addc_u32 s37, s3, 0
	s_mov_b32 m0, s16
	s_nop 0
	global_load_lds_dwordx4 v64, s[36:37]
	s_add_i32 m0, s16, 0x2000
	s_add_u32 s2, s2, 0x40080
	s_addc_u32 s3, s3, 0
	s_add_i32 s16, s33, s22
	global_load_lds_dwordx4 v130, s[36:37]
	s_mov_b32 m0, s16
	s_nop 0
	global_load_lds_dwordx4 v64, s[2:3]
	s_add_i32 m0, s16, 0x2000
	s_nop 0
	global_load_lds_dwordx4 v130, s[2:3]
	s_add_u32 s100, s100, 0x80
	s_addc_u32 s101, s101, 0
	s_mov_b32 m0, s27
	s_nop 0
	global_load_lds_dwordx4 v134, s[100:101]
	s_mov_b32 m0, s28
	s_nop 0
	global_load_lds_dwordx4 v132, s[100:101]
	s_waitcnt vmcnt(8)
	s_waitcnt lgkmcnt(0)
	s_barrier
	s_setprio 1
	s_waitcnt lgkmcnt(0)
	v_mfma_f32_16x16x32_bf16 v[60:63], v[140:143], v[194:197], v[60:63]
	v_mfma_f32_16x16x32_bf16 v[56:59], v[154:157], v[194:197], v[56:59]
	v_mfma_f32_16x16x32_bf16 v[44:47], v[140:143], v[212:215], v[44:47]
	v_mfma_f32_16x16x32_bf16 v[40:43], v[154:157], v[212:215], v[40:43]
	v_mfma_f32_16x16x32_bf16 v[28:31], v[140:143], v[220:223], v[28:31]
	v_mfma_f32_16x16x32_bf16 v[24:27], v[154:157], v[220:223], v[24:27]
	v_mfma_f32_16x16x32_bf16 v[12:15], v[140:143], v[228:231], v[12:15]
	v_mfma_f32_16x16x32_bf16 v[8:11], v[154:157], v[228:231], v[8:11]
	s_setprio 0
	s_setprio 1
	v_mfma_f32_16x16x32_bf16 v[60:63], v[144:147], v[208:211], v[60:63]
	v_mfma_f32_16x16x32_bf16 v[56:59], v[158:161], v[208:211], v[56:59]
	v_mfma_f32_16x16x32_bf16 v[44:47], v[144:147], v[216:219], v[44:47]
	v_mfma_f32_16x16x32_bf16 v[40:43], v[158:161], v[216:219], v[40:43]
	v_mfma_f32_16x16x32_bf16 v[28:31], v[144:147], v[224:227], v[28:31]
	v_mfma_f32_16x16x32_bf16 v[24:27], v[158:161], v[224:227], v[24:27]
	v_mfma_f32_16x16x32_bf16 v[12:15], v[144:147], v[232:235], v[12:15]
	v_mfma_f32_16x16x32_bf16 v[8:11], v[158:161], v[232:235], v[8:11]
	s_setprio 0
	s_setprio 1
	v_mfma_f32_16x16x32_bf16 v[52:55], v[178:181], v[194:197], v[52:55]
	v_mfma_f32_16x16x32_bf16 v[48:51], v[186:189], v[194:197], v[48:51]
	v_mfma_f32_16x16x32_bf16 v[36:39], v[178:181], v[212:215], v[36:39]
	v_mfma_f32_16x16x32_bf16 v[32:35], v[186:189], v[212:215], v[32:35]
	v_mfma_f32_16x16x32_bf16 v[20:23], v[178:181], v[220:223], v[20:23]
	v_mfma_f32_16x16x32_bf16 v[16:19], v[186:189], v[220:223], v[16:19]
	v_mfma_f32_16x16x32_bf16 v[4:7], v[178:181], v[228:231], v[4:7]
	v_mfma_f32_16x16x32_bf16 v[0:3], v[186:189], v[228:231], v[0:3]
	s_setprio 0
	s_setprio 1
	v_mfma_f32_16x16x32_bf16 v[52:55], v[182:185], v[208:211], v[52:55]
	v_mfma_f32_16x16x32_bf16 v[48:51], v[190:193], v[208:211], v[48:51]
	v_mfma_f32_16x16x32_bf16 v[36:39], v[182:185], v[216:219], v[36:39]
	v_mfma_f32_16x16x32_bf16 v[32:35], v[190:193], v[216:219], v[32:35]
	v_mfma_f32_16x16x32_bf16 v[20:23], v[182:185], v[224:227], v[20:23]
	v_mfma_f32_16x16x32_bf16 v[16:19], v[190:193], v[224:227], v[16:19]
	v_mfma_f32_16x16x32_bf16 v[4:7], v[182:185], v[232:235], v[4:7]
	v_mfma_f32_16x16x32_bf16 v[0:3], v[190:193], v[232:235], v[0:3]
	s_setprio 0
	s_barrier
	s_add_i32 s19, s19, 2
	s_add_u32 s0, s0, 0x100
	s_addc_u32 s1, s1, 0
	s_add_u32 s13, s13, 0x100
	s_addc_u32 s18, s18, 0
	s_cmp_gt_u32 s19, 13
	s_cbranch_scc0 .LBB0_1231
	s_mov_b64 s[36:37], 0x80
	s_and_b64 vcc, exec, s[6:7]
	s_cbranch_vccz .LBB0_1234
	s_barrier

; #define PG8_STAGE(bufoff, gbase, voff) do { _Pragma("unroll") for (int _i = 0; _i < 2; ++_i) \
;         __builtin_amdgcn_global_load_lds((const unsigned*)((const char*)(gbase) + (voff)[_i]), (PG8_LAS unsigned*)(lds + (bufoff) + ldsw + _i * 8192), 16, 0, 0); } while (0)
; #define PG8_LDA(dst, b, h) do { _Pragma("unroll") for (int m = 0; m < 4; ++m) _Pragma("unroll") for (int k = 0; k < 2; ++k) dst[m][k] = *(const PG8_LAS bf16x8*)(lds + PG8_SA(b, h) + aoff + m * 2048 + k * 1024); } while (0)
; #define PG8_LDB(dst, b, h) do { _Pragma("unroll") for (int n = 0; n < 2; ++n) _Pragma("unroll") for (int k = 0; k < 2; ++k) dst[n][k] = *(const PG8_LAS bf16x8*)(lds + PG8_SB(b, h) + boff + n * 2048 + k * 1024); } while (0)
; #define PG8_MMA(ai, bj, At, Bt) do { __builtin_amdgcn_s_setprio(1); _Pragma("unroll") for (int m = 0; m < 4; ++m) _Pragma("unroll") for (int n = 0; n < 2; ++n) _Pragma("unroll") for (int k = 0; k < 2; ++k) \
;         acc[ai][bj][m][n] = __builtin_amdgcn_mfma_f32_16x16x32_bf16(Bt[n][k], At[m][k], acc[ai][bj][m][n], 0, 0, 0); __builtin_amdgcn_s_setprio(0); } while (0)
; #define PG8_WAIT_V(n) asm volatile("s_waitcnt vmcnt(" #n ")" ::: "memory")
; #define PG8_WAIT_L(n) asm volatile("s_waitcnt lgkmcnt(" #n ")" ::: "memory")
; template <class Epi, class Sched, bool ALIGN_EPI = false, bool SP2 = false>
; __device__ __forceinline__ void gemm_phase(PG8_LAS unsigned char* lds, const Gemm g, const Sched& S, const Epi& E, const int wave0) {
;     ...
;             const bool last = (t == nt - 2);
;             const char* a1 = cA + (size_t)(t + 1) * kstep;
;             const char* a2 = last ? nA : cA + (size_t)(t + 2) * kstep; const char* b2 = last ? nB : cB + (size_t)(t + 2) * kstep;
;             const char* a3 = a2 + kstep; const char* b3 = b2 + kstep;
;             if (last && has_next) S.a_ready(nxt);
;             if constexpr (SP2) {
;             PG8_LDB(B0, 0, 0); PG8_LDB(B1, 0, 1); PG8_SCHED; PG8_LDA(At, 0, 0); PG8_STAGE(PG8_SA(1, 1), a1 + hstepA, voffA);
;             PG8_WAIT_V(8); PG8_WAIT_L(0); PG8_BAR; PG8_MMA(0, 0, At, B0); PG8_MMA(0, 1, At, B1); PG8_BAR; PG8_SCHED;
;             PG8_LDA(At, 0, 1); PG8_STAGE(PG8_SB(0, 0), b2, voffB); PG8_STAGE(PG8_SB(0, 1), b2 + hstepB, voffB); PG8_STAGE(PG8_SA(0, 0), a2, voffA);
;             PG8_WAIT_V(8); PG8_WAIT_L(0); PG8_BAR; PG8_MMA(1, 0, At, B0); PG8_MMA(1, 1, At, B1); PG8_BAR; PG8_SCHED;
.LBB0_1341:
	ds_read_b128 v[144:147], v252
	ds_read_b128 v[148:151], v252 offset:1024
	ds_read_b128 v[152:155], v252 offset:2048
	ds_read_b128 v[156:159], v252 offset:3072
	ds_read_b128 v[178:181], v253
	ds_read_b128 v[182:185], v253 offset:1024
	ds_read_b128 v[186:189], v253 offset:2048
	ds_read_b128 v[190:193], v253 offset:3072
	ds_read_b128 v[194:197], v143
	ds_read_b128 v[208:211], v143 offset:1024
	ds_read_b128 v[212:215], v143 offset:2048
	ds_read_b128 v[216:219], v143 offset:3072
	ds_read_b128 v[220:223], v143 offset:4096
	ds_read_b128 v[224:227], v143 offset:5120
	ds_read_b128 v[228:231], v143 offset:6144
	ds_read_b128 v[232:235], v143 offset:7168
	s_add_u32 s16, s0, 0xfff80080
	s_addc_u32 s17, s1, -1
	s_add_i32 s40, 0, 0x10000
	s_cmp_eq_u32 s37, 28
	s_cselect_b32 s19, s11, s17
	s_cselect_b32 s18, s33, s16
	s_cselect_b32 s17, s9, s36
	s_cselect_b32 s16, s34, s35
	s_add_i32 s42, 0, 0x14000
	s_add_i32 m0, s23, 0xc000
	s_nop 0
	global_load_lds_dwordx4 v136, s[0:1]
	s_add_i32 m0, s23, 0xe000
	s_nop 0
	global_load_lds_dwordx4 v138, s[0:1]
	s_waitcnt vmcnt(8)
	s_waitcnt lgkmcnt(0)
	s_barrier
	s_setprio 1
	s_waitcnt lgkmcnt(0)
	v_mfma_f32_16x16x32_bf16 v[126:129], v[144:147], v[194:197], v[126:129]
	v_mfma_f32_16x16x32_bf16 v[122:125], v[152:155], v[194:197], v[122:125]
	v_mfma_f32_16x16x32_bf16 v[118:121], v[144:147], v[212:215], v[118:121]
	v_mfma_f32_16x16x32_bf16 v[114:117], v[152:155], v[212:215], v[114:117]
	v_mfma_f32_16x16x32_bf16 v[102:105], v[144:147], v[220:223], v[102:105]
	v_mfma_f32_16x16x32_bf16 v[98:101], v[152:155], v[220:223], v[98:101]
	v_mfma_f32_16x16x32_bf16 v[86:89], v[144:147], v[228:231], v[86:89]
	v_mfma_f32_16x16x32_bf16 v[82:85], v[152:155], v[228:231], v[82:85]
	s_setprio 0
	s_setprio 1
	v_mfma_f32_16x16x32_bf16 v[126:129], v[148:151], v[208:211], v[126:129]
	v_mfma_f32_16x16x32_bf16 v[122:125], v[156:159], v[208:211], v[122:125]
	v_mfma_f32_16x16x32_bf16 v[118:121], v[148:151], v[216:219], v[118:121]
	v_mfma_f32_16x16x32_bf16 v[114:117], v[156:159], v[216:219], v[114:117]
	v_mfma_f32_16x16x32_bf16 v[102:105], v[148:151], v[224:227], v[102:105]
	v_mfma_f32_16x16x32_bf16 v[98:101], v[156:159], v[224:227], v[98:101]
	v_mfma_f32_16x16x32_bf16 v[86:89], v[148:151], v[232:235], v[86:89]
	v_mfma_f32_16x16x32_bf16 v[82:85], v[156:159], v[232:235], v[82:85]
	s_setprio 0
	s_setprio 1
	v_mfma_f32_16x16x32_bf16 v[110:113], v[178:181], v[194:197], v[110:113]
	v_mfma_f32_16x16x32_bf16 v[106:109], v[186:189], v[194:197], v[106:109]
	v_mfma_f32_16x16x32_bf16 v[94:97], v[178:181], v[212:215], v[94:97]
	v_mfma_f32_16x16x32_bf16 v[90:93], v[186:189], v[212:215], v[90:93]
	v_mfma_f32_16x16x32_bf16 v[78:81], v[178:181], v[220:223], v[78:81]
	v_mfma_f32_16x16x32_bf16 v[74:77], v[186:189], v[220:223], v[74:77]
	v_mfma_f32_16x16x32_bf16 v[70:73], v[178:181], v[228:231], v[70:73]
	v_mfma_f32_16x16x32_bf16 v[66:69], v[186:189], v[228:231], v[66:69]
	s_setprio 0
	s_setprio 1
	v_mfma_f32_16x16x32_bf16 v[110:113], v[182:185], v[208:211], v[110:113]
	v_mfma_f32_16x16x32_bf16 v[106:109], v[190:193], v[208:211], v[106:109]
	v_mfma_f32_16x16x32_bf16 v[94:97], v[182:185], v[216:219], v[94:97]
	v_mfma_f32_16x16x32_bf16 v[90:93], v[190:193], v[216:219], v[90:93]
	v_mfma_f32_16x16x32_bf16 v[78:81], v[182:185], v[224:227], v[78:81]
	v_mfma_f32_16x16x32_bf16 v[74:77], v[190:193], v[224:227], v[74:77]
	v_mfma_f32_16x16x32_bf16 v[70:73], v[182:185], v[232:235], v[70:73]
	v_mfma_f32_16x16x32_bf16 v[66:69], v[190:193], v[232:235], v[66:69]
	s_setprio 0
	s_barrier
	ds_read_b128 v[194:197], v143 offset:16384
	ds_read_b128 v[208:211], v143 offset:17408
	ds_read_b128 v[212:215], v143 offset:18432
	ds_read_b128 v[216:219], v143 offset:19456
	ds_read_b128 v[220:223], v143 offset:20480
	ds_read_b128 v[224:227], v143 offset:21504
	ds_read_b128 v[228:231], v143 offset:22528
	ds_read_b128 v[232:235], v143 offset:23552
	s_add_i32 s40, s40, s22
	s_mov_b32 m0, s40
	s_nop 0
	global_load_lds_dwordx4 v64, s[16:17]
	s_add_i32 m0, s40, 0x2000
	s_add_u32 s40, s16, 0x80000
	s_addc_u32 s41, s17, 0
	s_add_i32 s42, s42, s22
	global_load_lds_dwordx4 v130, s[16:17]
	s_mov_b32 m0, s42
	s_mov_b64 s[100:101], s[18:19]
	global_load_lds_dwordx4 v64, s[40:41]
	s_add_i32 m0, s42, 0x2000
	s_nop 0
	global_load_lds_dwordx4 v130, s[40:41]
	s_mov_b32 m0, s23
	s_nop 0
	global_load_lds_dwordx4 v134, s[18:19]
	s_mov_b32 m0, s24
	s_nop 0
	global_load_lds_dwordx4 v132, s[18:19]
	s_waitcnt vmcnt(8)
	s_waitcnt lgkmcnt(0)
	s_barrier
	s_setprio 1
	s_waitcnt lgkmcnt(0)
	v_mfma_f32_16x16x32_bf16 v[60:63], v[144:147], v[194:197], v[60:63]
	v_mfma_f32_16x16x32_bf16 v[56:59], v[152:155], v[194:197], v[56:59]
	v_mfma_f32_16x16x32_bf16 v[52:55], v[144:147], v[212:215], v[52:55]
	v_mfma_f32_16x16x32_bf16 v[48:51], v[152:155], v[212:215], v[48:51]
	v_mfma_f32_16x16x32_bf16 v[36:39], v[144:147], v[220:223], v[36:39]
	v_mfma_f32_16x16x32_bf16 v[32:35], v[152:155], v[220:223], v[32:35]
	v_mfma_f32_16x16x32_bf16 v[20:23], v[144:147], v[228:231], v[20:23]
	v_mfma_f32_16x16x32_bf16 v[16:19], v[152:155], v[228:231], v[16:19]
	s_setprio 0
	s_setprio 1
	v_mfma_f32_16x16x32_bf16 v[60:63], v[148:151], v[208:211], v[60:63]
	v_mfma_f32_16x16x32_bf16 v[56:59], v[156:159], v[208:211], v[56:59]
	v_mfma_f32_16x16x32_bf16 v[52:55], v[148:151], v[216:219], v[52:55]
	v_mfma_f32_16x16x32_bf16 v[48:51], v[156:159], v[216:219], v[48:51]
	v_mfma_f32_16x16x32_bf16 v[36:39], v[148:151], v[224:227], v[36:39]
	v_mfma_f32_16x16x32_bf16 v[32:35], v[156:159], v[224:227], v[32:35]
	v_mfma_f32_16x16x32_bf16 v[20:23], v[148:151], v[232:235], v[20:23]
	v_mfma_f32_16x16x32_bf16 v[16:19], v[156:159], v[232:235], v[16:19]
	s_setprio 0
	s_setprio 1
	v_mfma_f32_16x16x32_bf16 v[44:47], v[178:181], v[194:197], v[44:47]
	v_mfma_f32_16x16x32_bf16 v[40:43], v[186:189], v[194:197], v[40:43]
	v_mfma_f32_16x16x32_bf16 v[28:31], v[178:181], v[212:215], v[28:31]
	v_mfma_f32_16x16x32_bf16 v[24:27], v[186:189], v[212:215], v[24:27]
	v_mfma_f32_16x16x32_bf16 v[12:15], v[178:181], v[220:223], v[12:15]
	v_mfma_f32_16x16x32_bf16 v[8:11], v[186:189], v[220:223], v[8:11]
	v_mfma_f32_16x16x32_bf16 v[4:7], v[178:181], v[228:231], v[4:7]
	v_mfma_f32_16x16x32_bf16 v[0:3], v[186:189], v[228:231], v[0:3]
	s_setprio 0
	s_setprio 1
	v_mfma_f32_16x16x32_bf16 v[44:47], v[182:185], v[208:211], v[44:47]
	v_mfma_f32_16x16x32_bf16 v[40:43], v[190:193], v[208:211], v[40:43]
	v_mfma_f32_16x16x32_bf16 v[28:31], v[182:185], v[216:219], v[28:31]
	v_mfma_f32_16x16x32_bf16 v[24:27], v[190:193], v[216:219], v[24:27]
	v_mfma_f32_16x16x32_bf16 v[12:15], v[182:185], v[224:227], v[12:15]
	v_mfma_f32_16x16x32_bf16 v[8:11], v[190:193], v[224:227], v[8:11]
	v_mfma_f32_16x16x32_bf16 v[4:7], v[182:185], v[232:235], v[4:7]
	v_mfma_f32_16x16x32_bf16 v[0:3], v[190:193], v[232:235], v[0:3]
	s_setprio 0
	s_barrier
; #define PG8_STAGE(bufoff, gbase, voff) do { _Pragma("unroll") for (int _i = 0; _i < 2; ++_i) \
;         __builtin_amdgcn_global_load_lds((const unsigned*)((const char*)(gbase) + (voff)[_i]), (PG8_LAS unsigned*)(lds + (bufoff) + ldsw + _i * 8192), 16, 0, 0); } while (0)
; #define PG8_LDA(dst, b, h) do { _Pragma("unroll") for (int m = 0; m < 4; ++m) _Pragma("unroll") for (int k = 0; k < 2; ++k) dst[m][k] = *(const PG8_LAS bf16x8*)(lds + PG8_SA(b, h) + aoff + m * 2048 + k * 1024); } while (0)
; #define PG8_LDB(dst, b, h) do { _Pragma("unroll") for (int n = 0; n < 2; ++n) _Pragma("unroll") for (int k = 0; k < 2; ++k) dst[n][k] = *(const PG8_LAS bf16x8*)(lds + PG8_SB(b, h) + boff + n * 2048 + k * 1024); } while (0)
; #define PG8_MMA(ai, bj, At, Bt) do { __builtin_amdgcn_s_setprio(1); _Pragma("unroll") for (int m = 0; m < 4; ++m) _Pragma("unroll") for (int n = 0; n < 2; ++n) _Pragma("unroll") for (int k = 0; k < 2; ++k) \
;         acc[ai][bj][m][n] = __builtin_amdgcn_mfma_f32_16x16x32_bf16(Bt[n][k], At[m][k], acc[ai][bj][m][n], 0, 0, 0); __builtin_amdgcn_s_setprio(0); } while (0)
; #define PG8_WAIT_V(n) asm volatile("s_waitcnt vmcnt(" #n ")" ::: "memory")
; #define PG8_WAIT_L(n) asm volatile("s_waitcnt lgkmcnt(" #n ")" ::: "memory")
; #define PG8_BAR __builtin_amdgcn_s_barrier()
; #define PG8_SCHED __builtin_amdgcn_sched_barrier(0)
; template <class Epi, class Sched, bool ALIGN_EPI = false, bool SP2 = false>
; __device__ __forceinline__ void gemm_phase(PG8_LAS unsigned char* lds, const Gemm g, const Sched& S, const Epi& E, const int wave0) {
;     ...
;             PG8_LDB(B0, 1, 0); PG8_LDB(B1, 1, 1); PG8_SCHED; PG8_LDA(At, 1, 0); PG8_STAGE(PG8_SA(0, 1), a2 + hstepA, voffA);
;             PG8_WAIT_V(8); PG8_WAIT_L(0); PG8_BAR; PG8_MMA(0, 0, At, B0); PG8_MMA(0, 1, At, B1); PG8_BAR; PG8_SCHED;
;             PG8_LDA(At, 1, 1); PG8_STAGE(PG8_SB(1, 0), b3, voffB); PG8_STAGE(PG8_SB(1, 1), b3 + hstepB, voffB); PG8_STAGE(PG8_SA(1, 0), a3, voffA);
;             PG8_WAIT_V(8); PG8_WAIT_L(0); PG8_BAR; PG8_MMA(1, 0, At, B0); PG8_MMA(1, 1, At, B1); PG8_BAR; PG8_SCHED;
	ds_read_b128 v[144:147], v254
	ds_read_b128 v[148:151], v254 offset:1024
	ds_read_b128 v[152:155], v254 offset:2048
	ds_read_b128 v[156:159], v254 offset:3072
	ds_read_b128 v[178:181], v255
	ds_read_b128 v[182:185], v255 offset:1024
	ds_read_b128 v[186:189], v255 offset:2048
	ds_read_b128 v[190:193], v255 offset:3072
	ds_read_b128 v[194:197], v143 offset:32768
	ds_read_b128 v[208:211], v143 offset:33792
	ds_read_b128 v[212:215], v143 offset:34816
	ds_read_b128 v[216:219], v143 offset:35840
	ds_read_b128 v[220:223], v143 offset:36864
	ds_read_b128 v[224:227], v143 offset:37888
	ds_read_b128 v[228:231], v143 offset:38912
	ds_read_b128 v[232:235], v143 offset:39936
	s_add_i32 s40, 0, 0x18000
	s_add_i32 s41, 0, 0x1c000
	s_add_u32 s18, s18, 0x80000
	s_addc_u32 s19, s19, 0
	s_mov_b32 m0, s25
	s_nop 0
	global_load_lds_dwordx4 v134, s[18:19]
	s_mov_b32 m0, s26
	s_nop 0
	global_load_lds_dwordx4 v132, s[18:19]
	s_waitcnt vmcnt(8)
	s_waitcnt lgkmcnt(0)
	s_barrier
	s_setprio 1
	s_waitcnt lgkmcnt(0)
	v_mfma_f32_16x16x32_bf16 v[126:129], v[144:147], v[194:197], v[126:129]
	v_mfma_f32_16x16x32_bf16 v[122:125], v[152:155], v[194:197], v[122:125]
	v_mfma_f32_16x16x32_bf16 v[118:121], v[144:147], v[212:215], v[118:121]
	v_mfma_f32_16x16x32_bf16 v[114:117], v[152:155], v[212:215], v[114:117]
	v_mfma_f32_16x16x32_bf16 v[102:105], v[144:147], v[220:223], v[102:105]
	v_mfma_f32_16x16x32_bf16 v[98:101], v[152:155], v[220:223], v[98:101]
	v_mfma_f32_16x16x32_bf16 v[86:89], v[144:147], v[228:231], v[86:89]
	v_mfma_f32_16x16x32_bf16 v[82:85], v[152:155], v[228:231], v[82:85]
	s_setprio 0
	s_setprio 1
	v_mfma_f32_16x16x32_bf16 v[126:129], v[148:151], v[208:211], v[126:129]
	v_mfma_f32_16x16x32_bf16 v[122:125], v[156:159], v[208:211], v[122:125]
	v_mfma_f32_16x16x32_bf16 v[118:121], v[148:151], v[216:219], v[118:121]
	v_mfma_f32_16x16x32_bf16 v[114:117], v[156:159], v[216:219], v[114:117]
	v_mfma_f32_16x16x32_bf16 v[102:105], v[148:151], v[224:227], v[102:105]
	v_mfma_f32_16x16x32_bf16 v[98:101], v[156:159], v[224:227], v[98:101]
	v_mfma_f32_16x16x32_bf16 v[86:89], v[148:151], v[232:235], v[86:89]
	v_mfma_f32_16x16x32_bf16 v[82:85], v[156:159], v[232:235], v[82:85]
	s_setprio 0
	s_setprio 1
	v_mfma_f32_16x16x32_bf16 v[110:113], v[178:181], v[194:197], v[110:113]
	v_mfma_f32_16x16x32_bf16 v[106:109], v[186:189], v[194:197], v[106:109]
	v_mfma_f32_16x16x32_bf16 v[94:97], v[178:181], v[212:215], v[94:97]
	v_mfma_f32_16x16x32_bf16 v[90:93], v[186:189], v[212:215], v[90:93]
	v_mfma_f32_16x16x32_bf16 v[78:81], v[178:181], v[220:223], v[78:81]
	v_mfma_f32_16x16x32_bf16 v[74:77], v[186:189], v[220:223], v[74:77]
	v_mfma_f32_16x16x32_bf16 v[70:73], v[178:181], v[228:231], v[70:73]
	v_mfma_f32_16x16x32_bf16 v[66:69], v[186:189], v[228:231], v[66:69]
	s_setprio 0
	s_setprio 1
	v_mfma_f32_16x16x32_bf16 v[110:113], v[182:185], v[208:211], v[110:113]
	v_mfma_f32_16x16x32_bf16 v[106:109], v[190:193], v[208:211], v[106:109]
	v_mfma_f32_16x16x32_bf16 v[94:97], v[182:185], v[216:219], v[94:97]
	v_mfma_f32_16x16x32_bf16 v[90:93], v[190:193], v[216:219], v[90:93]
	v_mfma_f32_16x16x32_bf16 v[78:81], v[182:185], v[224:227], v[78:81]
	v_mfma_f32_16x16x32_bf16 v[74:77], v[190:193], v[224:227], v[74:77]
	v_mfma_f32_16x16x32_bf16 v[70:73], v[182:185], v[232:235], v[70:73]
	v_mfma_f32_16x16x32_bf16 v[66:69], v[190:193], v[232:235], v[66:69]
	s_setprio 0
	s_barrier
	ds_read_b128 v[194:197], v143 offset:49152
	ds_read_b128 v[208:211], v143 offset:50176
	ds_read_b128 v[212:215], v143 offset:51200
	ds_read_b128 v[216:219], v143 offset:52224
	ds_read_b128 v[220:223], v143 offset:53248
	ds_read_b128 v[224:227], v143 offset:54272
	ds_read_b128 v[228:231], v143 offset:55296
	ds_read_b128 v[232:235], v143 offset:56320
	s_add_i32 s18, s40, s22
	s_add_u32 s44, s16, 0x80
	s_addc_u32 s45, s17, 0
	s_mov_b32 m0, s18
	s_nop 0
	global_load_lds_dwordx4 v64, s[44:45]
	s_add_i32 m0, s18, 0x2000
	s_add_u32 s16, s16, 0x80080
	s_addc_u32 s17, s17, 0
	s_add_i32 s18, s41, s22
	global_load_lds_dwordx4 v130, s[44:45]
	s_mov_b32 m0, s18
	s_nop 0
	global_load_lds_dwordx4 v64, s[16:17]
	s_add_i32 m0, s18, 0x2000
	s_nop 0
	global_load_lds_dwordx4 v130, s[16:17]
	s_add_u32 s100, s100, 0x80
	s_addc_u32 s101, s101, 0
	s_mov_b32 m0, s27
	s_nop 0
	global_load_lds_dwordx4 v134, s[100:101]
	s_mov_b32 m0, s28
	s_nop 0
	global_load_lds_dwordx4 v132, s[100:101]
	s_waitcnt vmcnt(8)
	s_waitcnt lgkmcnt(0)
	s_barrier
	s_setprio 1
	s_waitcnt lgkmcnt(0)
	v_mfma_f32_16x16x32_bf16 v[60:63], v[144:147], v[194:197], v[60:63]
	v_mfma_f32_16x16x32_bf16 v[56:59], v[152:155], v[194:197], v[56:59]
	v_mfma_f32_16x16x32_bf16 v[52:55], v[144:147], v[212:215], v[52:55]
	v_mfma_f32_16x16x32_bf16 v[48:51], v[152:155], v[212:215], v[48:51]
	v_mfma_f32_16x16x32_bf16 v[36:39], v[144:147], v[220:223], v[36:39]
	v_mfma_f32_16x16x32_bf16 v[32:35], v[152:155], v[220:223], v[32:35]
	v_mfma_f32_16x16x32_bf16 v[20:23], v[144:147], v[228:231], v[20:23]
	v_mfma_f32_16x16x32_bf16 v[16:19], v[152:155], v[228:231], v[16:19]
	s_setprio 0
	s_setprio 1
	v_mfma_f32_16x16x32_bf16 v[60:63], v[148:151], v[208:211], v[60:63]
	v_mfma_f32_16x16x32_bf16 v[56:59], v[156:159], v[208:211], v[56:59]
	v_mfma_f32_16x16x32_bf16 v[52:55], v[148:151], v[216:219], v[52:55]
	v_mfma_f32_16x16x32_bf16 v[48:51], v[156:159], v[216:219], v[48:51]
	v_mfma_f32_16x16x32_bf16 v[36:39], v[148:151], v[224:227], v[36:39]
	v_mfma_f32_16x16x32_bf16 v[32:35], v[156:159], v[224:227], v[32:35]
	v_mfma_f32_16x16x32_bf16 v[20:23], v[148:151], v[232:235], v[20:23]
	v_mfma_f32_16x16x32_bf16 v[16:19], v[156:159], v[232:235], v[16:19]
	s_setprio 0
	s_setprio 1
	v_mfma_f32_16x16x32_bf16 v[44:47], v[178:181], v[194:197], v[44:47]
	v_mfma_f32_16x16x32_bf16 v[40:43], v[186:189], v[194:197], v[40:43]
	v_mfma_f32_16x16x32_bf16 v[28:31], v[178:181], v[212:215], v[28:31]
	v_mfma_f32_16x16x32_bf16 v[24:27], v[186:189], v[212:215], v[24:27]
	v_mfma_f32_16x16x32_bf16 v[12:15], v[178:181], v[220:223], v[12:15]
	v_mfma_f32_16x16x32_bf16 v[8:11], v[186:189], v[220:223], v[8:11]
	v_mfma_f32_16x16x32_bf16 v[4:7], v[178:181], v[228:231], v[4:7]
	v_mfma_f32_16x16x32_bf16 v[0:3], v[186:189], v[228:231], v[0:3]
	s_setprio 0
	s_setprio 1
	v_mfma_f32_16x16x32_bf16 v[44:47], v[182:185], v[208:211], v[44:47]
	v_mfma_f32_16x16x32_bf16 v[40:43], v[190:193], v[208:211], v[40:43]
	v_mfma_f32_16x16x32_bf16 v[28:31], v[182:185], v[216:219], v[28:31]
	v_mfma_f32_16x16x32_bf16 v[24:27], v[190:193], v[216:219], v[24:27]
	v_mfma_f32_16x16x32_bf16 v[12:15], v[182:185], v[224:227], v[12:15]
	v_mfma_f32_16x16x32_bf16 v[8:11], v[190:193], v[224:227], v[8:11]
	v_mfma_f32_16x16x32_bf16 v[4:7], v[182:185], v[232:235], v[4:7]
	v_mfma_f32_16x16x32_bf16 v[0:3], v[190:193], v[232:235], v[0:3]
	s_setprio 0
	s_barrier
	s_add_i32 s37, s37, 2
	s_add_u32 s0, s0, 0x100
	s_addc_u32 s1, s1, 0
	s_add_u32 s35, s35, 0x100
	s_addc_u32 s36, s36, 0
	s_cmp_gt_u32 s37, 29
	s_cbranch_scc0 .LBB0_1341
	s_mov_b64 s[44:45], 0x80
	s_and_b64 vcc, exec, s[6:7]
	s_mov_b64 s[34:35], 0x45000
	s_cbranch_vccz .LBB0_1344
	s_barrier

; #define PG8_STAGE(bufoff, gbase, voff) do { _Pragma("unroll") for (int _i = 0; _i < 2; ++_i) \
;         __builtin_amdgcn_global_load_lds((const unsigned*)((const char*)(gbase) + (voff)[_i]), (PG8_LAS unsigned*)(lds + (bufoff) + ldsw + _i * 8192), 16, 0, 0); } while (0)
; #define PG8_LDA(dst, b, h) do { _Pragma("unroll") for (int m = 0; m < 4; ++m) _Pragma("unroll") for (int k = 0; k < 2; ++k) dst[m][k] = *(const PG8_LAS bf16x8*)(lds + PG8_SA(b, h) + aoff + m * 2048 + k * 1024); } while (0)
; #define PG8_LDB(dst, b, h) do { _Pragma("unroll") for (int n = 0; n < 2; ++n) _Pragma("unroll") for (int k = 0; k < 2; ++k) dst[n][k] = *(const PG8_LAS bf16x8*)(lds + PG8_SB(b, h) + boff + n * 2048 + k * 1024); } while (0)
; #define PG8_MMA(ai, bj, At, Bt) do { __builtin_amdgcn_s_setprio(1); _Pragma("unroll") for (int m = 0; m < 4; ++m) _Pragma("unroll") for (int n = 0; n < 2; ++n) _Pragma("unroll") for (int k = 0; k < 2; ++k) \
;         acc[ai][bj][m][n] = __builtin_amdgcn_mfma_f32_16x16x32_bf16(Bt[n][k], At[m][k], acc[ai][bj][m][n], 0, 0, 0); __builtin_amdgcn_s_setprio(0); } while (0)
; #define PG8_WAIT_V(n) asm volatile("s_waitcnt vmcnt(" #n ")" ::: "memory")
; #define PG8_WAIT_L(n) asm volatile("s_waitcnt lgkmcnt(" #n ")" ::: "memory")
; template <class Epi, class Sched, bool ALIGN_EPI = false, bool SP2 = false>
; __device__ __forceinline__ void gemm_phase(PG8_LAS unsigned char* lds, const Gemm g, const Sched& S, const Epi& E, const int wave0) {
;     ...
;             const bool last = (t == nt - 2);
;             const char* a1 = cA + (size_t)(t + 1) * kstep;
;             const char* a2 = last ? nA : cA + (size_t)(t + 2) * kstep; const char* b2 = last ? nB : cB + (size_t)(t + 2) * kstep;
;             const char* a3 = a2 + kstep; const char* b3 = b2 + kstep;
;             if (last && has_next) S.a_ready(nxt);
;             if constexpr (SP2) {
;             PG8_LDB(B0, 0, 0); PG8_LDB(B1, 0, 1); PG8_SCHED; PG8_LDA(At, 0, 0); PG8_STAGE(PG8_SA(1, 1), a1 + hstepA, voffA);
;             PG8_WAIT_V(8); PG8_WAIT_L(0); PG8_BAR; PG8_MMA(0, 0, At, B0); PG8_MMA(0, 1, At, B1); PG8_BAR; PG8_SCHED;
;             PG8_LDA(At, 0, 1); PG8_STAGE(PG8_SB(0, 0), b2, voffB); PG8_STAGE(PG8_SB(0, 1), b2 + hstepB, voffB); PG8_STAGE(PG8_SA(0, 0), a2, voffA);
;             PG8_WAIT_V(8); PG8_WAIT_L(0); PG8_BAR; PG8_MMA(1, 0, At, B0); PG8_MMA(1, 1, At, B1); PG8_BAR; PG8_SCHED;
.LBB0_1360:
	ds_read_b128 v[144:147], v252
	ds_read_b128 v[148:151], v252 offset:1024
	ds_read_b128 v[152:155], v252 offset:2048
	ds_read_b128 v[156:159], v252 offset:3072
	ds_read_b128 v[178:181], v253
	ds_read_b128 v[182:185], v253 offset:1024
	ds_read_b128 v[186:189], v253 offset:2048
	ds_read_b128 v[190:193], v253 offset:3072
	ds_read_b128 v[194:197], v143
	ds_read_b128 v[208:211], v143 offset:1024
	ds_read_b128 v[212:215], v143 offset:2048
	ds_read_b128 v[216:219], v143 offset:3072
	ds_read_b128 v[220:223], v143 offset:4096
	ds_read_b128 v[224:227], v143 offset:5120
	ds_read_b128 v[228:231], v143 offset:6144
	ds_read_b128 v[232:235], v143 offset:7168
	s_add_u32 s16, s0, 0xfff80080
	s_addc_u32 s17, s1, -1
	s_add_i32 s42, 0, 0x10000
	s_cmp_eq_u32 s41, 12
	s_cselect_b32 s19, s5, s17
	s_cselect_b32 s18, s4, s16
	s_cselect_b32 s17, s11, s27
	s_cselect_b32 s16, s13, s15
	s_add_i32 s44, 0, 0x14000
	s_add_i32 m0, s23, 0xc000
	s_nop 0
	global_load_lds_dwordx4 v136, s[0:1]
	s_add_i32 m0, s23, 0xe000
	s_nop 0
	global_load_lds_dwordx4 v138, s[0:1]
	s_waitcnt vmcnt(8)
	s_waitcnt lgkmcnt(0)
	s_barrier
	s_setprio 1
	s_waitcnt lgkmcnt(0)
	v_mfma_f32_16x16x32_bf16 v[126:129], v[144:147], v[194:197], v[126:129]
	v_mfma_f32_16x16x32_bf16 v[122:125], v[152:155], v[194:197], v[122:125]
	v_mfma_f32_16x16x32_bf16 v[118:121], v[144:147], v[212:215], v[118:121]
	v_mfma_f32_16x16x32_bf16 v[114:117], v[152:155], v[212:215], v[114:117]
	v_mfma_f32_16x16x32_bf16 v[102:105], v[144:147], v[220:223], v[102:105]
	v_mfma_f32_16x16x32_bf16 v[98:101], v[152:155], v[220:223], v[98:101]
	v_mfma_f32_16x16x32_bf16 v[86:89], v[144:147], v[228:231], v[86:89]
	v_mfma_f32_16x16x32_bf16 v[82:85], v[152:155], v[228:231], v[82:85]
	s_setprio 0
	s_setprio 1
	v_mfma_f32_16x16x32_bf16 v[126:129], v[148:151], v[208:211], v[126:129]
	v_mfma_f32_16x16x32_bf16 v[122:125], v[156:159], v[208:211], v[122:125]
	v_mfma_f32_16x16x32_bf16 v[118:121], v[148:151], v[216:219], v[118:121]
	v_mfma_f32_16x16x32_bf16 v[114:117], v[156:159], v[216:219], v[114:117]
	v_mfma_f32_16x16x32_bf16 v[102:105], v[148:151], v[224:227], v[102:105]
	v_mfma_f32_16x16x32_bf16 v[98:101], v[156:159], v[224:227], v[98:101]
	v_mfma_f32_16x16x32_bf16 v[86:89], v[148:151], v[232:235], v[86:89]
	v_mfma_f32_16x16x32_bf16 v[82:85], v[156:159], v[232:235], v[82:85]
	s_setprio 0
	s_setprio 1
	v_mfma_f32_16x16x32_bf16 v[110:113], v[178:181], v[194:197], v[110:113]
	v_mfma_f32_16x16x32_bf16 v[106:109], v[186:189], v[194:197], v[106:109]
	v_mfma_f32_16x16x32_bf16 v[94:97], v[178:181], v[212:215], v[94:97]
	v_mfma_f32_16x16x32_bf16 v[90:93], v[186:189], v[212:215], v[90:93]
	v_mfma_f32_16x16x32_bf16 v[78:81], v[178:181], v[220:223], v[78:81]
	v_mfma_f32_16x16x32_bf16 v[74:77], v[186:189], v[220:223], v[74:77]
	v_mfma_f32_16x16x32_bf16 v[70:73], v[178:181], v[228:231], v[70:73]
	v_mfma_f32_16x16x32_bf16 v[66:69], v[186:189], v[228:231], v[66:69]
	s_setprio 0
	s_setprio 1
	v_mfma_f32_16x16x32_bf16 v[110:113], v[182:185], v[208:211], v[110:113]
	v_mfma_f32_16x16x32_bf16 v[106:109], v[190:193], v[208:211], v[106:109]
	v_mfma_f32_16x16x32_bf16 v[94:97], v[182:185], v[216:219], v[94:97]
	v_mfma_f32_16x16x32_bf16 v[90:93], v[190:193], v[216:219], v[90:93]
	v_mfma_f32_16x16x32_bf16 v[78:81], v[182:185], v[224:227], v[78:81]
	v_mfma_f32_16x16x32_bf16 v[74:77], v[190:193], v[224:227], v[74:77]
	v_mfma_f32_16x16x32_bf16 v[70:73], v[182:185], v[232:235], v[70:73]
	v_mfma_f32_16x16x32_bf16 v[66:69], v[190:193], v[232:235], v[66:69]
	s_setprio 0
	s_barrier
	ds_read_b128 v[194:197], v143 offset:16384
	ds_read_b128 v[208:211], v143 offset:17408
	ds_read_b128 v[212:215], v143 offset:18432
	ds_read_b128 v[216:219], v143 offset:19456
	ds_read_b128 v[220:223], v143 offset:20480
	ds_read_b128 v[224:227], v143 offset:21504
	ds_read_b128 v[228:231], v143 offset:22528
	ds_read_b128 v[232:235], v143 offset:23552
	s_add_i32 s42, s42, s22
	s_mov_b32 m0, s42
	s_nop 0
	global_load_lds_dwordx4 v64, s[16:17]
	s_add_i32 m0, s42, 0x2000
	s_add_u32 s42, s16, 0x80000
	s_addc_u32 s43, s17, 0
	s_add_i32 s44, s44, s22
	global_load_lds_dwordx4 v130, s[16:17]
	s_mov_b32 m0, s44
	s_mov_b64 s[100:101], s[18:19]
	global_load_lds_dwordx4 v64, s[42:43]
	s_add_i32 m0, s44, 0x2000
	s_nop 0
	global_load_lds_dwordx4 v130, s[42:43]
	s_mov_b32 m0, s23
	s_nop 0
	global_load_lds_dwordx4 v134, s[18:19]
	s_mov_b32 m0, s24
	s_nop 0
	global_load_lds_dwordx4 v132, s[18:19]
	s_waitcnt vmcnt(8)
	s_waitcnt lgkmcnt(0)
	s_barrier
	s_setprio 1
	s_waitcnt lgkmcnt(0)
	v_mfma_f32_16x16x32_bf16 v[60:63], v[144:147], v[194:197], v[60:63]
	v_mfma_f32_16x16x32_bf16 v[56:59], v[152:155], v[194:197], v[56:59]
	v_mfma_f32_16x16x32_bf16 v[52:55], v[144:147], v[212:215], v[52:55]
	v_mfma_f32_16x16x32_bf16 v[48:51], v[152:155], v[212:215], v[48:51]
	v_mfma_f32_16x16x32_bf16 v[36:39], v[144:147], v[220:223], v[36:39]
	v_mfma_f32_16x16x32_bf16 v[32:35], v[152:155], v[220:223], v[32:35]
	v_mfma_f32_16x16x32_bf16 v[20:23], v[144:147], v[228:231], v[20:23]
	v_mfma_f32_16x16x32_bf16 v[16:19], v[152:155], v[228:231], v[16:19]
	s_setprio 0
	s_setprio 1
	v_mfma_f32_16x16x32_bf16 v[60:63], v[148:151], v[208:211], v[60:63]
	v_mfma_f32_16x16x32_bf16 v[56:59], v[156:159], v[208:211], v[56:59]
	v_mfma_f32_16x16x32_bf16 v[52:55], v[148:151], v[216:219], v[52:55]
	v_mfma_f32_16x16x32_bf16 v[48:51], v[156:159], v[216:219], v[48:51]
	v_mfma_f32_16x16x32_bf16 v[36:39], v[148:151], v[224:227], v[36:39]
	v_mfma_f32_16x16x32_bf16 v[32:35], v[156:159], v[224:227], v[32:35]
	v_mfma_f32_16x16x32_bf16 v[20:23], v[148:151], v[232:235], v[20:23]
	v_mfma_f32_16x16x32_bf16 v[16:19], v[156:159], v[232:235], v[16:19]
	s_setprio 0
	s_setprio 1
	v_mfma_f32_16x16x32_bf16 v[44:47], v[178:181], v[194:197], v[44:47]
	v_mfma_f32_16x16x32_bf16 v[40:43], v[186:189], v[194:197], v[40:43]
	v_mfma_f32_16x16x32_bf16 v[28:31], v[178:181], v[212:215], v[28:31]
	v_mfma_f32_16x16x32_bf16 v[24:27], v[186:189], v[212:215], v[24:27]
	v_mfma_f32_16x16x32_bf16 v[12:15], v[178:181], v[220:223], v[12:15]
	v_mfma_f32_16x16x32_bf16 v[8:11], v[186:189], v[220:223], v[8:11]
	v_mfma_f32_16x16x32_bf16 v[4:7], v[178:181], v[228:231], v[4:7]
	v_mfma_f32_16x16x32_bf16 v[0:3], v[186:189], v[228:231], v[0:3]
	s_setprio 0
	s_setprio 1
	v_mfma_f32_16x16x32_bf16 v[44:47], v[182:185], v[208:211], v[44:47]
	v_mfma_f32_16x16x32_bf16 v[40:43], v[190:193], v[208:211], v[40:43]
	v_mfma_f32_16x16x32_bf16 v[28:31], v[182:185], v[216:219], v[28:31]
	v_mfma_f32_16x16x32_bf16 v[24:27], v[190:193], v[216:219], v[24:27]
	v_mfma_f32_16x16x32_bf16 v[12:15], v[182:185], v[224:227], v[12:15]
	v_mfma_f32_16x16x32_bf16 v[8:11], v[190:193], v[224:227], v[8:11]
	v_mfma_f32_16x16x32_bf16 v[4:7], v[182:185], v[232:235], v[4:7]
	v_mfma_f32_16x16x32_bf16 v[0:3], v[190:193], v[232:235], v[0:3]
	s_setprio 0
	s_barrier
; #define PG8_STAGE(bufoff, gbase, voff) do { _Pragma("unroll") for (int _i = 0; _i < 2; ++_i) \
;         __builtin_amdgcn_global_load_lds((const unsigned*)((const char*)(gbase) + (voff)[_i]), (PG8_LAS unsigned*)(lds + (bufoff) + ldsw + _i * 8192), 16, 0, 0); } while (0)
; #define PG8_LDA(dst, b, h) do { _Pragma("unroll") for (int m = 0; m < 4; ++m) _Pragma("unroll") for (int k = 0; k < 2; ++k) dst[m][k] = *(const PG8_LAS bf16x8*)(lds + PG8_SA(b, h) + aoff + m * 2048 + k * 1024); } while (0)
; #define PG8_LDB(dst, b, h) do { _Pragma("unroll") for (int n = 0; n < 2; ++n) _Pragma("unroll") for (int k = 0; k < 2; ++k) dst[n][k] = *(const PG8_LAS bf16x8*)(lds + PG8_SB(b, h) + boff + n * 2048 + k * 1024); } while (0)
; #define PG8_MMA(ai, bj, At, Bt) do { __builtin_amdgcn_s_setprio(1); _Pragma("unroll") for (int m = 0; m < 4; ++m) _Pragma("unroll") for (int n = 0; n < 2; ++n) _Pragma("unroll") for (int k = 0; k < 2; ++k) \
;         acc[ai][bj][m][n] = __builtin_amdgcn_mfma_f32_16x16x32_bf16(Bt[n][k], At[m][k], acc[ai][bj][m][n], 0, 0, 0); __builtin_amdgcn_s_setprio(0); } while (0)
; #define PG8_WAIT_V(n) asm volatile("s_waitcnt vmcnt(" #n ")" ::: "memory")
; #define PG8_WAIT_L(n) asm volatile("s_waitcnt lgkmcnt(" #n ")" ::: "memory")
; #define PG8_BAR __builtin_amdgcn_s_barrier()
; #define PG8_SCHED __builtin_amdgcn_sched_barrier(0)
; template <class Epi, class Sched, bool ALIGN_EPI = false, bool SP2 = false>
; __device__ __forceinline__ void gemm_phase(PG8_LAS unsigned char* lds, const Gemm g, const Sched& S, const Epi& E, const int wave0) {
;     ...
;         for (int t = 0; t < nt; t += 2) {
;             const bool last = (t == nt - 2);
;             const char* a1 = cA + (size_t)(t + 1) * kstep;
;             const char* a2 = last ? nA : cA + (size_t)(t + 2) * kstep; const char* b2 = last ? nB : cB + (size_t)(t + 2) * kstep;
;     ...
;             PG8_LDB(B0, 1, 0); PG8_LDB(B1, 1, 1); PG8_SCHED; PG8_LDA(At, 1, 0); PG8_STAGE(PG8_SA(0, 1), a2 + hstepA, voffA);
;             PG8_WAIT_V(8); PG8_WAIT_L(0); PG8_BAR; PG8_MMA(0, 0, At, B0); PG8_MMA(0, 1, At, B1); PG8_BAR; PG8_SCHED;
;             PG8_LDA(At, 1, 1); PG8_STAGE(PG8_SB(1, 0), b3, voffB); PG8_STAGE(PG8_SB(1, 1), b3 + hstepB, voffB); PG8_STAGE(PG8_SA(1, 0), a3, voffA);
;             PG8_WAIT_V(8); PG8_WAIT_L(0); PG8_BAR; PG8_MMA(1, 0, At, B0); PG8_MMA(1, 1, At, B1); PG8_BAR; PG8_SCHED;
	ds_read_b128 v[144:147], v254
	ds_read_b128 v[148:151], v254 offset:1024
	ds_read_b128 v[152:155], v254 offset:2048
	ds_read_b128 v[156:159], v254 offset:3072
	ds_read_b128 v[178:181], v255
	ds_read_b128 v[182:185], v255 offset:1024
	ds_read_b128 v[186:189], v255 offset:2048
	ds_read_b128 v[190:193], v255 offset:3072
	ds_read_b128 v[194:197], v143 offset:32768
	ds_read_b128 v[208:211], v143 offset:33792
	ds_read_b128 v[212:215], v143 offset:34816
	ds_read_b128 v[216:219], v143 offset:35840
	ds_read_b128 v[220:223], v143 offset:36864
	ds_read_b128 v[224:227], v143 offset:37888
	ds_read_b128 v[228:231], v143 offset:38912
	ds_read_b128 v[232:235], v143 offset:39936
	s_add_i32 s42, 0, 0x18000
	s_add_i32 s43, 0, 0x1c000
	s_add_u32 s18, s18, 0x80000
	s_addc_u32 s19, s19, 0
	s_mov_b32 m0, s25
	s_nop 0
	global_load_lds_dwordx4 v134, s[18:19]
	s_mov_b32 m0, s33
	s_nop 0
	global_load_lds_dwordx4 v132, s[18:19]
	s_waitcnt vmcnt(8)
	s_waitcnt lgkmcnt(0)
	s_barrier
	s_setprio 1
	s_waitcnt lgkmcnt(0)
	v_mfma_f32_16x16x32_bf16 v[126:129], v[144:147], v[194:197], v[126:129]
	v_mfma_f32_16x16x32_bf16 v[122:125], v[152:155], v[194:197], v[122:125]
	v_mfma_f32_16x16x32_bf16 v[118:121], v[144:147], v[212:215], v[118:121]
	v_mfma_f32_16x16x32_bf16 v[114:117], v[152:155], v[212:215], v[114:117]
	v_mfma_f32_16x16x32_bf16 v[102:105], v[144:147], v[220:223], v[102:105]
	v_mfma_f32_16x16x32_bf16 v[98:101], v[152:155], v[220:223], v[98:101]
	v_mfma_f32_16x16x32_bf16 v[86:89], v[144:147], v[228:231], v[86:89]
	v_mfma_f32_16x16x32_bf16 v[82:85], v[152:155], v[228:231], v[82:85]
	s_setprio 0
	s_setprio 1
	v_mfma_f32_16x16x32_bf16 v[126:129], v[148:151], v[208:211], v[126:129]
	v_mfma_f32_16x16x32_bf16 v[122:125], v[156:159], v[208:211], v[122:125]
	v_mfma_f32_16x16x32_bf16 v[118:121], v[148:151], v[216:219], v[118:121]
	v_mfma_f32_16x16x32_bf16 v[114:117], v[156:159], v[216:219], v[114:117]
	v_mfma_f32_16x16x32_bf16 v[102:105], v[148:151], v[224:227], v[102:105]
	v_mfma_f32_16x16x32_bf16 v[98:101], v[156:159], v[224:227], v[98:101]
	v_mfma_f32_16x16x32_bf16 v[86:89], v[148:151], v[232:235], v[86:89]
	v_mfma_f32_16x16x32_bf16 v[82:85], v[156:159], v[232:235], v[82:85]
	s_setprio 0
	s_setprio 1
	v_mfma_f32_16x16x32_bf16 v[110:113], v[178:181], v[194:197], v[110:113]
	v_mfma_f32_16x16x32_bf16 v[106:109], v[186:189], v[194:197], v[106:109]
	v_mfma_f32_16x16x32_bf16 v[94:97], v[178:181], v[212:215], v[94:97]
	v_mfma_f32_16x16x32_bf16 v[90:93], v[186:189], v[212:215], v[90:93]
	v_mfma_f32_16x16x32_bf16 v[78:81], v[178:181], v[220:223], v[78:81]
	v_mfma_f32_16x16x32_bf16 v[74:77], v[186:189], v[220:223], v[74:77]
	v_mfma_f32_16x16x32_bf16 v[70:73], v[178:181], v[228:231], v[70:73]
	v_mfma_f32_16x16x32_bf16 v[66:69], v[186:189], v[228:231], v[66:69]
	s_setprio 0
	s_setprio 1
	v_mfma_f32_16x16x32_bf16 v[110:113], v[182:185], v[208:211], v[110:113]
	v_mfma_f32_16x16x32_bf16 v[106:109], v[190:193], v[208:211], v[106:109]
	v_mfma_f32_16x16x32_bf16 v[94:97], v[182:185], v[216:219], v[94:97]
	v_mfma_f32_16x16x32_bf16 v[90:93], v[190:193], v[216:219], v[90:93]
	v_mfma_f32_16x16x32_bf16 v[78:81], v[182:185], v[224:227], v[78:81]
	v_mfma_f32_16x16x32_bf16 v[74:77], v[190:193], v[224:227], v[74:77]
	v_mfma_f32_16x16x32_bf16 v[70:73], v[182:185], v[232:235], v[70:73]
	v_mfma_f32_16x16x32_bf16 v[66:69], v[190:193], v[232:235], v[66:69]
	s_setprio 0
	s_barrier
	ds_read_b128 v[194:197], v143 offset:49152
	ds_read_b128 v[208:211], v143 offset:50176
	ds_read_b128 v[212:215], v143 offset:51200
	ds_read_b128 v[216:219], v143 offset:52224
	ds_read_b128 v[220:223], v143 offset:53248
	ds_read_b128 v[224:227], v143 offset:54272
	ds_read_b128 v[228:231], v143 offset:55296
	ds_read_b128 v[232:235], v143 offset:56320
	s_add_i32 s18, s42, s22
	s_add_u32 s46, s16, 0x80
	s_addc_u32 s47, s17, 0
	s_mov_b32 m0, s18
	s_nop 0
	global_load_lds_dwordx4 v64, s[46:47]
	s_add_i32 m0, s18, 0x2000
	s_add_u32 s16, s16, 0x80080
	s_addc_u32 s17, s17, 0
	s_add_i32 s18, s43, s22
	global_load_lds_dwordx4 v130, s[46:47]
	s_mov_b32 m0, s18
	s_nop 0
	global_load_lds_dwordx4 v64, s[16:17]
	s_add_i32 m0, s18, 0x2000
	s_nop 0
	global_load_lds_dwordx4 v130, s[16:17]
	s_add_u32 s100, s100, 0x80
	s_addc_u32 s101, s101, 0
	s_mov_b32 m0, s34
	s_nop 0
	global_load_lds_dwordx4 v134, s[100:101]
	s_mov_b32 m0, s35
	s_nop 0
	global_load_lds_dwordx4 v132, s[100:101]
	s_waitcnt vmcnt(8)
	s_waitcnt lgkmcnt(0)
	s_barrier
	s_setprio 1
	s_waitcnt lgkmcnt(0)
	v_mfma_f32_16x16x32_bf16 v[60:63], v[144:147], v[194:197], v[60:63]
	v_mfma_f32_16x16x32_bf16 v[56:59], v[152:155], v[194:197], v[56:59]
	v_mfma_f32_16x16x32_bf16 v[52:55], v[144:147], v[212:215], v[52:55]
	v_mfma_f32_16x16x32_bf16 v[48:51], v[152:155], v[212:215], v[48:51]
	v_mfma_f32_16x16x32_bf16 v[36:39], v[144:147], v[220:223], v[36:39]
	v_mfma_f32_16x16x32_bf16 v[32:35], v[152:155], v[220:223], v[32:35]
	v_mfma_f32_16x16x32_bf16 v[20:23], v[144:147], v[228:231], v[20:23]
	v_mfma_f32_16x16x32_bf16 v[16:19], v[152:155], v[228:231], v[16:19]
	s_setprio 0
	s_setprio 1
	v_mfma_f32_16x16x32_bf16 v[60:63], v[148:151], v[208:211], v[60:63]
	v_mfma_f32_16x16x32_bf16 v[56:59], v[156:159], v[208:211], v[56:59]
	v_mfma_f32_16x16x32_bf16 v[52:55], v[148:151], v[216:219], v[52:55]
	v_mfma_f32_16x16x32_bf16 v[48:51], v[156:159], v[216:219], v[48:51]
	v_mfma_f32_16x16x32_bf16 v[36:39], v[148:151], v[224:227], v[36:39]
	v_mfma_f32_16x16x32_bf16 v[32:35], v[156:159], v[224:227], v[32:35]
	v_mfma_f32_16x16x32_bf16 v[20:23], v[148:151], v[232:235], v[20:23]
	v_mfma_f32_16x16x32_bf16 v[16:19], v[156:159], v[232:235], v[16:19]
	s_setprio 0
	s_setprio 1
	v_mfma_f32_16x16x32_bf16 v[44:47], v[178:181], v[194:197], v[44:47]
	v_mfma_f32_16x16x32_bf16 v[40:43], v[186:189], v[194:197], v[40:43]
	v_mfma_f32_16x16x32_bf16 v[28:31], v[178:181], v[212:215], v[28:31]
	v_mfma_f32_16x16x32_bf16 v[24:27], v[186:189], v[212:215], v[24:27]
	v_mfma_f32_16x16x32_bf16 v[12:15], v[178:181], v[220:223], v[12:15]
	v_mfma_f32_16x16x32_bf16 v[8:11], v[186:189], v[220:223], v[8:11]
	v_mfma_f32_16x16x32_bf16 v[4:7], v[178:181], v[228:231], v[4:7]
	v_mfma_f32_16x16x32_bf16 v[0:3], v[186:189], v[228:231], v[0:3]
	s_setprio 0
	s_setprio 1
	v_mfma_f32_16x16x32_bf16 v[44:47], v[182:185], v[208:211], v[44:47]
	v_mfma_f32_16x16x32_bf16 v[40:43], v[190:193], v[208:211], v[40:43]
	v_mfma_f32_16x16x32_bf16 v[28:31], v[182:185], v[216:219], v[28:31]
	v_mfma_f32_16x16x32_bf16 v[24:27], v[190:193], v[216:219], v[24:27]
	v_mfma_f32_16x16x32_bf16 v[12:15], v[182:185], v[224:227], v[12:15]
	v_mfma_f32_16x16x32_bf16 v[8:11], v[190:193], v[224:227], v[8:11]
	v_mfma_f32_16x16x32_bf16 v[4:7], v[182:185], v[232:235], v[4:7]
	v_mfma_f32_16x16x32_bf16 v[0:3], v[190:193], v[232:235], v[0:3]
	s_setprio 0
	s_barrier
	s_add_i32 s41, s41, 2
	s_add_u32 s0, s0, 0x100
	s_addc_u32 s1, s1, 0
	s_add_u32 s15, s15, 0x100
	s_addc_u32 s27, s27, 0
	s_cmp_gt_u32 s41, 13
	s_cbranch_scc0 .LBB0_1360
	s_mov_b64 s[46:47], 0x80
	s_and_b64 vcc, exec, s[8:9]
	s_cbranch_vccz .LBB0_1363
	s_barrier

; #define PG8_STAGE(bufoff, gbase, voff) do { _Pragma("unroll") for (int _i = 0; _i < 2; ++_i) \
;         __builtin_amdgcn_global_load_lds((const unsigned*)((const char*)(gbase) + (voff)[_i]), (PG8_LAS unsigned*)(lds + (bufoff) + ldsw + _i * 8192), 16, 0, 0); } while (0)
; #define PG8_LDA(dst, b, h) do { _Pragma("unroll") for (int m = 0; m < 4; ++m) _Pragma("unroll") for (int k = 0; k < 2; ++k) dst[m][k] = *(const PG8_LAS bf16x8*)(lds + PG8_SA(b, h) + aoff + m * 2048 + k * 1024); } while (0)
; #define PG8_LDB(dst, b, h) do { _Pragma("unroll") for (int n = 0; n < 2; ++n) _Pragma("unroll") for (int k = 0; k < 2; ++k) dst[n][k] = *(const PG8_LAS bf16x8*)(lds + PG8_SB(b, h) + boff + n * 2048 + k * 1024); } while (0)
; #define PG8_MMA(ai, bj, At, Bt) do { __builtin_amdgcn_s_setprio(1); _Pragma("unroll") for (int m = 0; m < 4; ++m) _Pragma("unroll") for (int n = 0; n < 2; ++n) _Pragma("unroll") for (int k = 0; k < 2; ++k) \
;         acc[ai][bj][m][n] = __builtin_amdgcn_mfma_f32_16x16x32_bf16(Bt[n][k], At[m][k], acc[ai][bj][m][n], 0, 0, 0); __builtin_amdgcn_s_setprio(0); } while (0)
; #define PG8_WAIT_V(n) asm volatile("s_waitcnt vmcnt(" #n ")" ::: "memory")
; #define PG8_WAIT_L(n) asm volatile("s_waitcnt lgkmcnt(" #n ")" ::: "memory")
; template <class Epi, class Sched, bool ALIGN_EPI = false, bool SP2 = false>
; __device__ __forceinline__ void gemm_phase(PG8_LAS unsigned char* lds, const Gemm g, const Sched& S, const Epi& E, const int wave0) {
;     ...
;             const bool last = (t == nt - 2);
;             const char* a1 = cA + (size_t)(t + 1) * kstep;
;             const char* a2 = last ? nA : cA + (size_t)(t + 2) * kstep; const char* b2 = last ? nB : cB + (size_t)(t + 2) * kstep;
;             const char* a3 = a2 + kstep; const char* b3 = b2 + kstep;
;             if (last && has_next) S.a_ready(nxt);
;             if constexpr (SP2) {
;             PG8_LDB(B0, 0, 0); PG8_LDB(B1, 0, 1); PG8_SCHED; PG8_LDA(At, 0, 0); PG8_STAGE(PG8_SA(1, 1), a1 + hstepA, voffA);
;             PG8_WAIT_V(8); PG8_WAIT_L(0); PG8_BAR; PG8_MMA(0, 0, At, B0); PG8_MMA(0, 1, At, B1); PG8_BAR; PG8_SCHED;
;             PG8_LDA(At, 0, 1); PG8_STAGE(PG8_SB(0, 0), b2, voffB); PG8_STAGE(PG8_SB(0, 1), b2 + hstepB, voffB); PG8_STAGE(PG8_SA(0, 0), a2, voffA);
;             PG8_WAIT_V(8); PG8_WAIT_L(0); PG8_BAR; PG8_MMA(1, 0, At, B0); PG8_MMA(1, 1, At, B1); PG8_BAR; PG8_SCHED;
.LBB0_1571:
	ds_read_b128 v[140:143], v252
	ds_read_b128 v[148:151], v252 offset:1024
	ds_read_b128 v[152:155], v252 offset:2048
	ds_read_b128 v[156:159], v252 offset:3072
	ds_read_b128 v[178:181], v253
	ds_read_b128 v[182:185], v253 offset:1024
	ds_read_b128 v[186:189], v253 offset:2048
	ds_read_b128 v[190:193], v253 offset:3072
	ds_read_b128 v[194:197], v147
	ds_read_b128 v[208:211], v147 offset:1024
	ds_read_b128 v[212:215], v147 offset:2048
	ds_read_b128 v[216:219], v147 offset:3072
	ds_read_b128 v[220:223], v147 offset:4096
	ds_read_b128 v[224:227], v147 offset:5120
	ds_read_b128 v[228:231], v147 offset:6144
	ds_read_b128 v[232:235], v147 offset:7168
	s_add_u32 s16, s0, 0xfff80080
	s_addc_u32 s17, s1, -1
	s_add_i32 s46, 0, 0x10000
	s_cmp_eq_u32 s45, 28
	s_cselect_b32 s19, s9, s17
	s_cselect_b32 s18, s33, s16
	s_cselect_b32 s17, s7, s44
	s_cselect_b32 s16, s36, s37
	s_add_i32 s48, 0, 0x14000
	s_add_i32 m0, s15, 0xc000
	s_nop 0
	global_load_lds_dwordx4 v136, s[0:1]
	s_add_i32 m0, s15, 0xe000
	s_nop 0
	global_load_lds_dwordx4 v138, s[0:1]
	s_waitcnt vmcnt(8)
	s_waitcnt lgkmcnt(0)
	s_barrier
	s_setprio 1
	s_waitcnt lgkmcnt(0)
	v_mfma_f32_16x16x32_bf16 v[126:129], v[140:143], v[194:197], v[126:129]
	v_mfma_f32_16x16x32_bf16 v[122:125], v[152:155], v[194:197], v[122:125]
	v_mfma_f32_16x16x32_bf16 v[110:113], v[140:143], v[212:215], v[110:113]
	v_mfma_f32_16x16x32_bf16 v[106:109], v[152:155], v[212:215], v[106:109]
	v_mfma_f32_16x16x32_bf16 v[94:97], v[140:143], v[220:223], v[94:97]
	v_mfma_f32_16x16x32_bf16 v[90:93], v[152:155], v[220:223], v[90:93]
	v_mfma_f32_16x16x32_bf16 v[78:81], v[140:143], v[228:231], v[78:81]
	v_mfma_f32_16x16x32_bf16 v[74:77], v[152:155], v[228:231], v[74:77]
	s_setprio 0
	s_setprio 1
	v_mfma_f32_16x16x32_bf16 v[126:129], v[148:151], v[208:211], v[126:129]
	v_mfma_f32_16x16x32_bf16 v[122:125], v[156:159], v[208:211], v[122:125]
	v_mfma_f32_16x16x32_bf16 v[110:113], v[148:151], v[216:219], v[110:113]
	v_mfma_f32_16x16x32_bf16 v[106:109], v[156:159], v[216:219], v[106:109]
	v_mfma_f32_16x16x32_bf16 v[94:97], v[148:151], v[224:227], v[94:97]
	v_mfma_f32_16x16x32_bf16 v[90:93], v[156:159], v[224:227], v[90:93]
	v_mfma_f32_16x16x32_bf16 v[78:81], v[148:151], v[232:235], v[78:81]
	v_mfma_f32_16x16x32_bf16 v[74:77], v[156:159], v[232:235], v[74:77]
	s_setprio 0
	s_setprio 1
	v_mfma_f32_16x16x32_bf16 v[118:121], v[178:181], v[194:197], v[118:121]
	v_mfma_f32_16x16x32_bf16 v[114:117], v[186:189], v[194:197], v[114:117]
	v_mfma_f32_16x16x32_bf16 v[102:105], v[178:181], v[212:215], v[102:105]
	v_mfma_f32_16x16x32_bf16 v[98:101], v[186:189], v[212:215], v[98:101]
	v_mfma_f32_16x16x32_bf16 v[86:89], v[178:181], v[220:223], v[86:89]
	v_mfma_f32_16x16x32_bf16 v[82:85], v[186:189], v[220:223], v[82:85]
	v_mfma_f32_16x16x32_bf16 v[70:73], v[178:181], v[228:231], v[70:73]
	v_mfma_f32_16x16x32_bf16 v[66:69], v[186:189], v[228:231], v[66:69]
	s_setprio 0
	s_setprio 1
	v_mfma_f32_16x16x32_bf16 v[118:121], v[182:185], v[208:211], v[118:121]
	v_mfma_f32_16x16x32_bf16 v[114:117], v[190:193], v[208:211], v[114:117]
	v_mfma_f32_16x16x32_bf16 v[102:105], v[182:185], v[216:219], v[102:105]
	v_mfma_f32_16x16x32_bf16 v[98:101], v[190:193], v[216:219], v[98:101]
	v_mfma_f32_16x16x32_bf16 v[86:89], v[182:185], v[224:227], v[86:89]
	v_mfma_f32_16x16x32_bf16 v[82:85], v[190:193], v[224:227], v[82:85]
	v_mfma_f32_16x16x32_bf16 v[70:73], v[182:185], v[232:235], v[70:73]
	v_mfma_f32_16x16x32_bf16 v[66:69], v[190:193], v[232:235], v[66:69]
	s_setprio 0
	s_barrier
	ds_read_b128 v[194:197], v147 offset:16384
	ds_read_b128 v[208:211], v147 offset:17408
	ds_read_b128 v[212:215], v147 offset:18432
	ds_read_b128 v[216:219], v147 offset:19456
	ds_read_b128 v[220:223], v147 offset:20480
	ds_read_b128 v[224:227], v147 offset:21504
	ds_read_b128 v[228:231], v147 offset:22528
	ds_read_b128 v[232:235], v147 offset:23552
	s_add_i32 s46, s46, s28
	s_mov_b32 m0, s46
	s_nop 0
	global_load_lds_dwordx4 v64, s[16:17]
	s_add_i32 m0, s46, 0x2000
	s_add_u32 s46, s16, 0x80000
	s_addc_u32 s47, s17, 0
	s_add_i32 s48, s48, s28
	global_load_lds_dwordx4 v130, s[16:17]
	s_mov_b32 m0, s48
	s_mov_b64 s[100:101], s[18:19]
	global_load_lds_dwordx4 v64, s[46:47]
	s_add_i32 m0, s48, 0x2000
	s_nop 0
	global_load_lds_dwordx4 v130, s[46:47]
	s_mov_b32 m0, s15
	s_nop 0
	global_load_lds_dwordx4 v134, s[18:19]
	s_mov_b32 m0, s27
	s_nop 0
	global_load_lds_dwordx4 v132, s[18:19]
	s_waitcnt vmcnt(8)
	s_waitcnt lgkmcnt(0)
	s_barrier
	s_setprio 1
	s_waitcnt lgkmcnt(0)
	v_mfma_f32_16x16x32_bf16 v[60:63], v[140:143], v[194:197], v[60:63]
	v_mfma_f32_16x16x32_bf16 v[56:59], v[152:155], v[194:197], v[56:59]
	v_mfma_f32_16x16x32_bf16 v[44:47], v[140:143], v[212:215], v[44:47]
	v_mfma_f32_16x16x32_bf16 v[40:43], v[152:155], v[212:215], v[40:43]
	v_mfma_f32_16x16x32_bf16 v[28:31], v[140:143], v[220:223], v[28:31]
	v_mfma_f32_16x16x32_bf16 v[24:27], v[152:155], v[220:223], v[24:27]
	v_mfma_f32_16x16x32_bf16 v[12:15], v[140:143], v[228:231], v[12:15]
	v_mfma_f32_16x16x32_bf16 v[8:11], v[152:155], v[228:231], v[8:11]
	s_setprio 0
	s_setprio 1
	v_mfma_f32_16x16x32_bf16 v[60:63], v[148:151], v[208:211], v[60:63]
	v_mfma_f32_16x16x32_bf16 v[56:59], v[156:159], v[208:211], v[56:59]
	v_mfma_f32_16x16x32_bf16 v[44:47], v[148:151], v[216:219], v[44:47]
	v_mfma_f32_16x16x32_bf16 v[40:43], v[156:159], v[216:219], v[40:43]
	v_mfma_f32_16x16x32_bf16 v[28:31], v[148:151], v[224:227], v[28:31]
	v_mfma_f32_16x16x32_bf16 v[24:27], v[156:159], v[224:227], v[24:27]
	v_mfma_f32_16x16x32_bf16 v[12:15], v[148:151], v[232:235], v[12:15]
	v_mfma_f32_16x16x32_bf16 v[8:11], v[156:159], v[232:235], v[8:11]
	s_setprio 0
	s_setprio 1
	v_mfma_f32_16x16x32_bf16 v[52:55], v[178:181], v[194:197], v[52:55]
	v_mfma_f32_16x16x32_bf16 v[48:51], v[186:189], v[194:197], v[48:51]
	v_mfma_f32_16x16x32_bf16 v[36:39], v[178:181], v[212:215], v[36:39]
	v_mfma_f32_16x16x32_bf16 v[32:35], v[186:189], v[212:215], v[32:35]
	v_mfma_f32_16x16x32_bf16 v[20:23], v[178:181], v[220:223], v[20:23]
	v_mfma_f32_16x16x32_bf16 v[16:19], v[186:189], v[220:223], v[16:19]
	v_mfma_f32_16x16x32_bf16 v[4:7], v[178:181], v[228:231], v[4:7]
	v_mfma_f32_16x16x32_bf16 v[0:3], v[186:189], v[228:231], v[0:3]
	s_setprio 0
	s_setprio 1
	v_mfma_f32_16x16x32_bf16 v[52:55], v[182:185], v[208:211], v[52:55]
	v_mfma_f32_16x16x32_bf16 v[48:51], v[190:193], v[208:211], v[48:51]
	v_mfma_f32_16x16x32_bf16 v[36:39], v[182:185], v[216:219], v[36:39]
	v_mfma_f32_16x16x32_bf16 v[32:35], v[190:193], v[216:219], v[32:35]
	v_mfma_f32_16x16x32_bf16 v[20:23], v[182:185], v[224:227], v[20:23]
	v_mfma_f32_16x16x32_bf16 v[16:19], v[190:193], v[224:227], v[16:19]
	v_mfma_f32_16x16x32_bf16 v[4:7], v[182:185], v[232:235], v[4:7]
	v_mfma_f32_16x16x32_bf16 v[0:3], v[190:193], v[232:235], v[0:3]
	s_setprio 0
	s_barrier
; #define PG8_STAGE(bufoff, gbase, voff) do { _Pragma("unroll") for (int _i = 0; _i < 2; ++_i) \
;         __builtin_amdgcn_global_load_lds((const unsigned*)((const char*)(gbase) + (voff)[_i]), (PG8_LAS unsigned*)(lds + (bufoff) + ldsw + _i * 8192), 16, 0, 0); } while (0)
; #define PG8_LDA(dst, b, h) do { _Pragma("unroll") for (int m = 0; m < 4; ++m) _Pragma("unroll") for (int k = 0; k < 2; ++k) dst[m][k] = *(const PG8_LAS bf16x8*)(lds + PG8_SA(b, h) + aoff + m * 2048 + k * 1024); } while (0)
; #define PG8_LDB(dst, b, h) do { _Pragma("unroll") for (int n = 0; n < 2; ++n) _Pragma("unroll") for (int k = 0; k < 2; ++k) dst[n][k] = *(const PG8_LAS bf16x8*)(lds + PG8_SB(b, h) + boff + n * 2048 + k * 1024); } while (0)
; #define PG8_MMA(ai, bj, At, Bt) do { __builtin_amdgcn_s_setprio(1); _Pragma("unroll") for (int m = 0; m < 4; ++m) _Pragma("unroll") for (int n = 0; n < 2; ++n) _Pragma("unroll") for (int k = 0; k < 2; ++k) \
;         acc[ai][bj][m][n] = __builtin_amdgcn_mfma_f32_16x16x32_bf16(Bt[n][k], At[m][k], acc[ai][bj][m][n], 0, 0, 0); __builtin_amdgcn_s_setprio(0); } while (0)
; #define PG8_WAIT_V(n) asm volatile("s_waitcnt vmcnt(" #n ")" ::: "memory")
; #define PG8_WAIT_L(n) asm volatile("s_waitcnt lgkmcnt(" #n ")" ::: "memory")
; #define PG8_BAR __builtin_amdgcn_s_barrier()
; #define PG8_SCHED __builtin_amdgcn_sched_barrier(0)
; template <class Epi, class Sched, bool ALIGN_EPI = false, bool SP2 = false>
; __device__ __forceinline__ void gemm_phase(PG8_LAS unsigned char* lds, const Gemm g, const Sched& S, const Epi& E, const int wave0) {
;     ...
;         for (int t = 0; t < nt; t += 2) {
;             const bool last = (t == nt - 2);
;             const char* a1 = cA + (size_t)(t + 1) * kstep;
;             const char* a2 = last ? nA : cA + (size_t)(t + 2) * kstep; const char* b2 = last ? nB : cB + (size_t)(t + 2) * kstep;
;     ...
;             PG8_LDB(B0, 1, 0); PG8_LDB(B1, 1, 1); PG8_SCHED; PG8_LDA(At, 1, 0); PG8_STAGE(PG8_SA(0, 1), a2 + hstepA, voffA);
;             PG8_WAIT_V(8); PG8_WAIT_L(0); PG8_BAR; PG8_MMA(0, 0, At, B0); PG8_MMA(0, 1, At, B1); PG8_BAR; PG8_SCHED;
;             PG8_LDA(At, 1, 1); PG8_STAGE(PG8_SB(1, 0), b3, voffB); PG8_STAGE(PG8_SB(1, 1), b3 + hstepB, voffB); PG8_STAGE(PG8_SA(1, 0), a3, voffA);
;             PG8_WAIT_V(8); PG8_WAIT_L(0); PG8_BAR; PG8_MMA(1, 0, At, B0); PG8_MMA(1, 1, At, B1); PG8_BAR; PG8_SCHED;
	ds_read_b128 v[140:143], v254
	ds_read_b128 v[148:151], v254 offset:1024
	ds_read_b128 v[152:155], v254 offset:2048
	ds_read_b128 v[156:159], v254 offset:3072
	ds_read_b128 v[178:181], v255
	ds_read_b128 v[182:185], v255 offset:1024
	ds_read_b128 v[186:189], v255 offset:2048
	ds_read_b128 v[190:193], v255 offset:3072
	ds_read_b128 v[194:197], v147 offset:32768
	ds_read_b128 v[208:211], v147 offset:33792
	ds_read_b128 v[212:215], v147 offset:34816
	ds_read_b128 v[216:219], v147 offset:35840
	ds_read_b128 v[220:223], v147 offset:36864
	ds_read_b128 v[224:227], v147 offset:37888
	ds_read_b128 v[228:231], v147 offset:38912
	ds_read_b128 v[232:235], v147 offset:39936
	s_add_i32 s46, 0, 0x18000
	s_add_i32 s47, 0, 0x1c000
	s_add_u32 s18, s18, 0x80000
	s_addc_u32 s19, s19, 0
	s_mov_b32 m0, s29
	s_nop 0
	global_load_lds_dwordx4 v134, s[18:19]
	s_mov_b32 m0, s30
	s_nop 0
	global_load_lds_dwordx4 v132, s[18:19]
	s_waitcnt vmcnt(8)
	s_waitcnt lgkmcnt(0)
	s_barrier
	s_setprio 1
	s_waitcnt lgkmcnt(0)
	v_mfma_f32_16x16x32_bf16 v[126:129], v[140:143], v[194:197], v[126:129]
	v_mfma_f32_16x16x32_bf16 v[122:125], v[152:155], v[194:197], v[122:125]
	v_mfma_f32_16x16x32_bf16 v[110:113], v[140:143], v[212:215], v[110:113]
	v_mfma_f32_16x16x32_bf16 v[106:109], v[152:155], v[212:215], v[106:109]
	v_mfma_f32_16x16x32_bf16 v[94:97], v[140:143], v[220:223], v[94:97]
	v_mfma_f32_16x16x32_bf16 v[90:93], v[152:155], v[220:223], v[90:93]
	v_mfma_f32_16x16x32_bf16 v[78:81], v[140:143], v[228:231], v[78:81]
	v_mfma_f32_16x16x32_bf16 v[74:77], v[152:155], v[228:231], v[74:77]
	s_setprio 0
	s_setprio 1
	v_mfma_f32_16x16x32_bf16 v[126:129], v[148:151], v[208:211], v[126:129]
	v_mfma_f32_16x16x32_bf16 v[122:125], v[156:159], v[208:211], v[122:125]
	v_mfma_f32_16x16x32_bf16 v[110:113], v[148:151], v[216:219], v[110:113]
	v_mfma_f32_16x16x32_bf16 v[106:109], v[156:159], v[216:219], v[106:109]
	v_mfma_f32_16x16x32_bf16 v[94:97], v[148:151], v[224:227], v[94:97]
	v_mfma_f32_16x16x32_bf16 v[90:93], v[156:159], v[224:227], v[90:93]
	v_mfma_f32_16x16x32_bf16 v[78:81], v[148:151], v[232:235], v[78:81]
	v_mfma_f32_16x16x32_bf16 v[74:77], v[156:159], v[232:235], v[74:77]
	s_setprio 0
	s_setprio 1
	v_mfma_f32_16x16x32_bf16 v[118:121], v[178:181], v[194:197], v[118:121]
	v_mfma_f32_16x16x32_bf16 v[114:117], v[186:189], v[194:197], v[114:117]
	v_mfma_f32_16x16x32_bf16 v[102:105], v[178:181], v[212:215], v[102:105]
	v_mfma_f32_16x16x32_bf16 v[98:101], v[186:189], v[212:215], v[98:101]
	v_mfma_f32_16x16x32_bf16 v[86:89], v[178:181], v[220:223], v[86:89]
	v_mfma_f32_16x16x32_bf16 v[82:85], v[186:189], v[220:223], v[82:85]
	v_mfma_f32_16x16x32_bf16 v[70:73], v[178:181], v[228:231], v[70:73]
	v_mfma_f32_16x16x32_bf16 v[66:69], v[186:189], v[228:231], v[66:69]
	s_setprio 0
	s_setprio 1
	v_mfma_f32_16x16x32_bf16 v[118:121], v[182:185], v[208:211], v[118:121]
	v_mfma_f32_16x16x32_bf16 v[114:117], v[190:193], v[208:211], v[114:117]
	v_mfma_f32_16x16x32_bf16 v[102:105], v[182:185], v[216:219], v[102:105]
	v_mfma_f32_16x16x32_bf16 v[98:101], v[190:193], v[216:219], v[98:101]
	v_mfma_f32_16x16x32_bf16 v[86:89], v[182:185], v[224:227], v[86:89]
	v_mfma_f32_16x16x32_bf16 v[82:85], v[190:193], v[224:227], v[82:85]
	v_mfma_f32_16x16x32_bf16 v[70:73], v[182:185], v[232:235], v[70:73]
	v_mfma_f32_16x16x32_bf16 v[66:69], v[190:193], v[232:235], v[66:69]
	s_setprio 0
	s_barrier
	ds_read_b128 v[194:197], v147 offset:49152
	ds_read_b128 v[208:211], v147 offset:50176
	ds_read_b128 v[212:215], v147 offset:51200
	ds_read_b128 v[216:219], v147 offset:52224
	ds_read_b128 v[220:223], v147 offset:53248
	ds_read_b128 v[224:227], v147 offset:54272
	ds_read_b128 v[228:231], v147 offset:55296
	ds_read_b128 v[232:235], v147 offset:56320
	s_add_i32 s18, s46, s28
	s_add_u32 s50, s16, 0x80
	s_addc_u32 s51, s17, 0
	s_mov_b32 m0, s18
	s_nop 0
	global_load_lds_dwordx4 v64, s[50:51]
	s_add_i32 m0, s18, 0x2000
	s_add_u32 s16, s16, 0x80080
	s_addc_u32 s17, s17, 0
	s_add_i32 s18, s47, s28
	global_load_lds_dwordx4 v130, s[50:51]
	s_mov_b32 m0, s18
	s_nop 0
	global_load_lds_dwordx4 v64, s[16:17]
	s_add_i32 m0, s18, 0x2000
	s_nop 0
	global_load_lds_dwordx4 v130, s[16:17]
	s_add_u32 s100, s100, 0x80
	s_addc_u32 s101, s101, 0
	s_mov_b32 m0, s31
	s_nop 0
	global_load_lds_dwordx4 v134, s[100:101]
	s_mov_b32 m0, s34
	s_nop 0
	global_load_lds_dwordx4 v132, s[100:101]
	s_waitcnt vmcnt(8)
	s_waitcnt lgkmcnt(0)
	s_barrier
	s_setprio 1
	s_waitcnt lgkmcnt(0)
	v_mfma_f32_16x16x32_bf16 v[60:63], v[140:143], v[194:197], v[60:63]
	v_mfma_f32_16x16x32_bf16 v[56:59], v[152:155], v[194:197], v[56:59]
	v_mfma_f32_16x16x32_bf16 v[44:47], v[140:143], v[212:215], v[44:47]
	v_mfma_f32_16x16x32_bf16 v[40:43], v[152:155], v[212:215], v[40:43]
	v_mfma_f32_16x16x32_bf16 v[28:31], v[140:143], v[220:223], v[28:31]
	v_mfma_f32_16x16x32_bf16 v[24:27], v[152:155], v[220:223], v[24:27]
	v_mfma_f32_16x16x32_bf16 v[12:15], v[140:143], v[228:231], v[12:15]
	v_mfma_f32_16x16x32_bf16 v[8:11], v[152:155], v[228:231], v[8:11]
	s_setprio 0
	s_setprio 1
	v_mfma_f32_16x16x32_bf16 v[60:63], v[148:151], v[208:211], v[60:63]
	v_mfma_f32_16x16x32_bf16 v[56:59], v[156:159], v[208:211], v[56:59]
	v_mfma_f32_16x16x32_bf16 v[44:47], v[148:151], v[216:219], v[44:47]
	v_mfma_f32_16x16x32_bf16 v[40:43], v[156:159], v[216:219], v[40:43]
	v_mfma_f32_16x16x32_bf16 v[28:31], v[148:151], v[224:227], v[28:31]
	v_mfma_f32_16x16x32_bf16 v[24:27], v[156:159], v[224:227], v[24:27]
	v_mfma_f32_16x16x32_bf16 v[12:15], v[148:151], v[232:235], v[12:15]
	v_mfma_f32_16x16x32_bf16 v[8:11], v[156:159], v[232:235], v[8:11]
	s_setprio 0
	s_setprio 1
	v_mfma_f32_16x16x32_bf16 v[52:55], v[178:181], v[194:197], v[52:55]
	v_mfma_f32_16x16x32_bf16 v[48:51], v[186:189], v[194:197], v[48:51]
	v_mfma_f32_16x16x32_bf16 v[36:39], v[178:181], v[212:215], v[36:39]
	v_mfma_f32_16x16x32_bf16 v[32:35], v[186:189], v[212:215], v[32:35]
	v_mfma_f32_16x16x32_bf16 v[20:23], v[178:181], v[220:223], v[20:23]
	v_mfma_f32_16x16x32_bf16 v[16:19], v[186:189], v[220:223], v[16:19]
	v_mfma_f32_16x16x32_bf16 v[4:7], v[178:181], v[228:231], v[4:7]
	v_mfma_f32_16x16x32_bf16 v[0:3], v[186:189], v[228:231], v[0:3]
	s_setprio 0
	s_setprio 1
	v_mfma_f32_16x16x32_bf16 v[52:55], v[182:185], v[208:211], v[52:55]
	v_mfma_f32_16x16x32_bf16 v[48:51], v[190:193], v[208:211], v[48:51]
	v_mfma_f32_16x16x32_bf16 v[36:39], v[182:185], v[216:219], v[36:39]
	v_mfma_f32_16x16x32_bf16 v[32:35], v[190:193], v[216:219], v[32:35]
	v_mfma_f32_16x16x32_bf16 v[20:23], v[182:185], v[224:227], v[20:23]
	v_mfma_f32_16x16x32_bf16 v[16:19], v[190:193], v[224:227], v[16:19]
	v_mfma_f32_16x16x32_bf16 v[4:7], v[182:185], v[232:235], v[4:7]
	v_mfma_f32_16x16x32_bf16 v[0:3], v[190:193], v[232:235], v[0:3]
	s_setprio 0
	s_barrier
	s_add_i32 s45, s45, 2
	s_add_u32 s0, s0, 0x100
	s_addc_u32 s1, s1, 0
	s_add_u32 s37, s37, 0x100
	s_addc_u32 s44, s44, 0
	s_cmp_gt_u32 s45, 29
	s_cbranch_scc0 .LBB0_1571
	s_mov_b64 s[50:51], 0x80
	s_and_b64 vcc, exec, s[4:5]
	s_cbranch_vccz .LBB0_1574
	s_barrier

; #define PG8_STAGE(bufoff, gbase, voff) do { _Pragma("unroll") for (int _i = 0; _i < 2; ++_i) \
;         __builtin_amdgcn_global_load_lds((const unsigned*)((const char*)(gbase) + (voff)[_i]), (PG8_LAS unsigned*)(lds + (bufoff) + ldsw + _i * 8192), 16, 0, 0); } while (0)
; #define PG8_LDA(dst, b, h) do { _Pragma("unroll") for (int m = 0; m < 4; ++m) _Pragma("unroll") for (int k = 0; k < 2; ++k) dst[m][k] = *(const PG8_LAS bf16x8*)(lds + PG8_SA(b, h) + aoff + m * 2048 + k * 1024); } while (0)
; #define PG8_LDB(dst, b, h) do { _Pragma("unroll") for (int n = 0; n < 2; ++n) _Pragma("unroll") for (int k = 0; k < 2; ++k) dst[n][k] = *(const PG8_LAS bf16x8*)(lds + PG8_SB(b, h) + boff + n * 2048 + k * 1024); } while (0)
; #define PG8_MMA(ai, bj, At, Bt) do { __builtin_amdgcn_s_setprio(1); _Pragma("unroll") for (int m = 0; m < 4; ++m) _Pragma("unroll") for (int n = 0; n < 2; ++n) _Pragma("unroll") for (int k = 0; k < 2; ++k) \
;         acc[ai][bj][m][n] = __builtin_amdgcn_mfma_f32_16x16x32_bf16(Bt[n][k], At[m][k], acc[ai][bj][m][n], 0, 0, 0); __builtin_amdgcn_s_setprio(0); } while (0)
; #define PG8_WAIT_V(n) asm volatile("s_waitcnt vmcnt(" #n ")" ::: "memory")
; #define PG8_WAIT_L(n) asm volatile("s_waitcnt lgkmcnt(" #n ")" ::: "memory")
; template <class Epi, class Sched, bool ALIGN_EPI = false, bool SP2 = false>
; __device__ __forceinline__ void gemm_phase(PG8_LAS unsigned char* lds, const Gemm g, const Sched& S, const Epi& E, const int wave0) {
;     ...
;             const bool last = (t == nt - 2);
;             const char* a1 = cA + (size_t)(t + 1) * kstep;
;             const char* a2 = last ? nA : cA + (size_t)(t + 2) * kstep; const char* b2 = last ? nB : cB + (size_t)(t + 2) * kstep;
;             const char* a3 = a2 + kstep; const char* b3 = b2 + kstep;
;             if (last && has_next) S.a_ready(nxt);
;             if constexpr (SP2) {
;             PG8_LDB(B0, 0, 0); PG8_LDB(B1, 0, 1); PG8_SCHED; PG8_LDA(At, 0, 0); PG8_STAGE(PG8_SA(1, 1), a1 + hstepA, voffA);
;             PG8_WAIT_V(8); PG8_WAIT_L(0); PG8_BAR; PG8_MMA(0, 0, At, B0); PG8_MMA(0, 1, At, B1); PG8_BAR; PG8_SCHED;
;             PG8_LDA(At, 0, 1); PG8_STAGE(PG8_SB(0, 0), b2, voffB); PG8_STAGE(PG8_SB(0, 1), b2 + hstepB, voffB); PG8_STAGE(PG8_SA(0, 0), a2, voffA);
;             PG8_WAIT_V(8); PG8_WAIT_L(0); PG8_BAR; PG8_MMA(1, 0, At, B0); PG8_MMA(1, 1, At, B1); PG8_BAR; PG8_SCHED;
.LBB0_1685:
	ds_read_b128 v[144:147], v252
	ds_read_b128 v[148:151], v252 offset:1024
	ds_read_b128 v[152:155], v252 offset:2048
	ds_read_b128 v[156:159], v252 offset:3072
	ds_read_b128 v[178:181], v253
	ds_read_b128 v[182:185], v253 offset:1024
	ds_read_b128 v[186:189], v253 offset:2048
	ds_read_b128 v[190:193], v253 offset:3072
	ds_read_b128 v[194:197], v143
	ds_read_b128 v[208:211], v143 offset:1024
	ds_read_b128 v[212:215], v143 offset:2048
	ds_read_b128 v[216:219], v143 offset:3072
	ds_read_b128 v[220:223], v143 offset:4096
	ds_read_b128 v[224:227], v143 offset:5120
	ds_read_b128 v[228:231], v143 offset:6144
	ds_read_b128 v[232:235], v143 offset:7168
	s_add_u32 s16, s0, 0xffe00080
	s_addc_u32 s17, s1, -1
	s_add_i32 s43, 0, 0x10000
	s_cmpk_eq_i32 s42, 0x7c
	s_cselect_b32 s19, s11, s17
	s_cselect_b32 s18, s34, s16
	s_cselect_b32 s17, s9, s37
	s_cselect_b32 s16, s35, s36
	s_add_i32 s46, 0, 0x14000
	s_add_i32 m0, s21, 0xc000
	s_nop 0
	global_load_lds_dwordx4 v136, s[0:1]
	s_add_i32 m0, s21, 0xe000
	s_nop 0
	global_load_lds_dwordx4 v138, s[0:1]
	s_waitcnt vmcnt(8)
	s_waitcnt lgkmcnt(0)
	s_barrier
	s_setprio 1
	s_waitcnt lgkmcnt(0)
	v_mfma_f32_16x16x32_bf16 v[126:129], v[144:147], v[194:197], v[126:129]
	v_mfma_f32_16x16x32_bf16 v[122:125], v[152:155], v[194:197], v[122:125]
	v_mfma_f32_16x16x32_bf16 v[118:121], v[144:147], v[212:215], v[118:121]
	v_mfma_f32_16x16x32_bf16 v[114:117], v[152:155], v[212:215], v[114:117]
	v_mfma_f32_16x16x32_bf16 v[102:105], v[144:147], v[220:223], v[102:105]
	v_mfma_f32_16x16x32_bf16 v[98:101], v[152:155], v[220:223], v[98:101]
	v_mfma_f32_16x16x32_bf16 v[86:89], v[144:147], v[228:231], v[86:89]
	v_mfma_f32_16x16x32_bf16 v[82:85], v[152:155], v[228:231], v[82:85]
	s_setprio 0
	s_setprio 1
	v_mfma_f32_16x16x32_bf16 v[126:129], v[148:151], v[208:211], v[126:129]
	v_mfma_f32_16x16x32_bf16 v[122:125], v[156:159], v[208:211], v[122:125]
	v_mfma_f32_16x16x32_bf16 v[118:121], v[148:151], v[216:219], v[118:121]
	v_mfma_f32_16x16x32_bf16 v[114:117], v[156:159], v[216:219], v[114:117]
	v_mfma_f32_16x16x32_bf16 v[102:105], v[148:151], v[224:227], v[102:105]
	v_mfma_f32_16x16x32_bf16 v[98:101], v[156:159], v[224:227], v[98:101]
	v_mfma_f32_16x16x32_bf16 v[86:89], v[148:151], v[232:235], v[86:89]
	v_mfma_f32_16x16x32_bf16 v[82:85], v[156:159], v[232:235], v[82:85]
	s_setprio 0
	s_setprio 1
	v_mfma_f32_16x16x32_bf16 v[110:113], v[178:181], v[194:197], v[110:113]
	v_mfma_f32_16x16x32_bf16 v[106:109], v[186:189], v[194:197], v[106:109]
	v_mfma_f32_16x16x32_bf16 v[94:97], v[178:181], v[212:215], v[94:97]
	v_mfma_f32_16x16x32_bf16 v[90:93], v[186:189], v[212:215], v[90:93]
	v_mfma_f32_16x16x32_bf16 v[78:81], v[178:181], v[220:223], v[78:81]
	v_mfma_f32_16x16x32_bf16 v[74:77], v[186:189], v[220:223], v[74:77]
	v_mfma_f32_16x16x32_bf16 v[70:73], v[178:181], v[228:231], v[70:73]
	v_mfma_f32_16x16x32_bf16 v[66:69], v[186:189], v[228:231], v[66:69]
	s_setprio 0
	s_setprio 1
	v_mfma_f32_16x16x32_bf16 v[110:113], v[182:185], v[208:211], v[110:113]
	v_mfma_f32_16x16x32_bf16 v[106:109], v[190:193], v[208:211], v[106:109]
	v_mfma_f32_16x16x32_bf16 v[94:97], v[182:185], v[216:219], v[94:97]
	v_mfma_f32_16x16x32_bf16 v[90:93], v[190:193], v[216:219], v[90:93]
	v_mfma_f32_16x16x32_bf16 v[78:81], v[182:185], v[224:227], v[78:81]
	v_mfma_f32_16x16x32_bf16 v[74:77], v[190:193], v[224:227], v[74:77]
	v_mfma_f32_16x16x32_bf16 v[70:73], v[182:185], v[232:235], v[70:73]
	v_mfma_f32_16x16x32_bf16 v[66:69], v[190:193], v[232:235], v[66:69]
	s_setprio 0
	s_barrier
	ds_read_b128 v[194:197], v143 offset:16384
	ds_read_b128 v[208:211], v143 offset:17408
	ds_read_b128 v[212:215], v143 offset:18432
	ds_read_b128 v[216:219], v143 offset:19456
	ds_read_b128 v[220:223], v143 offset:20480
	ds_read_b128 v[224:227], v143 offset:21504
	ds_read_b128 v[228:231], v143 offset:22528
	ds_read_b128 v[232:235], v143 offset:23552
	s_add_i32 s43, s43, s20
	s_mov_b32 m0, s43
	s_nop 0
	global_load_lds_dwordx4 v64, s[16:17]
	s_add_i32 m0, s43, 0x2000
	s_add_u32 s44, s16, 0x200000
	s_addc_u32 s45, s17, 0
	s_add_i32 s43, s46, s20
	global_load_lds_dwordx4 v130, s[16:17]
	s_mov_b32 m0, s43
	s_mov_b64 s[100:101], s[18:19]
	global_load_lds_dwordx4 v64, s[44:45]
	s_add_i32 m0, s43, 0x2000
	s_nop 0
	global_load_lds_dwordx4 v130, s[44:45]
	s_mov_b32 m0, s21
	s_nop 0
	global_load_lds_dwordx4 v134, s[18:19]
	s_mov_b32 m0, s25
	s_nop 0
	global_load_lds_dwordx4 v132, s[18:19]
	s_waitcnt vmcnt(8)
	s_waitcnt lgkmcnt(0)
	s_barrier
	s_setprio 1
	s_waitcnt lgkmcnt(0)
	v_mfma_f32_16x16x32_bf16 v[60:63], v[144:147], v[194:197], v[60:63]
	v_mfma_f32_16x16x32_bf16 v[56:59], v[152:155], v[194:197], v[56:59]
	v_mfma_f32_16x16x32_bf16 v[52:55], v[144:147], v[212:215], v[52:55]
	v_mfma_f32_16x16x32_bf16 v[48:51], v[152:155], v[212:215], v[48:51]
	v_mfma_f32_16x16x32_bf16 v[36:39], v[144:147], v[220:223], v[36:39]
	v_mfma_f32_16x16x32_bf16 v[32:35], v[152:155], v[220:223], v[32:35]
	v_mfma_f32_16x16x32_bf16 v[20:23], v[144:147], v[228:231], v[20:23]
	v_mfma_f32_16x16x32_bf16 v[16:19], v[152:155], v[228:231], v[16:19]
	s_setprio 0
	s_setprio 1
	v_mfma_f32_16x16x32_bf16 v[60:63], v[148:151], v[208:211], v[60:63]
	v_mfma_f32_16x16x32_bf16 v[56:59], v[156:159], v[208:211], v[56:59]
	v_mfma_f32_16x16x32_bf16 v[52:55], v[148:151], v[216:219], v[52:55]
	v_mfma_f32_16x16x32_bf16 v[48:51], v[156:159], v[216:219], v[48:51]
	v_mfma_f32_16x16x32_bf16 v[36:39], v[148:151], v[224:227], v[36:39]
	v_mfma_f32_16x16x32_bf16 v[32:35], v[156:159], v[224:227], v[32:35]
	v_mfma_f32_16x16x32_bf16 v[20:23], v[148:151], v[232:235], v[20:23]
	v_mfma_f32_16x16x32_bf16 v[16:19], v[156:159], v[232:235], v[16:19]
	s_setprio 0
	s_setprio 1
	v_mfma_f32_16x16x32_bf16 v[44:47], v[178:181], v[194:197], v[44:47]
	v_mfma_f32_16x16x32_bf16 v[40:43], v[186:189], v[194:197], v[40:43]
	v_mfma_f32_16x16x32_bf16 v[28:31], v[178:181], v[212:215], v[28:31]
	v_mfma_f32_16x16x32_bf16 v[24:27], v[186:189], v[212:215], v[24:27]
	v_mfma_f32_16x16x32_bf16 v[12:15], v[178:181], v[220:223], v[12:15]
	v_mfma_f32_16x16x32_bf16 v[8:11], v[186:189], v[220:223], v[8:11]
	v_mfma_f32_16x16x32_bf16 v[4:7], v[178:181], v[228:231], v[4:7]
	v_mfma_f32_16x16x32_bf16 v[0:3], v[186:189], v[228:231], v[0:3]
	s_setprio 0
	s_setprio 1
	v_mfma_f32_16x16x32_bf16 v[44:47], v[182:185], v[208:211], v[44:47]
	v_mfma_f32_16x16x32_bf16 v[40:43], v[190:193], v[208:211], v[40:43]
	v_mfma_f32_16x16x32_bf16 v[28:31], v[182:185], v[216:219], v[28:31]
	v_mfma_f32_16x16x32_bf16 v[24:27], v[190:193], v[216:219], v[24:27]
	v_mfma_f32_16x16x32_bf16 v[12:15], v[182:185], v[224:227], v[12:15]
	v_mfma_f32_16x16x32_bf16 v[8:11], v[190:193], v[224:227], v[8:11]
	v_mfma_f32_16x16x32_bf16 v[4:7], v[182:185], v[232:235], v[4:7]
	v_mfma_f32_16x16x32_bf16 v[0:3], v[190:193], v[232:235], v[0:3]
	s_setprio 0
	s_barrier
; #define PG8_STAGE(bufoff, gbase, voff) do { _Pragma("unroll") for (int _i = 0; _i < 2; ++_i) \
;         __builtin_amdgcn_global_load_lds((const unsigned*)((const char*)(gbase) + (voff)[_i]), (PG8_LAS unsigned*)(lds + (bufoff) + ldsw + _i * 8192), 16, 0, 0); } while (0)
; #define PG8_LDA(dst, b, h) do { _Pragma("unroll") for (int m = 0; m < 4; ++m) _Pragma("unroll") for (int k = 0; k < 2; ++k) dst[m][k] = *(const PG8_LAS bf16x8*)(lds + PG8_SA(b, h) + aoff + m * 2048 + k * 1024); } while (0)
; #define PG8_LDB(dst, b, h) do { _Pragma("unroll") for (int n = 0; n < 2; ++n) _Pragma("unroll") for (int k = 0; k < 2; ++k) dst[n][k] = *(const PG8_LAS bf16x8*)(lds + PG8_SB(b, h) + boff + n * 2048 + k * 1024); } while (0)
; #define PG8_MMA(ai, bj, At, Bt) do { __builtin_amdgcn_s_setprio(1); _Pragma("unroll") for (int m = 0; m < 4; ++m) _Pragma("unroll") for (int n = 0; n < 2; ++n) _Pragma("unroll") for (int k = 0; k < 2; ++k) \
;         acc[ai][bj][m][n] = __builtin_amdgcn_mfma_f32_16x16x32_bf16(Bt[n][k], At[m][k], acc[ai][bj][m][n], 0, 0, 0); __builtin_amdgcn_s_setprio(0); } while (0)
; #define PG8_WAIT_V(n) asm volatile("s_waitcnt vmcnt(" #n ")" ::: "memory")
; #define PG8_WAIT_L(n) asm volatile("s_waitcnt lgkmcnt(" #n ")" ::: "memory")
; #define PG8_BAR __builtin_amdgcn_s_barrier()
; #define PG8_SCHED __builtin_amdgcn_sched_barrier(0)
; template <class Epi, class Sched, bool ALIGN_EPI = false, bool SP2 = false>
; __device__ __forceinline__ void gemm_phase(PG8_LAS unsigned char* lds, const Gemm g, const Sched& S, const Epi& E, const int wave0) {
;     ...
;         for (int t = 0; t < nt; t += 2) {
;             const bool last = (t == nt - 2);
;             const char* a1 = cA + (size_t)(t + 1) * kstep;
;             const char* a2 = last ? nA : cA + (size_t)(t + 2) * kstep; const char* b2 = last ? nB : cB + (size_t)(t + 2) * kstep;
;     ...
;             PG8_LDB(B0, 1, 0); PG8_LDB(B1, 1, 1); PG8_SCHED; PG8_LDA(At, 1, 0); PG8_STAGE(PG8_SA(0, 1), a2 + hstepA, voffA);
;             PG8_WAIT_V(8); PG8_WAIT_L(0); PG8_BAR; PG8_MMA(0, 0, At, B0); PG8_MMA(0, 1, At, B1); PG8_BAR; PG8_SCHED;
;             PG8_LDA(At, 1, 1); PG8_STAGE(PG8_SB(1, 0), b3, voffB); PG8_STAGE(PG8_SB(1, 1), b3 + hstepB, voffB); PG8_STAGE(PG8_SA(1, 0), a3, voffA);
;             PG8_WAIT_V(8); PG8_WAIT_L(0); PG8_BAR; PG8_MMA(1, 0, At, B0); PG8_MMA(1, 1, At, B1); PG8_BAR; PG8_SCHED;
	ds_read_b128 v[144:147], v254
	ds_read_b128 v[148:151], v254 offset:1024
	ds_read_b128 v[152:155], v254 offset:2048
	ds_read_b128 v[156:159], v254 offset:3072
	ds_read_b128 v[178:181], v255
	ds_read_b128 v[182:185], v255 offset:1024
	ds_read_b128 v[186:189], v255 offset:2048
	ds_read_b128 v[190:193], v255 offset:3072
	ds_read_b128 v[194:197], v143 offset:32768
	ds_read_b128 v[208:211], v143 offset:33792
	ds_read_b128 v[212:215], v143 offset:34816
	ds_read_b128 v[216:219], v143 offset:35840
	ds_read_b128 v[220:223], v143 offset:36864
	ds_read_b128 v[224:227], v143 offset:37888
	ds_read_b128 v[228:231], v143 offset:38912
	ds_read_b128 v[232:235], v143 offset:39936
	s_add_i32 s43, 0, 0x18000
	s_add_i32 s44, 0, 0x1c000
	s_add_u32 s18, s18, 0x200000
	s_addc_u32 s19, s19, 0
	s_mov_b32 m0, s26
	s_nop 0
	global_load_lds_dwordx4 v134, s[18:19]
	s_mov_b32 m0, s27
	s_nop 0
	global_load_lds_dwordx4 v132, s[18:19]
	s_waitcnt vmcnt(8)
	s_waitcnt lgkmcnt(0)
	s_barrier
	s_setprio 1
	s_waitcnt lgkmcnt(0)
	v_mfma_f32_16x16x32_bf16 v[126:129], v[144:147], v[194:197], v[126:129]
	v_mfma_f32_16x16x32_bf16 v[122:125], v[152:155], v[194:197], v[122:125]
	v_mfma_f32_16x16x32_bf16 v[118:121], v[144:147], v[212:215], v[118:121]
	v_mfma_f32_16x16x32_bf16 v[114:117], v[152:155], v[212:215], v[114:117]
	v_mfma_f32_16x16x32_bf16 v[102:105], v[144:147], v[220:223], v[102:105]
	v_mfma_f32_16x16x32_bf16 v[98:101], v[152:155], v[220:223], v[98:101]
	v_mfma_f32_16x16x32_bf16 v[86:89], v[144:147], v[228:231], v[86:89]
	v_mfma_f32_16x16x32_bf16 v[82:85], v[152:155], v[228:231], v[82:85]
	s_setprio 0
	s_setprio 1
	v_mfma_f32_16x16x32_bf16 v[126:129], v[148:151], v[208:211], v[126:129]
	v_mfma_f32_16x16x32_bf16 v[122:125], v[156:159], v[208:211], v[122:125]
	v_mfma_f32_16x16x32_bf16 v[118:121], v[148:151], v[216:219], v[118:121]
	v_mfma_f32_16x16x32_bf16 v[114:117], v[156:159], v[216:219], v[114:117]
	v_mfma_f32_16x16x32_bf16 v[102:105], v[148:151], v[224:227], v[102:105]
	v_mfma_f32_16x16x32_bf16 v[98:101], v[156:159], v[224:227], v[98:101]
	v_mfma_f32_16x16x32_bf16 v[86:89], v[148:151], v[232:235], v[86:89]
	v_mfma_f32_16x16x32_bf16 v[82:85], v[156:159], v[232:235], v[82:85]
	s_setprio 0
	s_setprio 1
	v_mfma_f32_16x16x32_bf16 v[110:113], v[178:181], v[194:197], v[110:113]
	v_mfma_f32_16x16x32_bf16 v[106:109], v[186:189], v[194:197], v[106:109]
	v_mfma_f32_16x16x32_bf16 v[94:97], v[178:181], v[212:215], v[94:97]
	v_mfma_f32_16x16x32_bf16 v[90:93], v[186:189], v[212:215], v[90:93]
	v_mfma_f32_16x16x32_bf16 v[78:81], v[178:181], v[220:223], v[78:81]
	v_mfma_f32_16x16x32_bf16 v[74:77], v[186:189], v[220:223], v[74:77]
	v_mfma_f32_16x16x32_bf16 v[70:73], v[178:181], v[228:231], v[70:73]
	v_mfma_f32_16x16x32_bf16 v[66:69], v[186:189], v[228:231], v[66:69]
	s_setprio 0
	s_setprio 1
	v_mfma_f32_16x16x32_bf16 v[110:113], v[182:185], v[208:211], v[110:113]
	v_mfma_f32_16x16x32_bf16 v[106:109], v[190:193], v[208:211], v[106:109]
	v_mfma_f32_16x16x32_bf16 v[94:97], v[182:185], v[216:219], v[94:97]
	v_mfma_f32_16x16x32_bf16 v[90:93], v[190:193], v[216:219], v[90:93]
	v_mfma_f32_16x16x32_bf16 v[78:81], v[182:185], v[224:227], v[78:81]
	v_mfma_f32_16x16x32_bf16 v[74:77], v[190:193], v[224:227], v[74:77]
	v_mfma_f32_16x16x32_bf16 v[70:73], v[182:185], v[232:235], v[70:73]
	v_mfma_f32_16x16x32_bf16 v[66:69], v[190:193], v[232:235], v[66:69]
	s_setprio 0
	s_barrier
	ds_read_b128 v[194:197], v143 offset:49152
	ds_read_b128 v[208:211], v143 offset:50176
	ds_read_b128 v[212:215], v143 offset:51200
	ds_read_b128 v[216:219], v143 offset:52224
	ds_read_b128 v[220:223], v143 offset:53248
	ds_read_b128 v[224:227], v143 offset:54272
	ds_read_b128 v[228:231], v143 offset:55296
	ds_read_b128 v[232:235], v143 offset:56320
	s_add_i32 s18, s43, s20
	s_add_u32 s48, s16, 0x80
	s_addc_u32 s49, s17, 0
	s_mov_b32 m0, s18
	s_nop 0
	global_load_lds_dwordx4 v64, s[48:49]
	s_add_i32 m0, s18, 0x2000
	s_add_u32 s16, s16, 0x200080
	s_addc_u32 s17, s17, 0
	s_add_i32 s18, s44, s20
	global_load_lds_dwordx4 v130, s[48:49]
	s_mov_b32 m0, s18
	s_nop 0
	global_load_lds_dwordx4 v64, s[16:17]
	s_add_i32 m0, s18, 0x2000
	s_nop 0
	global_load_lds_dwordx4 v130, s[16:17]
	s_add_u32 s100, s100, 0x80
	s_addc_u32 s101, s101, 0
	s_mov_b32 m0, s28
	s_nop 0
	global_load_lds_dwordx4 v134, s[100:101]
	s_mov_b32 m0, s29
	s_nop 0
	global_load_lds_dwordx4 v132, s[100:101]
	s_waitcnt vmcnt(8)
	s_waitcnt lgkmcnt(0)
	s_barrier
	s_setprio 1
	s_waitcnt lgkmcnt(0)
	v_mfma_f32_16x16x32_bf16 v[60:63], v[144:147], v[194:197], v[60:63]
	v_mfma_f32_16x16x32_bf16 v[56:59], v[152:155], v[194:197], v[56:59]
	v_mfma_f32_16x16x32_bf16 v[52:55], v[144:147], v[212:215], v[52:55]
	v_mfma_f32_16x16x32_bf16 v[48:51], v[152:155], v[212:215], v[48:51]
	v_mfma_f32_16x16x32_bf16 v[36:39], v[144:147], v[220:223], v[36:39]
	v_mfma_f32_16x16x32_bf16 v[32:35], v[152:155], v[220:223], v[32:35]
	v_mfma_f32_16x16x32_bf16 v[20:23], v[144:147], v[228:231], v[20:23]
	v_mfma_f32_16x16x32_bf16 v[16:19], v[152:155], v[228:231], v[16:19]
	s_setprio 0
	s_setprio 1
	v_mfma_f32_16x16x32_bf16 v[60:63], v[148:151], v[208:211], v[60:63]
	v_mfma_f32_16x16x32_bf16 v[56:59], v[156:159], v[208:211], v[56:59]
	v_mfma_f32_16x16x32_bf16 v[52:55], v[148:151], v[216:219], v[52:55]
	v_mfma_f32_16x16x32_bf16 v[48:51], v[156:159], v[216:219], v[48:51]
	v_mfma_f32_16x16x32_bf16 v[36:39], v[148:151], v[224:227], v[36:39]
	v_mfma_f32_16x16x32_bf16 v[32:35], v[156:159], v[224:227], v[32:35]
	v_mfma_f32_16x16x32_bf16 v[20:23], v[148:151], v[232:235], v[20:23]
	v_mfma_f32_16x16x32_bf16 v[16:19], v[156:159], v[232:235], v[16:19]
	s_setprio 0
	s_setprio 1
	v_mfma_f32_16x16x32_bf16 v[44:47], v[178:181], v[194:197], v[44:47]
	v_mfma_f32_16x16x32_bf16 v[40:43], v[186:189], v[194:197], v[40:43]
	v_mfma_f32_16x16x32_bf16 v[28:31], v[178:181], v[212:215], v[28:31]
	v_mfma_f32_16x16x32_bf16 v[24:27], v[186:189], v[212:215], v[24:27]
	v_mfma_f32_16x16x32_bf16 v[12:15], v[178:181], v[220:223], v[12:15]
	v_mfma_f32_16x16x32_bf16 v[8:11], v[186:189], v[220:223], v[8:11]
	v_mfma_f32_16x16x32_bf16 v[4:7], v[178:181], v[228:231], v[4:7]
	v_mfma_f32_16x16x32_bf16 v[0:3], v[186:189], v[228:231], v[0:3]
	s_setprio 0
	s_setprio 1
	v_mfma_f32_16x16x32_bf16 v[44:47], v[182:185], v[208:211], v[44:47]
	v_mfma_f32_16x16x32_bf16 v[40:43], v[190:193], v[208:211], v[40:43]
	v_mfma_f32_16x16x32_bf16 v[28:31], v[182:185], v[216:219], v[28:31]
	v_mfma_f32_16x16x32_bf16 v[24:27], v[190:193], v[216:219], v[24:27]
	v_mfma_f32_16x16x32_bf16 v[12:15], v[182:185], v[224:227], v[12:15]
	v_mfma_f32_16x16x32_bf16 v[8:11], v[190:193], v[224:227], v[8:11]
	v_mfma_f32_16x16x32_bf16 v[4:7], v[182:185], v[232:235], v[4:7]
	v_mfma_f32_16x16x32_bf16 v[0:3], v[190:193], v[232:235], v[0:3]
	s_setprio 0
	s_barrier
	s_add_i32 s42, s42, 2
	s_add_u32 s0, s0, 0x100
	s_addc_u32 s1, s1, 0
	s_add_u32 s36, s36, 0x100
	s_addc_u32 s37, s37, 0
	s_cmpk_gt_u32 s42, 0x7d
	s_cbranch_scc0 .LBB0_1685
	s_mov_b64 s[48:49], 0x80
	s_and_b64 vcc, exec, s[6:7]
	s_mov_b64 s[34:35], 0x45000
	s_cbranch_vccz .LBB0_1688
	s_barrier

; #define PG8_STAGE(bufoff, gbase, voff) do { _Pragma("unroll") for (int _i = 0; _i < 2; ++_i) \
;         __builtin_amdgcn_global_load_lds((const unsigned*)((const char*)(gbase) + (voff)[_i]), (PG8_LAS unsigned*)(lds + (bufoff) + ldsw + _i * 8192), 16, 0, 0); } while (0)
; #define PG8_LDA(dst, b, h) do { _Pragma("unroll") for (int m = 0; m < 4; ++m) _Pragma("unroll") for (int k = 0; k < 2; ++k) dst[m][k] = *(const PG8_LAS bf16x8*)(lds + PG8_SA(b, h) + aoff + m * 2048 + k * 1024); } while (0)
; #define PG8_LDB(dst, b, h) do { _Pragma("unroll") for (int n = 0; n < 2; ++n) _Pragma("unroll") for (int k = 0; k < 2; ++k) dst[n][k] = *(const PG8_LAS bf16x8*)(lds + PG8_SB(b, h) + boff + n * 2048 + k * 1024); } while (0)
; #define PG8_MMA(ai, bj, At, Bt) do { __builtin_amdgcn_s_setprio(1); _Pragma("unroll") for (int m = 0; m < 4; ++m) _Pragma("unroll") for (int n = 0; n < 2; ++n) _Pragma("unroll") for (int k = 0; k < 2; ++k) \
;         acc[ai][bj][m][n] = __builtin_amdgcn_mfma_f32_16x16x32_bf16(Bt[n][k], At[m][k], acc[ai][bj][m][n], 0, 0, 0); __builtin_amdgcn_s_setprio(0); } while (0)
; #define PG8_WAIT_V(n) asm volatile("s_waitcnt vmcnt(" #n ")" ::: "memory")
; #define PG8_WAIT_L(n) asm volatile("s_waitcnt lgkmcnt(" #n ")" ::: "memory")
; template <class Epi, class Sched, bool ALIGN_EPI = false, bool SP2 = false>
; __device__ __forceinline__ void gemm_phase(PG8_LAS unsigned char* lds, const Gemm g, const Sched& S, const Epi& E, const int wave0) {
;     ...
;             const bool last = (t == nt - 2);
;             const char* a1 = cA + (size_t)(t + 1) * kstep;
;             const char* a2 = last ? nA : cA + (size_t)(t + 2) * kstep; const char* b2 = last ? nB : cB + (size_t)(t + 2) * kstep;
;             const char* a3 = a2 + kstep; const char* b3 = b2 + kstep;
;             if (last && has_next) S.a_ready(nxt);
;             if constexpr (SP2) {
;             PG8_LDB(B0, 0, 0); PG8_LDB(B1, 0, 1); PG8_SCHED; PG8_LDA(At, 0, 0); PG8_STAGE(PG8_SA(1, 1), a1 + hstepA, voffA);
;             PG8_WAIT_V(8); PG8_WAIT_L(0); PG8_BAR; PG8_MMA(0, 0, At, B0); PG8_MMA(0, 1, At, B1); PG8_BAR; PG8_SCHED;
;             PG8_LDA(At, 0, 1); PG8_STAGE(PG8_SB(0, 0), b2, voffB); PG8_STAGE(PG8_SB(0, 1), b2 + hstepB, voffB); PG8_STAGE(PG8_SA(0, 0), a2, voffA);
;             PG8_WAIT_V(8); PG8_WAIT_L(0); PG8_BAR; PG8_MMA(1, 0, At, B0); PG8_MMA(1, 1, At, B1); PG8_BAR; PG8_SCHED;
.LBB0_1702:
	ds_read_b128 v[144:147], v252
	ds_read_b128 v[148:151], v252 offset:1024
	ds_read_b128 v[152:155], v252 offset:2048
	ds_read_b128 v[156:159], v252 offset:3072
	ds_read_b128 v[178:181], v253
	ds_read_b128 v[182:185], v253 offset:1024
	ds_read_b128 v[186:189], v253 offset:2048
	ds_read_b128 v[190:193], v253 offset:3072
	ds_read_b128 v[194:197], v143
	ds_read_b128 v[208:211], v143 offset:1024
	ds_read_b128 v[212:215], v143 offset:2048
	ds_read_b128 v[216:219], v143 offset:3072
	ds_read_b128 v[220:223], v143 offset:4096
	ds_read_b128 v[224:227], v143 offset:5120
	ds_read_b128 v[228:231], v143 offset:6144
	ds_read_b128 v[232:235], v143 offset:7168
	s_add_u32 s18, s16, 0xffe00080
	s_addc_u32 s19, s17, -1
	s_add_i32 s44, 0, 0x10000
	s_cmp_eq_u32 s43, 12
	s_cselect_b32 s21, s9, s19
	s_cselect_b32 s20, s11, s18
	s_cselect_b32 s19, s13, s42
	s_cselect_b32 s18, s38, s39
	s_add_i32 s46, 0, 0x14000
	s_add_i32 m0, s28, 0xc000
	s_nop 0
	global_load_lds_dwordx4 v136, s[16:17]
	s_add_i32 m0, s28, 0xe000
	s_nop 0
	global_load_lds_dwordx4 v138, s[16:17]
	s_waitcnt vmcnt(8)
	s_waitcnt lgkmcnt(0)
	s_barrier
	s_setprio 1
	s_waitcnt lgkmcnt(0)
	v_mfma_f32_16x16x32_bf16 v[126:129], v[144:147], v[194:197], v[126:129]
	v_mfma_f32_16x16x32_bf16 v[122:125], v[152:155], v[194:197], v[122:125]
	v_mfma_f32_16x16x32_bf16 v[118:121], v[144:147], v[212:215], v[118:121]
	v_mfma_f32_16x16x32_bf16 v[114:117], v[152:155], v[212:215], v[114:117]
	v_mfma_f32_16x16x32_bf16 v[102:105], v[144:147], v[220:223], v[102:105]
	v_mfma_f32_16x16x32_bf16 v[98:101], v[152:155], v[220:223], v[98:101]
	v_mfma_f32_16x16x32_bf16 v[86:89], v[144:147], v[228:231], v[86:89]
	v_mfma_f32_16x16x32_bf16 v[82:85], v[152:155], v[228:231], v[82:85]
	s_setprio 0
	s_setprio 1
	v_mfma_f32_16x16x32_bf16 v[126:129], v[148:151], v[208:211], v[126:129]
	v_mfma_f32_16x16x32_bf16 v[122:125], v[156:159], v[208:211], v[122:125]
	v_mfma_f32_16x16x32_bf16 v[118:121], v[148:151], v[216:219], v[118:121]
	v_mfma_f32_16x16x32_bf16 v[114:117], v[156:159], v[216:219], v[114:117]
	v_mfma_f32_16x16x32_bf16 v[102:105], v[148:151], v[224:227], v[102:105]
	v_mfma_f32_16x16x32_bf16 v[98:101], v[156:159], v[224:227], v[98:101]
	v_mfma_f32_16x16x32_bf16 v[86:89], v[148:151], v[232:235], v[86:89]
	v_mfma_f32_16x16x32_bf16 v[82:85], v[156:159], v[232:235], v[82:85]
	s_setprio 0
	s_setprio 1
	v_mfma_f32_16x16x32_bf16 v[110:113], v[178:181], v[194:197], v[110:113]
	v_mfma_f32_16x16x32_bf16 v[106:109], v[186:189], v[194:197], v[106:109]
	v_mfma_f32_16x16x32_bf16 v[94:97], v[178:181], v[212:215], v[94:97]
	v_mfma_f32_16x16x32_bf16 v[90:93], v[186:189], v[212:215], v[90:93]
	v_mfma_f32_16x16x32_bf16 v[78:81], v[178:181], v[220:223], v[78:81]
	v_mfma_f32_16x16x32_bf16 v[74:77], v[186:189], v[220:223], v[74:77]
	v_mfma_f32_16x16x32_bf16 v[70:73], v[178:181], v[228:231], v[70:73]
	v_mfma_f32_16x16x32_bf16 v[66:69], v[186:189], v[228:231], v[66:69]
	s_setprio 0
	s_setprio 1
	v_mfma_f32_16x16x32_bf16 v[110:113], v[182:185], v[208:211], v[110:113]
	v_mfma_f32_16x16x32_bf16 v[106:109], v[190:193], v[208:211], v[106:109]
	v_mfma_f32_16x16x32_bf16 v[94:97], v[182:185], v[216:219], v[94:97]
	v_mfma_f32_16x16x32_bf16 v[90:93], v[190:193], v[216:219], v[90:93]
	v_mfma_f32_16x16x32_bf16 v[78:81], v[182:185], v[224:227], v[78:81]
	v_mfma_f32_16x16x32_bf16 v[74:77], v[190:193], v[224:227], v[74:77]
	v_mfma_f32_16x16x32_bf16 v[70:73], v[182:185], v[232:235], v[70:73]
	v_mfma_f32_16x16x32_bf16 v[66:69], v[190:193], v[232:235], v[66:69]
	s_setprio 0
	s_barrier
	ds_read_b128 v[194:197], v143 offset:16384
	ds_read_b128 v[208:211], v143 offset:17408
	ds_read_b128 v[212:215], v143 offset:18432
	ds_read_b128 v[216:219], v143 offset:19456
	ds_read_b128 v[220:223], v143 offset:20480
	ds_read_b128 v[224:227], v143 offset:21504
	ds_read_b128 v[228:231], v143 offset:22528
	ds_read_b128 v[232:235], v143 offset:23552
	s_add_i32 s44, s44, s25
	s_mov_b32 m0, s44
	s_nop 0
	global_load_lds_dwordx4 v64, s[18:19]
	s_add_i32 m0, s44, 0x2000
	s_add_u32 s44, s18, 0x200000
	s_addc_u32 s45, s19, 0
	s_add_i32 s46, s46, s25
	global_load_lds_dwordx4 v130, s[18:19]
	s_mov_b32 m0, s46
	s_mov_b64 s[100:101], s[20:21]
	global_load_lds_dwordx4 v64, s[44:45]
	s_add_i32 m0, s46, 0x2000
	s_nop 0
	global_load_lds_dwordx4 v130, s[44:45]
	s_mov_b32 m0, s28
	s_nop 0
	global_load_lds_dwordx4 v134, s[20:21]
	s_mov_b32 m0, s29
	s_nop 0
	global_load_lds_dwordx4 v132, s[20:21]
	s_waitcnt vmcnt(8)
	s_waitcnt lgkmcnt(0)
	s_barrier
	s_setprio 1
	s_waitcnt lgkmcnt(0)
	v_mfma_f32_16x16x32_bf16 v[60:63], v[144:147], v[194:197], v[60:63]
	v_mfma_f32_16x16x32_bf16 v[56:59], v[152:155], v[194:197], v[56:59]
	v_mfma_f32_16x16x32_bf16 v[52:55], v[144:147], v[212:215], v[52:55]
	v_mfma_f32_16x16x32_bf16 v[48:51], v[152:155], v[212:215], v[48:51]
	v_mfma_f32_16x16x32_bf16 v[36:39], v[144:147], v[220:223], v[36:39]
	v_mfma_f32_16x16x32_bf16 v[32:35], v[152:155], v[220:223], v[32:35]
	v_mfma_f32_16x16x32_bf16 v[20:23], v[144:147], v[228:231], v[20:23]
	v_mfma_f32_16x16x32_bf16 v[16:19], v[152:155], v[228:231], v[16:19]
	s_setprio 0
	s_setprio 1
	v_mfma_f32_16x16x32_bf16 v[60:63], v[148:151], v[208:211], v[60:63]
	v_mfma_f32_16x16x32_bf16 v[56:59], v[156:159], v[208:211], v[56:59]
	v_mfma_f32_16x16x32_bf16 v[52:55], v[148:151], v[216:219], v[52:55]
	v_mfma_f32_16x16x32_bf16 v[48:51], v[156:159], v[216:219], v[48:51]
	v_mfma_f32_16x16x32_bf16 v[36:39], v[148:151], v[224:227], v[36:39]
	v_mfma_f32_16x16x32_bf16 v[32:35], v[156:159], v[224:227], v[32:35]
	v_mfma_f32_16x16x32_bf16 v[20:23], v[148:151], v[232:235], v[20:23]
	v_mfma_f32_16x16x32_bf16 v[16:19], v[156:159], v[232:235], v[16:19]
	s_setprio 0
	s_setprio 1
	v_mfma_f32_16x16x32_bf16 v[44:47], v[178:181], v[194:197], v[44:47]
	v_mfma_f32_16x16x32_bf16 v[40:43], v[186:189], v[194:197], v[40:43]
	v_mfma_f32_16x16x32_bf16 v[28:31], v[178:181], v[212:215], v[28:31]
	v_mfma_f32_16x16x32_bf16 v[24:27], v[186:189], v[212:215], v[24:27]
	v_mfma_f32_16x16x32_bf16 v[12:15], v[178:181], v[220:223], v[12:15]
	v_mfma_f32_16x16x32_bf16 v[8:11], v[186:189], v[220:223], v[8:11]
	v_mfma_f32_16x16x32_bf16 v[4:7], v[178:181], v[228:231], v[4:7]
	v_mfma_f32_16x16x32_bf16 v[0:3], v[186:189], v[228:231], v[0:3]
	s_setprio 0
	s_setprio 1
	v_mfma_f32_16x16x32_bf16 v[44:47], v[182:185], v[208:211], v[44:47]
	v_mfma_f32_16x16x32_bf16 v[40:43], v[190:193], v[208:211], v[40:43]
	v_mfma_f32_16x16x32_bf16 v[28:31], v[182:185], v[216:219], v[28:31]
	v_mfma_f32_16x16x32_bf16 v[24:27], v[190:193], v[216:219], v[24:27]
	v_mfma_f32_16x16x32_bf16 v[12:15], v[182:185], v[224:227], v[12:15]
	v_mfma_f32_16x16x32_bf16 v[8:11], v[190:193], v[224:227], v[8:11]
	v_mfma_f32_16x16x32_bf16 v[4:7], v[182:185], v[232:235], v[4:7]
	v_mfma_f32_16x16x32_bf16 v[0:3], v[190:193], v[232:235], v[0:3]
	s_setprio 0
	s_barrier
; #define PG8_STAGE(bufoff, gbase, voff) do { _Pragma("unroll") for (int _i = 0; _i < 2; ++_i) \
;         __builtin_amdgcn_global_load_lds((const unsigned*)((const char*)(gbase) + (voff)[_i]), (PG8_LAS unsigned*)(lds + (bufoff) + ldsw + _i * 8192), 16, 0, 0); } while (0)
; #define PG8_LDA(dst, b, h) do { _Pragma("unroll") for (int m = 0; m < 4; ++m) _Pragma("unroll") for (int k = 0; k < 2; ++k) dst[m][k] = *(const PG8_LAS bf16x8*)(lds + PG8_SA(b, h) + aoff + m * 2048 + k * 1024); } while (0)
; #define PG8_LDB(dst, b, h) do { _Pragma("unroll") for (int n = 0; n < 2; ++n) _Pragma("unroll") for (int k = 0; k < 2; ++k) dst[n][k] = *(const PG8_LAS bf16x8*)(lds + PG8_SB(b, h) + boff + n * 2048 + k * 1024); } while (0)
; #define PG8_MMA(ai, bj, At, Bt) do { __builtin_amdgcn_s_setprio(1); _Pragma("unroll") for (int m = 0; m < 4; ++m) _Pragma("unroll") for (int n = 0; n < 2; ++n) _Pragma("unroll") for (int k = 0; k < 2; ++k) \
;         acc[ai][bj][m][n] = __builtin_amdgcn_mfma_f32_16x16x32_bf16(Bt[n][k], At[m][k], acc[ai][bj][m][n], 0, 0, 0); __builtin_amdgcn_s_setprio(0); } while (0)
; #define PG8_WAIT_V(n) asm volatile("s_waitcnt vmcnt(" #n ")" ::: "memory")
; #define PG8_WAIT_L(n) asm volatile("s_waitcnt lgkmcnt(" #n ")" ::: "memory")
; #define PG8_BAR __builtin_amdgcn_s_barrier()
; #define PG8_SCHED __builtin_amdgcn_sched_barrier(0)
; template <class Epi, class Sched, bool ALIGN_EPI = false, bool SP2 = false>
; __device__ __forceinline__ void gemm_phase(PG8_LAS unsigned char* lds, const Gemm g, const Sched& S, const Epi& E, const int wave0) {
;     ...
;         for (int t = 0; t < nt; t += 2) {
;             const bool last = (t == nt - 2);
;             const char* a1 = cA + (size_t)(t + 1) * kstep;
;             const char* a2 = last ? nA : cA + (size_t)(t + 2) * kstep; const char* b2 = last ? nB : cB + (size_t)(t + 2) * kstep;
;     ...
;             PG8_LDB(B0, 1, 0); PG8_LDB(B1, 1, 1); PG8_SCHED; PG8_LDA(At, 1, 0); PG8_STAGE(PG8_SA(0, 1), a2 + hstepA, voffA);
;             PG8_WAIT_V(8); PG8_WAIT_L(0); PG8_BAR; PG8_MMA(0, 0, At, B0); PG8_MMA(0, 1, At, B1); PG8_BAR; PG8_SCHED;
;             PG8_LDA(At, 1, 1); PG8_STAGE(PG8_SB(1, 0), b3, voffB); PG8_STAGE(PG8_SB(1, 1), b3 + hstepB, voffB); PG8_STAGE(PG8_SA(1, 0), a3, voffA);
;             PG8_WAIT_V(8); PG8_WAIT_L(0); PG8_BAR; PG8_MMA(1, 0, At, B0); PG8_MMA(1, 1, At, B1); PG8_BAR; PG8_SCHED;
	ds_read_b128 v[144:147], v254
	ds_read_b128 v[148:151], v254 offset:1024
	ds_read_b128 v[152:155], v254 offset:2048
	ds_read_b128 v[156:159], v254 offset:3072
	ds_read_b128 v[178:181], v255
	ds_read_b128 v[182:185], v255 offset:1024
	ds_read_b128 v[186:189], v255 offset:2048
	ds_read_b128 v[190:193], v255 offset:3072
	ds_read_b128 v[194:197], v143 offset:32768
	ds_read_b128 v[208:211], v143 offset:33792
	ds_read_b128 v[212:215], v143 offset:34816
	ds_read_b128 v[216:219], v143 offset:35840
	ds_read_b128 v[220:223], v143 offset:36864
	ds_read_b128 v[224:227], v143 offset:37888
	ds_read_b128 v[228:231], v143 offset:38912
	ds_read_b128 v[232:235], v143 offset:39936
	s_add_i32 s44, 0, 0x18000
	s_add_i32 s45, 0, 0x1c000
	s_add_u32 s20, s20, 0x200000
	s_addc_u32 s21, s21, 0
	s_mov_b32 m0, s30
	s_nop 0
	global_load_lds_dwordx4 v134, s[20:21]
	s_mov_b32 m0, s31
	s_nop 0
	global_load_lds_dwordx4 v132, s[20:21]
	s_waitcnt vmcnt(8)
	s_waitcnt lgkmcnt(0)
	s_barrier
	s_setprio 1
	s_waitcnt lgkmcnt(0)
	v_mfma_f32_16x16x32_bf16 v[126:129], v[144:147], v[194:197], v[126:129]
	v_mfma_f32_16x16x32_bf16 v[122:125], v[152:155], v[194:197], v[122:125]
	v_mfma_f32_16x16x32_bf16 v[118:121], v[144:147], v[212:215], v[118:121]
	v_mfma_f32_16x16x32_bf16 v[114:117], v[152:155], v[212:215], v[114:117]
	v_mfma_f32_16x16x32_bf16 v[102:105], v[144:147], v[220:223], v[102:105]
	v_mfma_f32_16x16x32_bf16 v[98:101], v[152:155], v[220:223], v[98:101]
	v_mfma_f32_16x16x32_bf16 v[86:89], v[144:147], v[228:231], v[86:89]
	v_mfma_f32_16x16x32_bf16 v[82:85], v[152:155], v[228:231], v[82:85]
	s_setprio 0
	s_setprio 1
	v_mfma_f32_16x16x32_bf16 v[126:129], v[148:151], v[208:211], v[126:129]
	v_mfma_f32_16x16x32_bf16 v[122:125], v[156:159], v[208:211], v[122:125]
	v_mfma_f32_16x16x32_bf16 v[118:121], v[148:151], v[216:219], v[118:121]
	v_mfma_f32_16x16x32_bf16 v[114:117], v[156:159], v[216:219], v[114:117]
	v_mfma_f32_16x16x32_bf16 v[102:105], v[148:151], v[224:227], v[102:105]
	v_mfma_f32_16x16x32_bf16 v[98:101], v[156:159], v[224:227], v[98:101]
	v_mfma_f32_16x16x32_bf16 v[86:89], v[148:151], v[232:235], v[86:89]
	v_mfma_f32_16x16x32_bf16 v[82:85], v[156:159], v[232:235], v[82:85]
	s_setprio 0
	s_setprio 1
	v_mfma_f32_16x16x32_bf16 v[110:113], v[178:181], v[194:197], v[110:113]
	v_mfma_f32_16x16x32_bf16 v[106:109], v[186:189], v[194:197], v[106:109]
	v_mfma_f32_16x16x32_bf16 v[94:97], v[178:181], v[212:215], v[94:97]
	v_mfma_f32_16x16x32_bf16 v[90:93], v[186:189], v[212:215], v[90:93]
	v_mfma_f32_16x16x32_bf16 v[78:81], v[178:181], v[220:223], v[78:81]
	v_mfma_f32_16x16x32_bf16 v[74:77], v[186:189], v[220:223], v[74:77]
	v_mfma_f32_16x16x32_bf16 v[70:73], v[178:181], v[228:231], v[70:73]
	v_mfma_f32_16x16x32_bf16 v[66:69], v[186:189], v[228:231], v[66:69]
	s_setprio 0
	s_setprio 1
	v_mfma_f32_16x16x32_bf16 v[110:113], v[182:185], v[208:211], v[110:113]
	v_mfma_f32_16x16x32_bf16 v[106:109], v[190:193], v[208:211], v[106:109]
	v_mfma_f32_16x16x32_bf16 v[94:97], v[182:185], v[216:219], v[94:97]
	v_mfma_f32_16x16x32_bf16 v[90:93], v[190:193], v[216:219], v[90:93]
	v_mfma_f32_16x16x32_bf16 v[78:81], v[182:185], v[224:227], v[78:81]
	v_mfma_f32_16x16x32_bf16 v[74:77], v[190:193], v[224:227], v[74:77]
	v_mfma_f32_16x16x32_bf16 v[70:73], v[182:185], v[232:235], v[70:73]
	v_mfma_f32_16x16x32_bf16 v[66:69], v[190:193], v[232:235], v[66:69]
	s_setprio 0
	s_barrier
	ds_read_b128 v[194:197], v143 offset:49152
	ds_read_b128 v[208:211], v143 offset:50176
	ds_read_b128 v[212:215], v143 offset:51200
	ds_read_b128 v[216:219], v143 offset:52224
	ds_read_b128 v[220:223], v143 offset:53248
	ds_read_b128 v[224:227], v143 offset:54272
	ds_read_b128 v[228:231], v143 offset:55296
	ds_read_b128 v[232:235], v143 offset:56320
	s_add_i32 s20, s44, s25
	s_add_u32 s48, s18, 0x80
	s_addc_u32 s49, s19, 0
	s_mov_b32 m0, s20
	s_nop 0
	global_load_lds_dwordx4 v64, s[48:49]
	s_add_i32 m0, s20, 0x2000
	s_add_u32 s18, s18, 0x200080
	s_addc_u32 s19, s19, 0
	s_add_i32 s20, s45, s25
	global_load_lds_dwordx4 v130, s[48:49]
	s_mov_b32 m0, s20
	s_nop 0
	global_load_lds_dwordx4 v64, s[18:19]
	s_add_i32 m0, s20, 0x2000
	s_nop 0
	global_load_lds_dwordx4 v130, s[18:19]
	s_add_u32 s100, s100, 0x80
	s_addc_u32 s101, s101, 0
	s_mov_b32 m0, s33
	s_nop 0
	global_load_lds_dwordx4 v134, s[100:101]
	s_mov_b32 m0, s34
	s_nop 0
	global_load_lds_dwordx4 v132, s[100:101]
	s_waitcnt vmcnt(8)
	s_waitcnt lgkmcnt(0)
	s_barrier
	s_setprio 1
	s_waitcnt lgkmcnt(0)
	v_mfma_f32_16x16x32_bf16 v[60:63], v[144:147], v[194:197], v[60:63]
	v_mfma_f32_16x16x32_bf16 v[56:59], v[152:155], v[194:197], v[56:59]
	v_mfma_f32_16x16x32_bf16 v[52:55], v[144:147], v[212:215], v[52:55]
	v_mfma_f32_16x16x32_bf16 v[48:51], v[152:155], v[212:215], v[48:51]
	v_mfma_f32_16x16x32_bf16 v[36:39], v[144:147], v[220:223], v[36:39]
	v_mfma_f32_16x16x32_bf16 v[32:35], v[152:155], v[220:223], v[32:35]
	v_mfma_f32_16x16x32_bf16 v[20:23], v[144:147], v[228:231], v[20:23]
	v_mfma_f32_16x16x32_bf16 v[16:19], v[152:155], v[228:231], v[16:19]
	s_setprio 0
	s_setprio 1
	v_mfma_f32_16x16x32_bf16 v[60:63], v[148:151], v[208:211], v[60:63]
	v_mfma_f32_16x16x32_bf16 v[56:59], v[156:159], v[208:211], v[56:59]
	v_mfma_f32_16x16x32_bf16 v[52:55], v[148:151], v[216:219], v[52:55]
	v_mfma_f32_16x16x32_bf16 v[48:51], v[156:159], v[216:219], v[48:51]
	v_mfma_f32_16x16x32_bf16 v[36:39], v[148:151], v[224:227], v[36:39]
	v_mfma_f32_16x16x32_bf16 v[32:35], v[156:159], v[224:227], v[32:35]
	v_mfma_f32_16x16x32_bf16 v[20:23], v[148:151], v[232:235], v[20:23]
	v_mfma_f32_16x16x32_bf16 v[16:19], v[156:159], v[232:235], v[16:19]
	s_setprio 0
	s_setprio 1
	v_mfma_f32_16x16x32_bf16 v[44:47], v[178:181], v[194:197], v[44:47]
	v_mfma_f32_16x16x32_bf16 v[40:43], v[186:189], v[194:197], v[40:43]
	v_mfma_f32_16x16x32_bf16 v[28:31], v[178:181], v[212:215], v[28:31]
	v_mfma_f32_16x16x32_bf16 v[24:27], v[186:189], v[212:215], v[24:27]
	v_mfma_f32_16x16x32_bf16 v[12:15], v[178:181], v[220:223], v[12:15]
	v_mfma_f32_16x16x32_bf16 v[8:11], v[186:189], v[220:223], v[8:11]
	v_mfma_f32_16x16x32_bf16 v[4:7], v[178:181], v[228:231], v[4:7]
	v_mfma_f32_16x16x32_bf16 v[0:3], v[186:189], v[228:231], v[0:3]
	s_setprio 0
	s_setprio 1
	v_mfma_f32_16x16x32_bf16 v[44:47], v[182:185], v[208:211], v[44:47]
	v_mfma_f32_16x16x32_bf16 v[40:43], v[190:193], v[208:211], v[40:43]
	v_mfma_f32_16x16x32_bf16 v[28:31], v[182:185], v[216:219], v[28:31]
	v_mfma_f32_16x16x32_bf16 v[24:27], v[190:193], v[216:219], v[24:27]
	v_mfma_f32_16x16x32_bf16 v[12:15], v[182:185], v[224:227], v[12:15]
	v_mfma_f32_16x16x32_bf16 v[8:11], v[190:193], v[224:227], v[8:11]
	v_mfma_f32_16x16x32_bf16 v[4:7], v[182:185], v[232:235], v[4:7]
	v_mfma_f32_16x16x32_bf16 v[0:3], v[190:193], v[232:235], v[0:3]
	s_setprio 0
	s_barrier
	s_add_i32 s43, s43, 2
	s_add_u32 s16, s16, 0x100
	s_addc_u32 s17, s17, 0
	s_add_u32 s39, s39, 0x100
	s_addc_u32 s42, s42, 0
	s_cmp_gt_u32 s43, 13
	s_cbranch_scc0 .LBB0_1702
	s_mov_b64 s[48:49], 0x80
	s_and_b64 vcc, exec, s[6:7]
	s_cbranch_vccz .LBB0_1705
	s_barrier
